# DA/NSA: per-cluster s_setprio flips removed, one static s_setprio 1 for waves 4-7 per unit (static priority raise for the younger half)
# baseline (speedup 1.0000x reference)
; template <int KSTR> DI void qk64c(f32x16& s0, f32x16& s1, const lds8* kp, const bf16x8 (&q)[4], const f32x16& negm) {
;   bf16x8 a[8];
; #pragma unroll
;   for (int ks = 0; ks < 4; ++ks) { a[2 * ks] = *(const LAS bf16x8*)(kp + ks * 32); a[2 * ks + 1] = *(const LAS bf16x8*)(kp + 32 * KSTR + ks * 32); }
;   SBAR();
;   __builtin_amdgcn_s_setprio(1);
;   s0 = MFMA32(a[0], q[0], negm); s1 = MFMA32(a[1], q[0], negm);
; #pragma unroll
; DI void da_unit(const Params& p, lds8* lds, int bl, int hd, int qb, float lam) {
;   int tid = threadIdx.x; asm volatile("" : "+v"(tid));
;   const int lane = tid & 63, wid = __builtin_amdgcn_readfirstlane(tid >> 6);
;   unsigned char* ws = p.ws;
;   bf16_t* QDA = (bf16_t*)(ws + OFF_QDA); const bf16_t* KDA = (const bf16_t*)(ws + OFF_KDA); const bf16_t* VDA = (const bf16_t*)(ws + OFF_VDA);
;   const int r = lane & 31, h = lane >> 5, qs = wid & 3, c = wid >> 2;
;   const size_t rowbase = (size_t)bl * SEQ; const int q0 = qb * 128; const int qpos = q0 + 32 * qs + r;
;   bf16x8 q[4];
;   { const bf16_t* qp = QDA + (rowbase + qpos) * DM + hd * 128 + c * 64 + 8 * h;
; #pragma unroll
;     for (int ks = 0; ks < 4; ++ks) q[ks] = *(const bf16x8*)(qp + 16 * ks); }
;   const int nt = 2 * (qb + 1);
;   DaCtx cx;
;   { const int ch0 = tid, ch1 = tid + 512; cx.sr0 = ch0 >> 4; cx.sc0 = ch0 & 15; cx.sr1 = ch1 >> 4; cx.sc1 = ch1 & 15; }
;   cx.kg = KDA + rowbase * DM + hd * 128; cx.vg = VDA + rowbase * DM + hd * 128;
;   cx.koff = r * DA_KSTR + h * 16 + c * 128;
;   cx.voff = 64 * DA_KSTR + (4 * h + ((lane & 15) >> 2)) * DA_KSTR + ((lane >> 4) & 1) * 32 + (lane & 3) * 8;
;   cx.qpos = qpos; cx.h = h; cx.qs = qs; cx.q0 = q0;
; #pragma unroll
;   for (int t0 = 0; t0 < 2; ++t0) { const size_t ro = (size_t)t0 * 64; lds8* b = lds + t0 * DA_STAGE;
;     const u32x4 kr0 = *(const u32x4*)(cx.kg + (ro + cx.sr0) * DM + cx.sc0 * 8), kr1 = *(const u32x4*)(cx.kg + (ro + cx.sr1) * DM + cx.sc1 * 8);
;     const u32x4 vr0 = *(const u32x4*)(cx.vg + (ro + cx.sr0) * DM + cx.sc0 * 8), vr1 = *(const u32x4*)(cx.vg + (ro + cx.sr1) * DM + cx.sc1 * 8);
;     *(LAS u32x4*)(b + cx.sr0 * DA_KSTR + cx.sc0 * 16) = kr0; *(LAS u32x4*)(b + cx.sr1 * DA_KSTR + cx.sc1 * 16) = kr1;
;     *(LAS u32x4*)(b + 64 * DA_KSTR + cx.sr0 * DA_KSTR + cx.sc0 * 16) = vr0; *(LAS u32x4*)(b + 64 * DA_KSTR + cx.sr1 * DA_KSTR + cx.sc1 * 16) = vr1; }
;   __syncthreads();
.LBB0_845:
	s_or_b64 exec, exec, s[10:11]
	v_mov_b32_e32 v134, v200
	s_ashr_i32 s6, s20, 7
	s_sub_i32 s12, 15, s6
	v_readfirstlane_b32 s16, v134
	s_bfe_u32 s14, s16, 0x20006
	s_lshl_b32 s1, s12, 7
	s_lshl_b32 s3, s14, 5
	s_bfe_u32 s13, s20, 0x40003
	v_and_b32_e32 v179, 31, v134
	s_or_b32 s18, s3, s1
	s_lshl_b32 s0, s13, 11
	v_or_b32_e32 v183, s18, v179
	v_add_u32_e32 v186, s0, v183
	v_readlane_b32 s10, v254, 43
	v_lshlrev_b64 v[0:1], 11, v[186:187]
	v_readlane_b32 s11, v254, 44
	s_ashr_i32 s17, s16, 8
	s_setprio 0
	s_cmp_eq_u32 s17, 1
	s_cbranch_scc0 .Lda_prio_lo
	s_setprio 1
.Lda_prio_lo:
	v_bfe_u32 v135, v134, 5, 1
	v_lshl_add_u64 v[0:1], s[10:11], 0, v[0:1]
	s_lshl_b32 s10, s20, 7
	s_and_b32 s15, s10, 0x380
	s_lshl_b32 s88, s15, 1
	s_lshl_b32 s10, s17, 6
	v_lshl_add_u64 v[0:1], v[0:1], 0, s[88:89]
	s_ashr_i32 s11, s10, 31
	v_lshl_add_u64 v[2:3], s[10:11], 1, v[0:1]
	s_lshl_b32 s10, s13, 22
	v_readlane_b32 s2, v254, 45
	v_lshlrev_b32_e32 v0, 4, v135
	v_mov_b32_e32 v1, v187
	s_add_u32 s11, s2, s10
	v_readlane_b32 s2, v254, 46
	v_lshl_add_u64 v[2:3], v[2:3], 0, v[0:1]
	s_addc_u32 s13, s2, 0
	global_load_dwordx4 v[172:175], v[2:3], off
	global_load_dwordx4 v[168:171], v[2:3], off offset:32
	global_load_dwordx4 v[164:167], v[2:3], off offset:64
	global_load_dwordx4 v[160:163], v[2:3], off offset:96
	s_add_u32 s22, s11, s88
	v_lshlrev_b32_e32 v3, 1, v134
	v_ashrrev_i32_e32 v2, 4, v134
	v_and_b32_e32 v136, 15, v134
	s_addc_u32 s23, s13, 0
	v_readlane_b32 s2, v254, 47
	v_and_b32_e32 v100, 32, v3
	v_lshlrev_b32_e32 v3, 3, v134
	v_add_u32_e32 v1, 0x200, v134
	s_add_u32 s10, s2, s10
	v_readlane_b32 s2, v254, 48
	v_and_b32_e32 v101, 24, v3
	v_ashrrev_i32_e32 v3, 31, v2
	v_lshlrev_b32_e32 v186, 4, v136
	v_ashrrev_i32_e32 v4, 4, v1
	s_addc_u32 s11, s2, 0
	v_lshl_add_u64 v[6:7], s[22:23], 0, v[186:187]
	v_lshlrev_b64 v[96:97], 11, v[2:3]
	s_add_u32 s24, s10, s88
	v_ashrrev_i32_e32 v5, 31, v4
	v_lshl_add_u64 v[8:9], v[6:7], 0, v[96:97]
	s_addc_u32 s25, s11, 0
	global_load_dwordx4 v[10:13], v[8:9], off
	v_lshlrev_b64 v[98:99], 11, v[4:5]
	v_lshl_add_u64 v[22:23], s[24:25], 0, v[186:187]
	s_movk_i32 s2, 0x130
	v_lshl_add_u64 v[6:7], v[6:7], 0, v[98:99]
	v_mul_lo_u32 v138, v4, s2
	global_load_dwordx4 v[14:17], v[6:7], off
	v_lshl_add_u64 v[4:5], v[22:23], 0, v[96:97]
	v_mul_lo_u32 v137, v2, s2
	global_load_dwordx4 v[18:21], v[4:5], off
	v_lshl_add_u64 v[2:3], v[22:23], 0, v[98:99]
	global_load_dwordx4 v[22:25], v[2:3], off
	v_add3_u32 v26, 0, v137, v186
	s_mov_b32 s2, 0x20000
	v_add3_u32 v27, 0, v138, v186
	v_lshlrev_b32_e32 v180, 2, v135
	v_bfe_u32 v1, v134, 2, 2
	s_lshl_b32 s10, s17, 7
	v_or_b32_e32 v1, v180, v1
	v_or_b32_e32 v181, v101, v100
	s_mov_b32 s19, 0
	v_mul_u32_u24_e32 v182, 0x130, v1
	v_add_co_u32_e32 v28, vcc, s2, v8
	s_nop 1
	v_addc_co_u32_e32 v29, vcc, 0, v9, vcc
	v_add_co_u32_e32 v32, vcc, s2, v6
	global_load_dwordx4 v[28:31], v[28:29], off
	s_nop 0
	v_addc_co_u32_e32 v33, vcc, 0, v7, vcc
	v_add_co_u32_e32 v36, vcc, s2, v4
	global_load_dwordx4 v[32:35], v[32:33], off
	s_nop 0
	v_addc_co_u32_e32 v37, vcc, 0, v5, vcc
	v_add_co_u32_e32 v40, vcc, s2, v2
	global_load_dwordx4 v[36:39], v[36:37], off
	s_nop 0
	v_addc_co_u32_e32 v41, vcc, 0, v3, vcc
	global_load_dwordx4 v[40:43], v[40:41], off
	s_cmp_eq_u32 s6, 15
	s_waitcnt vmcnt(7)
	ds_write_b128 v26, v[10:13]
	s_waitcnt vmcnt(6)
	ds_write_b128 v27, v[14:17]
	s_waitcnt vmcnt(5)
	ds_write_b128 v26, v[18:21] offset:19456
	s_waitcnt vmcnt(4)
	ds_write_b128 v27, v[22:25] offset:19456
	s_waitcnt vmcnt(3)
	ds_write_b128 v26, v[28:31] offset:38912
	s_waitcnt vmcnt(2)
	ds_write_b128 v27, v[32:35] offset:38912
	s_waitcnt vmcnt(1)
	ds_write_b128 v26, v[36:39] offset:58368
	s_waitcnt vmcnt(0)
	ds_write_b128 v27, v[40:43] offset:58368
	v_mul_u32_u24_e32 v10, 0x130, v179
	v_add3_u32 v144, v0, v10, s10
	s_mov_b32 s10, 0
	s_waitcnt lgkmcnt(0)
	s_barrier
	s_cbranch_scc1 .LBB0_853
	v_add_co_u32_e32 v0, vcc, 0x40000, v8
	s_mov_b32 s11, 1
	s_nop 0
	v_addc_co_u32_e32 v1, vcc, 0, v9, vcc
	v_add_co_u32_e32 v6, vcc, 0x40000, v6
	s_lshl_b32 s19, s12, 1
	s_nop 0
	v_addc_co_u32_e32 v7, vcc, 0, v7, vcc
	global_load_dwordx4 v[80:83], v[0:1], off
	global_load_dwordx4 v[84:87], v[6:7], off
	v_add_co_u32_e32 v0, vcc, 0x40000, v4
	s_nop 1
	v_addc_co_u32_e32 v1, vcc, 0, v5, vcc
	v_add_co_u32_e32 v2, vcc, 0x40000, v2
	s_nop 1
	v_addc_co_u32_e32 v3, vcc, 0, v3, vcc
	global_load_dwordx4 v[88:91], v[0:1], off
	global_load_dwordx4 v[92:95], v[2:3], off
	v_add_u32_e32 v4, 0, v144
	ds_read_b128 v[0:3], v4
	ds_read_b128 v[32:35], v4 offset:32
	ds_read_b128 v[16:19], v4 offset:9728
	ds_read_b128 v[36:39], v4 offset:9760
	ds_read_b128 v[40:43], v4 offset:64
	ds_read_b128 v[44:47], v4 offset:96
	ds_read_b128 v[48:51], v4 offset:9792
	ds_read_b128 v[52:55], v4 offset:9824
	s_nop 0
	s_waitcnt lgkmcnt(7)
	v_mfma_f32_32x32x16_bf16 v[0:15], v[0:3], v[172:175], 0
	s_waitcnt lgkmcnt(5)
	v_mfma_f32_32x32x16_bf16 v[16:31], v[16:19], v[172:175], 0
	v_mfma_f32_32x32x16_bf16 v[0:15], v[32:35], v[168:171], v[0:15]
	s_waitcnt lgkmcnt(4)
	v_mfma_f32_32x32x16_bf16 v[16:31], v[36:39], v[168:171], v[16:31]
	s_waitcnt lgkmcnt(3)
	v_mfma_f32_32x32x16_bf16 v[0:15], v[40:43], v[164:167], v[0:15]
	s_waitcnt lgkmcnt(1)
	v_mfma_f32_32x32x16_bf16 v[16:31], v[48:51], v[164:167], v[16:31]
	v_mfma_f32_32x32x16_bf16 v[0:15], v[44:47], v[160:163], v[0:15]
	s_waitcnt lgkmcnt(0)
; template <int VSTR, int NDVB> DI void pv64(f32x16 (&O)[NDVB], const lds8* vp, const bf16x8 (&P)[4]) {
;   bf16x8 f[2][NDVB];
; #pragma unroll
; DI float rowmax32(const f32x16& s0, const f32x16& s1) {
;   float a = fmaxf(fmaxf(s0[0], s0[1]), s1[0]), b = fmaxf(fmaxf(s0[2], s0[3]), s1[1]); a = fmaxf(fmaxf(a, s1[2]), s1[3]);
; #pragma unroll
;   for (int r = 4; r < 16; r += 4) { a = fmaxf(fmaxf(a, s0[r]), s0[r + 1]); b = fmaxf(fmaxf(b, s0[r + 2]), s0[r + 3]); a = fmaxf(fmaxf(a, s1[r]), s1[r + 1]); b = fmaxf(fmaxf(b, s1[r + 2]), s1[r + 3]); }
;   const float m = fmaxf(a, b);
;   return fmaxf(m, __shfl_xor(m, 32));
; }
; template <int NDVB, bool HAS_NEXT> DI void softmax_def(f32x16& sa0, f32x16& sa1, f32x16& sb0, f32x16& sb1, f32x16 (&O)[NDVB], float& muse, float& l, bool first, bf16x8 (&P)[4], bool check = true) {
;   float mx = 0.f;
;   if (check) mx = rowmax32(sa0, sa1);
;   if (check && (first || __any(mx > 8.f))) {
;     float dl = first ? mx : fmaxf(mx, 0.f);
;     if (mx < -1e29f) dl = 0.f;
;     const float alpha = __builtin_amdgcn_exp2f(-dl);
;     muse += dl; l *= alpha;
; #pragma unroll
;     for (int i = 0; i < 16; ++i) { sa0[i] -= dl; sa1[i] -= dl; }
;     if (HAS_NEXT) {
; #pragma unroll
;       for (int i = 0; i < 16; ++i) { sb0[i] -= dl; sb1[i] -= dl; }
;     }
; #pragma unroll
;     for (int d = 0; d < NDVB; ++d)
; #pragma unroll
;       for (int i = 0; i < 16; ++i) O[d][i] *= alpha;
;   }
;   float sum = 0.f;
; #pragma unroll
;   for (int i = 0; i < 16; ++i) { sa0[i] = __builtin_amdgcn_exp2f(sa0[i]); sum += sa0[i]; }
; #pragma unroll
;   for (int i = 0; i < 16; ++i) { sa1[i] = __builtin_amdgcn_exp2f(sa1[i]); sum += sa1[i]; }
;   l += sum;
;   u32x4 w;
;   w.x = cvtpk(sa0[0], sa0[1]); w.y = cvtpk(sa0[2], sa0[3]); w.z = cvtpk(sa0[4], sa0[5]); w.w = cvtpk(sa0[6], sa0[7]); P[0] = __builtin_bit_cast(bf16x8, w);
;   w.x = cvtpk(sa0[8], sa0[9]); w.y = cvtpk(sa0[10], sa0[11]); w.z = cvtpk(sa0[12], sa0[13]); w.w = cvtpk(sa0[14], sa0[15]); P[1] = __builtin_bit_cast(bf16x8, w);
;   w.x = cvtpk(sa1[0], sa1[1]); w.y = cvtpk(sa1[2], sa1[3]); w.z = cvtpk(sa1[4], sa1[5]); w.w = cvtpk(sa1[6], sa1[7]); P[2] = __builtin_bit_cast(bf16x8, w);
;   w.x = cvtpk(sa1[8], sa1[9]); w.y = cvtpk(sa1[10], sa1[11]); w.z = cvtpk(sa1[12], sa1[13]); w.w = cvtpk(sa1[14], sa1[15]); P[3] = __builtin_bit_cast(bf16x8, w);
; }
	v_mfma_f32_32x32x16_bf16 v[16:31], v[52:55], v[160:163], v[16:31]
	s_nop 0
	s_nop 8
	v_max_f32_e32 v32, v1, v1
	v_max_f32_e32 v33, v0, v0
	v_max_f32_e32 v32, v33, v32
	v_max3_f32 v33, v2, v3, v17
	v_max3_f32 v32, v32, v16, v18
	v_max3_f32 v32, v32, v19, v4
	v_max3_f32 v33, v33, v6, v7
	v_max3_f32 v32, v32, v5, v20
	v_max3_f32 v33, v33, v22, v23
	v_max3_f32 v32, v32, v21, v8
	v_max3_f32 v33, v33, v10, v11
	v_max3_f32 v32, v32, v9, v24
	v_max3_f32 v33, v33, v26, v27
	v_max3_f32 v32, v32, v25, v12
	v_max3_f32 v33, v33, v14, v15
	v_max3_f32 v32, v32, v13, v28
	v_max3_f32 v33, v33, v30, v31
	v_and_b32_e32 v34, 64, v202
	v_max3_f32 v32, v32, v29, v33
	v_xor_b32_e32 v33, 32, v202
	v_add_u32_e32 v34, 64, v34
	v_cmp_lt_i32_e32 vcc, v33, v34
	v_add3_u32 v212, v181, v182, 0
	s_nop 0
	v_cndmask_b32_e32 v33, v202, v33, vcc
	v_lshlrev_b32_e32 v139, 2, v33
	ds_bpermute_b32 v33, v139, v32
	s_waitcnt lgkmcnt(0)
	v_max_f32_e32 v33, v33, v33
	v_max_f32_e32 v32, v32, v33
	v_cmp_ngt_f32_e32 vcc, s85, v32
	s_nop 1
	v_cndmask_b32_e32 v145, 0, v32, vcc
	v_exp_f32_e64 v32, -v145
	v_sub_f32_e32 v16, v16, v145
	v_sub_f32_e32 v17, v17, v145
	v_sub_f32_e32 v18, v18, v145
	v_sub_f32_e32 v19, v19, v145
	v_mul_f32_e32 v64, 0, v32
	v_exp_f32_e32 v188, v16
	v_exp_f32_e32 v189, v17
	v_exp_f32_e32 v190, v18
	v_exp_f32_e32 v191, v19
	ds_read_b64_tr_b16 v[16:17], v212 offset:19456
	ds_read_b64_tr_b16 v[32:33], v212 offset:19520
	ds_read_b64_tr_b16 v[48:49], v212 offset:19584
	ds_read_b64_tr_b16 v[114:115], v212 offset:19648
	ds_read_b64_tr_b16 v[18:19], v212 offset:21888
	ds_read_b64_tr_b16 v[34:35], v212 offset:21952
	ds_read_b64_tr_b16 v[50:51], v212 offset:22016
	ds_read_b64_tr_b16 v[116:117], v212 offset:22080
	ds_read_b64_tr_b16 v[118:119], v212 offset:24320
	ds_read_b64_tr_b16 v[122:123], v212 offset:24384
	ds_read_b64_tr_b16 v[126:127], v212 offset:24448
	ds_read_b64_tr_b16 v[130:131], v212 offset:24512
	ds_read_b64_tr_b16 v[120:121], v212 offset:26752
	ds_read_b64_tr_b16 v[124:125], v212 offset:26816
	ds_read_b64_tr_b16 v[128:129], v212 offset:26880
	ds_read_b64_tr_b16 v[132:133], v212 offset:26944
	v_sub_f32_e32 v0, v0, v145
	v_sub_f32_e32 v1, v1, v145
	v_sub_f32_e32 v2, v2, v145
	v_sub_f32_e32 v3, v3, v145
	v_sub_f32_e32 v20, v20, v145
	v_sub_f32_e32 v21, v21, v145
	v_sub_f32_e32 v22, v22, v145
	v_sub_f32_e32 v23, v23, v145
	v_sub_f32_e32 v24, v24, v145
	v_sub_f32_e32 v25, v25, v145
	v_sub_f32_e32 v26, v26, v145
	v_sub_f32_e32 v27, v27, v145
	v_sub_f32_e32 v28, v28, v145
	v_sub_f32_e32 v29, v29, v145
	v_sub_f32_e32 v30, v30, v145
	v_sub_f32_e32 v31, v31, v145
	v_sub_f32_e32 v4, v4, v145
	v_sub_f32_e32 v5, v5, v145
	v_sub_f32_e32 v6, v6, v145
	v_sub_f32_e32 v7, v7, v145
	v_sub_f32_e32 v8, v8, v145
	v_sub_f32_e32 v9, v9, v145
	v_sub_f32_e32 v10, v10, v145
	v_sub_f32_e32 v11, v11, v145
	v_sub_f32_e32 v12, v12, v145
	v_sub_f32_e32 v13, v13, v145
	v_sub_f32_e32 v14, v14, v145
	v_sub_f32_e32 v15, v15, v145
	v_exp_f32_e32 v146, v0
	v_exp_f32_e32 v147, v1
	v_exp_f32_e32 v148, v2
	v_exp_f32_e32 v149, v3
	v_exp_f32_e32 v150, v4
	v_exp_f32_e32 v151, v5
	v_exp_f32_e32 v152, v6
	v_exp_f32_e32 v153, v7
	v_exp_f32_e32 v154, v8
	v_exp_f32_e32 v155, v9
	v_exp_f32_e32 v156, v10
	v_exp_f32_e32 v157, v11
	v_exp_f32_e32 v158, v12
	v_exp_f32_e32 v159, v13
	v_exp_f32_e32 v176, v14
	v_exp_f32_e32 v177, v15
	v_exp_f32_e32 v192, v20
	v_exp_f32_e32 v193, v21
	v_exp_f32_e32 v194, v22
	v_exp_f32_e32 v195, v23
	v_exp_f32_e32 v196, v24
	v_exp_f32_e32 v197, v25
	v_exp_f32_e32 v198, v26
	v_exp_f32_e32 v199, v27
	v_exp_f32_e32 v208, v28
	v_exp_f32_e32 v209, v29
	v_exp_f32_e32 v210, v30
	v_exp_f32_e32 v211, v31
	v_mov_b32_e32 v65, v64
	v_mov_b32_e32 v66, v64
	v_mov_b32_e32 v67, v64
	v_mov_b32_e32 v68, v64
	v_mov_b32_e32 v69, v64
	v_mov_b32_e32 v70, v64
	v_mov_b32_e32 v71, v64
	v_mov_b32_e32 v72, v64
	v_mov_b32_e32 v73, v64
	v_mov_b32_e32 v74, v64
	v_mov_b32_e32 v75, v64
	v_mov_b32_e32 v76, v64
	v_mov_b32_e32 v77, v64
	v_mov_b32_e32 v78, v64
	v_mov_b32_e32 v79, v64
	v_cvt_pk_bf16_f32 v140, v146, v147
	v_cvt_pk_bf16_f32 v141, v148, v149
	v_cmp_neq_f32_e32 vcc, 0, v145
	v_cvt_pk_bf16_f32 v102, v196, v197
	v_cvt_pk_bf16_f32 v103, v198, v199
	v_cvt_pk_bf16_f32 v104, v208, v209
	v_cvt_pk_bf16_f32 v105, v210, v211
	v_cvt_pk_bf16_f32 v106, v188, v189
	v_cvt_pk_bf16_f32 v107, v190, v191
	v_cvt_pk_bf16_f32 v108, v192, v193
	v_cvt_pk_bf16_f32 v109, v194, v195
	v_cvt_pk_bf16_f32 v110, v154, v155
	v_cvt_pk_bf16_f32 v111, v156, v157
	v_cvt_pk_bf16_f32 v112, v158, v159
	v_cvt_pk_bf16_f32 v113, v176, v177
	v_cvt_pk_bf16_f32 v142, v150, v151
	v_cvt_pk_bf16_f32 v143, v152, v153
	s_nop 0
	s_waitcnt lgkmcnt(11)
	v_mfma_f32_32x32x16_bf16 v[0:15], v[16:19], v[140:143], v[64:79]
	s_waitcnt lgkmcnt(10)
	v_mfma_f32_32x32x16_bf16 v[16:31], v[32:35], v[140:143], v[64:79]
	s_waitcnt lgkmcnt(9)
	v_mfma_f32_32x32x16_bf16 v[32:47], v[48:51], v[140:143], v[64:79]
	v_mov_b64_e32 v[48:49], v[64:65]
	v_mov_b64_e32 v[50:51], v[66:67]
	v_mov_b64_e32 v[52:53], v[68:69]
	v_mov_b64_e32 v[54:55], v[70:71]
	v_mov_b64_e32 v[56:57], v[72:73]
	v_mov_b64_e32 v[58:59], v[74:75]
	v_mov_b64_e32 v[60:61], v[76:77]
	v_mov_b64_e32 v[62:63], v[78:79]
	s_waitcnt lgkmcnt(8)
	s_nop 0
	v_mfma_f32_32x32x16_bf16 v[48:63], v[114:117], v[140:143], v[48:63]
	s_nop 0
	ds_read_b64_tr_b16 v[66:67], v212 offset:29184
	ds_read_b64_tr_b16 v[70:71], v212 offset:29248
	ds_read_b64_tr_b16 v[74:75], v212 offset:29312
	ds_read_b64_tr_b16 v[114:115], v212 offset:29376
	ds_read_b64_tr_b16 v[68:69], v212 offset:31616
	ds_read_b64_tr_b16 v[72:73], v212 offset:31680
	ds_read_b64_tr_b16 v[76:77], v212 offset:31744
	ds_read_b64_tr_b16 v[116:117], v212 offset:31808
	s_nop 0
	s_waitcnt lgkmcnt(11)
; #define LAS __attribute__((address_space(3)))
; #define MFMA32(a, b, c) __builtin_amdgcn_mfma_f32_32x32x16_bf16((a), (b), (c), 0, 0, 0)
; #define SBAR() __builtin_amdgcn_sched_barrier(0)
; DI s16x4 trrd(const lds8* p) { typedef short v4i16_t __attribute__((ext_vector_type(4))); return __builtin_bit_cast(s16x4, __builtin_amdgcn_ds_read_tr16_b64_v4i16((LAS v4i16_t*)p)); }
; template <int VSTR, int NDVB> DI void pv64(f32x16 (&O)[NDVB], const lds8* vp, const bf16x8 (&P)[4]) {
;   bf16x8 f[2][NDVB];
; #pragma unroll
;   for (int d = 0; d < NDVB; ++d) { const s16x4 lo = trrd(vp + d * 64), hi = trrd(vp + 8 * VSTR + d * 64); f[0][d] = __builtin_shufflevector(lo, hi, 0, 1, 2, 3, 4, 5, 6, 7); }
; #pragma unroll
;   for (int kk = 0; kk < 4; ++kk) {
;     if (kk < 3) {
; #pragma unroll
;       for (int d = 0; d < NDVB; ++d) { const s16x4 lo = trrd(vp + (16 * (kk + 1)) * VSTR + d * 64), hi = trrd(vp + (16 * (kk + 1) + 8) * VSTR + d * 64);
;         f[(kk + 1) & 1][d] = __builtin_shufflevector(lo, hi, 0, 1, 2, 3, 4, 5, 6, 7); }
;     }
;     SBAR();
;     __builtin_amdgcn_s_setprio(1);
; #pragma unroll
;     for (int d = 0; d < NDVB; ++d) O[d] = MFMA32(f[kk & 1][d], P[kk], O[d]);
;     __builtin_amdgcn_s_setprio(0);
;     SBAR();
;   }
; }
; template <bool LOAD2, bool MASK>
; DI void da_step(lds8* lds, const DaCtx& cx, int t, const bf16x8 (&q)[4], f32x16 (&O)[4], float& muse, float& l, f32x16& negm) {
;     ...
;     const float mprev = muse;
;     softmax_def<4, false>(sa0, sa1, du0, du1, O, muse, l, t == 0, P, MASK || (t & 1) == 0);
;     if (__any(muse != mprev)) {
; #pragma unroll
;       for (int i = 0; i < 16; ++i) negm[i] = -muse;
;     }
;     pv64<DA_KSTR, 4>(O, lds + st * DA_STAGE + cx.voff, P);
;   }
;   if (LOAD2) { lds8* b = lds + stn2 * DA_STAGE;
;     *(LAS u32x4*)(b + cx.sr0 * DA_KSTR + cx.sc0 * 16) = kr0; *(LAS u32x4*)(b + cx.sr1 * DA_KSTR + cx.sc1 * 16) = kr1;
;     *(LAS u32x4*)(b + 64 * DA_KSTR + cx.sr0 * DA_KSTR + cx.sc0 * 16) = vr0; *(LAS u32x4*)(b + 64 * DA_KSTR + cx.sr1 * DA_KSTR + cx.sc1 * 16) = vr1;
;     __syncthreads(); }
	v_mfma_f32_32x32x16_bf16 v[0:15], v[118:121], v[110:113], v[0:15]
	s_waitcnt lgkmcnt(10)
	v_mfma_f32_32x32x16_bf16 v[16:31], v[122:125], v[110:113], v[16:31]
	s_waitcnt lgkmcnt(9)
	v_mfma_f32_32x32x16_bf16 v[32:47], v[126:129], v[110:113], v[32:47]
	s_waitcnt lgkmcnt(8)
	v_mfma_f32_32x32x16_bf16 v[48:63], v[130:133], v[110:113], v[48:63]
	s_nop 0
	ds_read_b64_tr_b16 v[110:111], v212 offset:34048
	ds_read_b64_tr_b16 v[118:119], v212 offset:34112
	ds_read_b64_tr_b16 v[122:123], v212 offset:34176
	ds_read_b64_tr_b16 v[126:127], v212 offset:34240
	ds_read_b64_tr_b16 v[112:113], v212 offset:36480
	ds_read_b64_tr_b16 v[120:121], v212 offset:36544
	ds_read_b64_tr_b16 v[124:125], v212 offset:36608
	ds_read_b64_tr_b16 v[128:129], v212 offset:36672
	s_nop 0
	s_waitcnt lgkmcnt(11)
	v_mfma_f32_32x32x16_bf16 v[0:15], v[66:69], v[106:109], v[0:15]
	s_waitcnt lgkmcnt(10)
	v_mfma_f32_32x32x16_bf16 v[16:31], v[70:73], v[106:109], v[16:31]
	s_waitcnt lgkmcnt(9)
	v_mfma_f32_32x32x16_bf16 v[32:47], v[74:77], v[106:109], v[32:47]
	s_waitcnt lgkmcnt(8)
	v_mfma_f32_32x32x16_bf16 v[48:63], v[114:117], v[106:109], v[48:63]
	s_nop 0
	s_nop 0
	s_waitcnt lgkmcnt(3)
	v_mfma_f32_32x32x16_bf16 v[0:15], v[110:113], v[102:105], v[0:15]
	s_waitcnt lgkmcnt(2)
	v_mfma_f32_32x32x16_bf16 v[16:31], v[118:121], v[102:105], v[16:31]
	s_waitcnt lgkmcnt(1)
	v_mfma_f32_32x32x16_bf16 v[32:47], v[122:125], v[102:105], v[32:47]
	s_waitcnt lgkmcnt(0)
	v_mfma_f32_32x32x16_bf16 v[48:63], v[126:129], v[102:105], v[48:63]
	s_nop 0
	v_readlane_b32 s2, v255, 5
	v_mov_b32_e32 v67, v187
	s_cmp_lg_u64 vcc, 0
	v_add3_u32 v65, s2, v137, v186
	s_waitcnt vmcnt(3)
	ds_write_b128 v65, v[80:83]
	v_add3_u32 v65, s2, v138, v186
	v_readlane_b32 s2, v255, 6
	s_waitcnt vmcnt(2)
	ds_write_b128 v65, v[84:87]
	s_cselect_b64 s[12:13], -1, 0
	v_add3_u32 v65, s2, v137, v186
	s_waitcnt vmcnt(1)
	ds_write_b128 v65, v[88:91]
	v_add3_u32 v65, s2, v138, v186
	s_waitcnt vmcnt(0)
	ds_write_b128 v65, v[92:95]
	v_add_f32_e32 v65, 0, v146
	v_add_f32_e32 v65, v147, v65
	v_add_f32_e32 v65, v148, v65
	v_add_f32_e32 v65, v149, v65
	v_add_f32_e32 v65, v150, v65
	v_add_f32_e32 v65, v151, v65
	v_add_f32_e32 v65, v152, v65
	v_add_f32_e32 v65, v153, v65
	v_add_f32_e32 v65, v154, v65
	v_add_f32_e32 v65, v155, v65
	v_add_f32_e32 v65, v156, v65
	v_add_f32_e32 v65, v157, v65
	v_add_f32_e32 v65, v158, v65
	v_add_f32_e32 v65, v159, v65
	v_add_f32_e32 v65, v176, v65
	v_add_f32_e32 v65, v177, v65
	v_add_f32_e32 v65, v188, v65
	v_add_f32_e32 v65, v189, v65
	v_add_f32_e32 v65, v190, v65
	v_add_f32_e32 v65, v191, v65
	v_add_f32_e32 v65, v192, v65
	v_add_f32_e32 v65, v193, v65
	v_add_f32_e32 v65, v194, v65
	v_add_f32_e32 v65, v195, v65
	v_add_f32_e32 v65, v196, v65
	v_add_f32_e32 v65, v197, v65
	v_add_f32_e32 v65, v198, v65
	v_add_f32_e32 v65, v199, v65
	v_add_f32_e32 v65, v208, v65
	v_add_f32_e32 v65, v209, v65
	v_add_f32_e32 v65, v210, v65
	v_add_f32_e32 v66, v211, v65
	v_mov_b32_e32 v65, v145
	v_pk_add_f32 v[176:177], v[64:65], v[66:67]
	s_lshl_b32 s6, s6, 1
	v_cndmask_b32_e64 v64, 0, -v177, s[12:13]
	s_lshl_b32 s12, s20, 19
	s_and_b32 s13, s20, 7
	s_sub_i32 s6, 29, s6
	s_and_b32 s12, s12, 0x3c00000
	s_lshl_b32 s13, s13, 8
	s_add_u32 s13, s56, s13
	s_addc_u32 s20, s57, 0
	v_add_u32_e32 v80, v182, v100
	v_readlane_b32 s2, v255, 7
	s_add_u32 s12, s13, s12
	s_addc_u32 s13, s20, 0
	v_add3_u32 v140, v80, v101, s2
	v_readlane_b32 s2, v255, 8
	v_mov_b32_e32 v65, v64
	v_mov_b32_e32 v66, v64
	v_mov_b32_e32 v67, v64
	v_mov_b32_e32 v68, v64
	v_mov_b32_e32 v69, v64
	v_mov_b32_e32 v70, v64
	v_mov_b32_e32 v71, v64
	v_mov_b32_e32 v72, v64
	v_mov_b32_e32 v73, v64
	v_mov_b32_e32 v74, v64
	v_mov_b32_e32 v75, v64
	v_mov_b32_e32 v76, v64
	v_mov_b32_e32 v77, v64
	v_mov_b32_e32 v78, v64
	v_mov_b32_e32 v79, v64
	v_lshl_add_u64 v[130:131], s[12:13], 0, v[96:97]
	v_lshl_add_u64 v[132:133], s[12:13], 0, v[98:99]
	v_add_u32_e32 v141, s2, v144
	s_mov_b32 s12, 0
	s_waitcnt lgkmcnt(0)
	s_barrier
; DI int crow(int i, int h) { return (i & 3) + 8 * (i >> 2) + 4 * h; }
; #define SBAR() __builtin_amdgcn_sched_barrier(0)
; template <int NDVB, bool HAS_NEXT> DI void softmax_def(f32x16& sa0, f32x16& sa1, f32x16& sb0, f32x16& sb1, f32x16 (&O)[NDVB], float& muse, float& l, bool first, bf16x8 (&P)[4], bool check = true) {
;   float mx = 0.f;
;   if (check) mx = rowmax32(sa0, sa1);
;   if (check && (first || __any(mx > 8.f))) {
;     float dl = first ? mx : fmaxf(mx, 0.f);
;     if (mx < -1e29f) dl = 0.f;
;     const float alpha = __builtin_amdgcn_exp2f(-dl);
;     muse += dl; l *= alpha;
; #pragma unroll
;     for (int i = 0; i < 16; ++i) { sa0[i] -= dl; sa1[i] -= dl; }
;     if (HAS_NEXT) {
; #pragma unroll
;       for (int i = 0; i < 16; ++i) { sb0[i] -= dl; sb1[i] -= dl; }
;     }
; #pragma unroll
;     for (int d = 0; d < NDVB; ++d)
; #pragma unroll
;       for (int i = 0; i < 16; ++i) O[d][i] *= alpha;
;   }
; template <bool LOAD2, bool MASK>
; DI void da_step(lds8* lds, const DaCtx& cx, int t, const bf16x8 (&q)[4], f32x16 (&O)[4], float& muse, float& l, f32x16& negm) {
;   u32x4 kr0, kr1, vr0, vr1;
;   if (LOAD2) { const size_t ro = (size_t)(t + 2) * 64;
;     kr0 = *(const u32x4*)(cx.kg + (ro + cx.sr0) * DM + cx.sc0 * 8); kr1 = *(const u32x4*)(cx.kg + (ro + cx.sr1) * DM + cx.sc1 * 8);
;     vr0 = *(const u32x4*)(cx.vg + (ro + cx.sr0) * DM + cx.sc0 * 8); vr1 = *(const u32x4*)(cx.vg + (ro + cx.sr1) * DM + cx.sc1 * 8); }
;   SBAR();
;   const int st = t % 3, stn2 = (st == 0) ? 2 : st - 1;
;   const bool cur_live = !MASK || 64 * t <= cx.q0 + 32 * cx.qs + 31;
;   if (cur_live) {
;     f32x16 sa0, sa1, du0, du1;
;     qk64c<DA_KSTR>(sa0, sa1, lds + st * DA_STAGE + cx.koff, q, negm);
;     if (MASK) {
;       if (64 * t + 63 > cx.q0 + 32 * cx.qs) {
; #pragma unroll
;         for (int i = 0; i < 16; ++i) { const int key = 64 * t + crow(i, cx.h); if (key > cx.qpos) sa0[i] = NEG; if (key + 32 > cx.qpos) sa1[i] = NEG; }
;       }
;     }
;     bf16x8 P[4];
;     const float mprev = muse;
;     softmax_def<4, false>(sa0, sa1, du0, du1, O, muse, l, t == 0, P, MASK || (t & 1) == 0);
;     if (__any(muse != mprev)) {
; #pragma unroll
;       for (int i = 0; i < 16; ++i) negm[i] = -muse;
;     }
;     pv64<DA_KSTR, 4>(O, lds + st * DA_STAGE + cx.voff, P);
.LBB0_847:
	v_lshl_add_u64 v[80:81], v[130:131], 0, v[186:187]
	v_add_co_u32_e32 v82, vcc, s86, v80
	s_mul_hi_u32 s20, s11, 0xaaaaaaab
	s_nop 0
	v_addc_co_u32_e32 v83, vcc, 0, v81, vcc
	global_load_dwordx4 v[112:115], v[82:83], off
	v_lshl_add_u64 v[82:83], v[132:133], 0, v[186:187]
	v_add_co_u32_e32 v84, vcc, s86, v82
	s_lshr_b32 s21, s20, 1
	s_nop 0
	v_addc_co_u32_e32 v85, vcc, 0, v83, vcc
	v_add_co_u32_e32 v80, vcc, s87, v80
	global_load_dwordx4 v[116:119], v[84:85], off
	s_nop 0
	v_addc_co_u32_e32 v81, vcc, 0, v81, vcc
	global_load_dwordx4 v[120:123], v[80:81], off
	v_add_co_u32_e32 v80, vcc, s87, v82
	s_add_i32 s13, s12, 1
	s_nop 0
	v_addc_co_u32_e32 v81, vcc, 0, v83, vcc
	global_load_dwordx4 v[124:127], v[80:81], off
	s_mul_i32 s20, s21, 0xfffe3800
	v_add_u32_e32 v84, s20, v141
	ds_read_b128 v[80:83], v84
	ds_read_b128 v[146:149], v84 offset:32
	ds_read_b128 v[150:153], v84 offset:9728
	ds_read_b128 v[154:157], v84 offset:9760
	ds_read_b128 v[192:195], v84 offset:64
	ds_read_b128 v[196:199], v84 offset:96
	ds_read_b128 v[208:211], v84 offset:9792
	ds_read_b128 v[212:215], v84 offset:9824
	s_nop 0
	s_waitcnt lgkmcnt(7)
	v_mfma_f32_32x32x16_bf16 v[96:111], v[80:83], v[172:175], v[64:79]
	s_waitcnt lgkmcnt(5)
	v_mfma_f32_32x32x16_bf16 v[80:95], v[150:153], v[172:175], v[64:79]
	v_mfma_f32_32x32x16_bf16 v[96:111], v[146:149], v[168:171], v[96:111]
	s_waitcnt lgkmcnt(4)
	v_mfma_f32_32x32x16_bf16 v[80:95], v[154:157], v[168:171], v[80:95]
	s_waitcnt lgkmcnt(3)
	v_mfma_f32_32x32x16_bf16 v[96:111], v[192:195], v[164:167], v[96:111]
	s_waitcnt lgkmcnt(1)
	v_mfma_f32_32x32x16_bf16 v[80:95], v[208:211], v[164:167], v[80:95]
	v_mfma_f32_32x32x16_bf16 v[96:111], v[196:199], v[160:163], v[96:111]
	s_waitcnt lgkmcnt(0)
	v_mfma_f32_32x32x16_bf16 v[80:95], v[212:215], v[160:163], v[80:95]
	s_nop 0
	s_bitcmp1_b32 s13, 0
	s_cselect_b64 s[22:23], -1, 0
	s_and_b64 vcc, exec, s[22:23]
	s_cbranch_vccnz .LBB0_850
	s_nop 4
	v_max_f32_e32 v128, v97, v97
	v_max_f32_e32 v129, v96, v96
	v_max_f32_e32 v128, v129, v128
	v_max3_f32 v129, v98, v99, v81
	v_max3_f32 v128, v128, v80, v82
	v_max3_f32 v128, v128, v83, v100
	v_max3_f32 v129, v129, v102, v103
	v_max3_f32 v128, v128, v101, v84
	v_max3_f32 v129, v129, v86, v87
	v_max3_f32 v128, v128, v85, v104
	v_max3_f32 v129, v129, v106, v107
	v_max3_f32 v128, v128, v105, v88
	v_max3_f32 v129, v129, v90, v91
	v_max3_f32 v128, v128, v89, v108
	v_max3_f32 v129, v129, v110, v111
	v_max3_f32 v128, v128, v109, v92
	v_max3_f32 v129, v129, v94, v95
	v_max3_f32 v128, v128, v93, v129
	ds_bpermute_b32 v129, v139, v128
	s_waitcnt lgkmcnt(0)
	v_max_f32_e32 v129, v129, v129
	v_max_f32_e32 v128, v128, v129
	v_cmp_lt_f32_e32 vcc, s7, v128
	s_cbranch_vccz .LBB0_850
	v_max_f32_e32 v129, v128, v128
	v_max_f32_e32 v129, 0, v129
	v_cmp_ngt_f32_e32 vcc, s85, v128
	s_nop 1
	v_cndmask_b32_e32 v143, 0, v129, vcc
	v_exp_f32_e64 v142, -v143
	v_sub_f32_e32 v111, v111, v143
	v_sub_f32_e32 v110, v110, v143
	v_sub_f32_e32 v109, v109, v143
	v_pk_add_f32 v[146:147], v[176:177], v[142:143]
	v_pk_mul_f32 v[128:129], v[176:177], v[142:143]
	v_sub_f32_e32 v108, v108, v143
	v_mov_b32_e32 v129, v147
	v_sub_f32_e32 v107, v107, v143
	v_sub_f32_e32 v106, v106, v143
	v_sub_f32_e32 v105, v105, v143
	v_sub_f32_e32 v104, v104, v143
	v_sub_f32_e32 v103, v103, v143
	v_sub_f32_e32 v102, v102, v143
	v_sub_f32_e32 v101, v101, v143
	v_sub_f32_e32 v100, v100, v143
	v_sub_f32_e32 v99, v99, v143
	v_sub_f32_e32 v98, v98, v143
	v_sub_f32_e32 v97, v97, v143
	v_sub_f32_e32 v96, v96, v143
	v_sub_f32_e32 v95, v95, v143
	v_sub_f32_e32 v94, v94, v143
	v_sub_f32_e32 v93, v93, v143
	v_sub_f32_e32 v92, v92, v143
	v_sub_f32_e32 v91, v91, v143
	v_sub_f32_e32 v90, v90, v143
	v_sub_f32_e32 v89, v89, v143
	v_sub_f32_e32 v88, v88, v143
	v_sub_f32_e32 v87, v87, v143
	v_sub_f32_e32 v86, v86, v143
	v_sub_f32_e32 v85, v85, v143
	v_sub_f32_e32 v84, v84, v143
	v_sub_f32_e32 v83, v83, v143
	v_sub_f32_e32 v82, v82, v143
	v_sub_f32_e32 v81, v81, v143
	v_sub_f32_e32 v80, v80, v143
	v_pk_mul_f32 v[14:15], v[14:15], v[142:143] op_sel_hi:[1,0]
	v_pk_mul_f32 v[12:13], v[12:13], v[142:143] op_sel_hi:[1,0]
	v_pk_mul_f32 v[10:11], v[10:11], v[142:143] op_sel_hi:[1,0]
	v_pk_mul_f32 v[8:9], v[8:9], v[142:143] op_sel_hi:[1,0]
	v_pk_mul_f32 v[6:7], v[6:7], v[142:143] op_sel_hi:[1,0]
	v_pk_mul_f32 v[4:5], v[4:5], v[142:143] op_sel_hi:[1,0]
	v_pk_mul_f32 v[2:3], v[2:3], v[142:143] op_sel_hi:[1,0]
	v_pk_mul_f32 v[0:1], v[0:1], v[142:143] op_sel_hi:[1,0]
	v_pk_mul_f32 v[30:31], v[30:31], v[142:143] op_sel_hi:[1,0]
	v_pk_mul_f32 v[28:29], v[28:29], v[142:143] op_sel_hi:[1,0]
	v_pk_mul_f32 v[26:27], v[26:27], v[142:143] op_sel_hi:[1,0]
	v_pk_mul_f32 v[24:25], v[24:25], v[142:143] op_sel_hi:[1,0]
	v_pk_mul_f32 v[22:23], v[22:23], v[142:143] op_sel_hi:[1,0]
	v_pk_mul_f32 v[20:21], v[20:21], v[142:143] op_sel_hi:[1,0]
	v_pk_mul_f32 v[18:19], v[18:19], v[142:143] op_sel_hi:[1,0]
	v_pk_mul_f32 v[16:17], v[16:17], v[142:143] op_sel_hi:[1,0]
	v_pk_mul_f32 v[46:47], v[46:47], v[142:143] op_sel_hi:[1,0]
	v_pk_mul_f32 v[44:45], v[44:45], v[142:143] op_sel_hi:[1,0]
	v_pk_mul_f32 v[42:43], v[42:43], v[142:143] op_sel_hi:[1,0]
	v_pk_mul_f32 v[40:41], v[40:41], v[142:143] op_sel_hi:[1,0]
	v_pk_mul_f32 v[38:39], v[38:39], v[142:143] op_sel_hi:[1,0]
	v_pk_mul_f32 v[36:37], v[36:37], v[142:143] op_sel_hi:[1,0]
	v_pk_mul_f32 v[34:35], v[34:35], v[142:143] op_sel_hi:[1,0]
	v_pk_mul_f32 v[32:33], v[32:33], v[142:143] op_sel_hi:[1,0]
	v_pk_mul_f32 v[62:63], v[62:63], v[142:143] op_sel_hi:[1,0]
	v_pk_mul_f32 v[60:61], v[60:61], v[142:143] op_sel_hi:[1,0]
	v_pk_mul_f32 v[58:59], v[58:59], v[142:143] op_sel_hi:[1,0]
	v_pk_mul_f32 v[56:57], v[56:57], v[142:143] op_sel_hi:[1,0]
	v_pk_mul_f32 v[54:55], v[54:55], v[142:143] op_sel_hi:[1,0]
	v_pk_mul_f32 v[52:53], v[52:53], v[142:143] op_sel_hi:[1,0]
	v_pk_mul_f32 v[50:51], v[50:51], v[142:143] op_sel_hi:[1,0]
	v_pk_mul_f32 v[48:49], v[48:49], v[142:143] op_sel_hi:[1,0]
	s_branch .LBB0_851

; template <int NDVB, bool HAS_NEXT> DI void softmax_def(f32x16& sa0, f32x16& sa1, f32x16& sb0, f32x16& sb1, f32x16 (&O)[NDVB], float& muse, float& l, bool first, bf16x8 (&P)[4], bool check = true) {
;     ...
;   float sum = 0.f;
; #pragma unroll
;   for (int i = 0; i < 16; ++i) { sa0[i] = __builtin_amdgcn_exp2f(sa0[i]); sum += sa0[i]; }
; #pragma unroll
;   for (int i = 0; i < 16; ++i) { sa1[i] = __builtin_amdgcn_exp2f(sa1[i]); sum += sa1[i]; }
;   l += sum;
;   u32x4 w;
;   w.x = cvtpk(sa0[0], sa0[1]); w.y = cvtpk(sa0[2], sa0[3]); w.z = cvtpk(sa0[4], sa0[5]); w.w = cvtpk(sa0[6], sa0[7]); P[0] = __builtin_bit_cast(bf16x8, w);
;   w.x = cvtpk(sa0[8], sa0[9]); w.y = cvtpk(sa0[10], sa0[11]); w.z = cvtpk(sa0[12], sa0[13]); w.w = cvtpk(sa0[14], sa0[15]); P[1] = __builtin_bit_cast(bf16x8, w);
;   w.x = cvtpk(sa1[0], sa1[1]); w.y = cvtpk(sa1[2], sa1[3]); w.z = cvtpk(sa1[4], sa1[5]); w.w = cvtpk(sa1[6], sa1[7]); P[2] = __builtin_bit_cast(bf16x8, w);
;   w.x = cvtpk(sa1[8], sa1[9]); w.y = cvtpk(sa1[10], sa1[11]); w.z = cvtpk(sa1[12], sa1[13]); w.w = cvtpk(sa1[14], sa1[15]); P[3] = __builtin_bit_cast(bf16x8, w);
; }
; template <bool LOAD2, bool MASK>
; DI void da_step(lds8* lds, const DaCtx& cx, int t, const bf16x8 (&q)[4], f32x16 (&O)[4], float& muse, float& l, f32x16& negm) {
;   u32x4 kr0, kr1, vr0, vr1;
;   if (LOAD2) { const size_t ro = (size_t)(t + 2) * 64;
;     kr0 = *(const u32x4*)(cx.kg + (ro + cx.sr0) * DM + cx.sc0 * 8); kr1 = *(const u32x4*)(cx.kg + (ro + cx.sr1) * DM + cx.sc1 * 8);
;     vr0 = *(const u32x4*)(cx.vg + (ro + cx.sr0) * DM + cx.sc0 * 8); vr1 = *(const u32x4*)(cx.vg + (ro + cx.sr1) * DM + cx.sc1 * 8); }
;   SBAR();
;   const int st = t % 3, stn2 = (st == 0) ? 2 : st - 1;
;   const bool cur_live = !MASK || 64 * t <= cx.q0 + 32 * cx.qs + 31;
;   if (cur_live) {
;     f32x16 sa0, sa1, du0, du1;
;     qk64c<DA_KSTR>(sa0, sa1, lds + st * DA_STAGE + cx.koff, q, negm);
;     if (MASK) {
;       if (64 * t + 63 > cx.q0 + 32 * cx.qs) {
; #pragma unroll
;         for (int i = 0; i < 16; ++i) { const int key = 64 * t + crow(i, cx.h); if (key > cx.qpos) sa0[i] = NEG; if (key + 32 > cx.qpos) sa1[i] = NEG; }
;       }
;     }
;     bf16x8 P[4];
;     const float mprev = muse;
;     softmax_def<4, false>(sa0, sa1, du0, du1, O, muse, l, t == 0, P, MASK || (t & 1) == 0);
;     if (__any(muse != mprev)) {
; #pragma unroll
.Lda_nobar_b:
	s_nop 0
	s_waitcnt lgkmcnt(14)
	v_mfma_f32_32x32x16_bf16 v[0:15], v[232:235], v[216:219], v[0:15]
	v_exp_f32_e32 v104, v104
	v_exp_f32_e32 v105, v105
	v_exp_f32_e32 v106, v106
	s_waitcnt lgkmcnt(12)
	v_mfma_f32_32x32x16_bf16 v[16:31], v[236:239], v[216:219], v[16:31]
	v_exp_f32_e32 v107, v107
	v_exp_f32_e32 v108, v108
	v_exp_f32_e32 v109, v109
	s_waitcnt lgkmcnt(10)
	v_mfma_f32_32x32x16_bf16 v[32:47], v[240:243], v[216:219], v[32:47]
	v_exp_f32_e32 v110, v110
	v_exp_f32_e32 v111, v111
	v_add_f32_e32 v142, 0, v96
	v_add_f32_e32 v142, v97, v142
	s_waitcnt lgkmcnt(8)
	v_mfma_f32_32x32x16_bf16 v[48:63], v[244:247], v[216:219], v[48:63]
	v_cvt_pk_bf16_f32 v220, v104, v105
	v_cvt_pk_bf16_f32 v221, v106, v107
	v_cvt_pk_bf16_f32 v222, v108, v109
	v_cvt_pk_bf16_f32 v223, v110, v111
	v_add_f32_e32 v142, v98, v142
	v_add_f32_e32 v142, v99, v142
	s_nop 0
	ds_read_b64_tr_b16 v[232:233], v145 offset:9728
	ds_read_b64_tr_b16 v[234:235], v145 offset:12160
	ds_read_b64_tr_b16 v[236:237], v145 offset:9792
	ds_read_b64_tr_b16 v[238:239], v145 offset:12224
	ds_read_b64_tr_b16 v[240:241], v145 offset:9856
	ds_read_b64_tr_b16 v[242:243], v145 offset:12288
	ds_read_b64_tr_b16 v[244:245], v145 offset:9920
	ds_read_b64_tr_b16 v[246:247], v145 offset:12352
	s_nop 0
	s_waitcnt lgkmcnt(14)
	v_mfma_f32_32x32x16_bf16 v[0:15], v[146:149], v[220:223], v[0:15]
	v_exp_f32_e32 v80, v80
	v_exp_f32_e32 v81, v81
	v_add_f32_e32 v142, v100, v142
	v_add_f32_e32 v142, v101, v142
	s_waitcnt lgkmcnt(12)
	v_mfma_f32_32x32x16_bf16 v[16:31], v[150:153], v[220:223], v[16:31]
	v_exp_f32_e32 v82, v82
	v_exp_f32_e32 v83, v83
	v_add_f32_e32 v142, v102, v142
	v_add_f32_e32 v142, v103, v142
	s_waitcnt lgkmcnt(10)
	v_mfma_f32_32x32x16_bf16 v[32:47], v[154:157], v[220:223], v[32:47]
	v_exp_f32_e32 v84, v84
	v_exp_f32_e32 v85, v85
	v_add_f32_e32 v142, v104, v142
	v_add_f32_e32 v142, v105, v142
	s_waitcnt lgkmcnt(8)
	v_mfma_f32_32x32x16_bf16 v[48:63], v[192:195], v[220:223], v[48:63]
	v_exp_f32_e32 v86, v86
	v_exp_f32_e32 v87, v87
	v_add_f32_e32 v142, v106, v142
	v_add_f32_e32 v142, v107, v142
	v_add_f32_e32 v142, v108, v142
	v_add_f32_e32 v142, v109, v142
	v_add_f32_e32 v142, v110, v142
	v_add_f32_e32 v142, v111, v142
	v_cvt_pk_bf16_f32 v224, v80, v81
	v_cvt_pk_bf16_f32 v225, v82, v83
	v_cvt_pk_bf16_f32 v226, v84, v85
	v_cvt_pk_bf16_f32 v227, v86, v87
	s_nop 0
	ds_read_b64_tr_b16 v[250:251], v145 offset:17088
	ds_read_b64_tr_b16 v[108:109], v145 offset:14720
	ds_read_b64_tr_b16 v[110:111], v145 offset:17152
	ds_read_b64_tr_b16 v[146:147], v145 offset:14784
	ds_read_b64_tr_b16 v[150:151], v145 offset:14592
	ds_read_b64_tr_b16 v[152:153], v145 offset:17024
	ds_read_b64_tr_b16 v[248:249], v145 offset:14656
	ds_read_b64_tr_b16 v[148:149], v145 offset:17216
	s_nop 0
	s_waitcnt lgkmcnt(14)
	v_mfma_f32_32x32x16_bf16 v[0:15], v[232:235], v[224:227], v[0:15]
	v_exp_f32_e32 v88, v88
	v_exp_f32_e32 v89, v89
	v_add_f32_e32 v142, v80, v142
	v_add_f32_e32 v142, v81, v142
	s_waitcnt lgkmcnt(12)
	v_mfma_f32_32x32x16_bf16 v[16:31], v[236:239], v[224:227], v[16:31]
	v_exp_f32_e32 v90, v90
	v_exp_f32_e32 v91, v91
	v_add_f32_e32 v142, v82, v142
	v_add_f32_e32 v142, v83, v142
	s_waitcnt lgkmcnt(10)
	v_mfma_f32_32x32x16_bf16 v[32:47], v[240:243], v[224:227], v[32:47]
	v_exp_f32_e32 v92, v92
	v_exp_f32_e32 v93, v93
	v_add_f32_e32 v142, v84, v142
	v_add_f32_e32 v142, v85, v142
	s_waitcnt lgkmcnt(8)
	v_mfma_f32_32x32x16_bf16 v[48:63], v[244:247], v[224:227], v[48:63]
	v_exp_f32_e32 v94, v94
	v_exp_f32_e32 v95, v95
	v_add_f32_e32 v142, v86, v142
	v_add_f32_e32 v142, v87, v142
	v_cvt_pk_bf16_f32 v228, v88, v89
	v_cvt_pk_bf16_f32 v229, v90, v91
	v_cvt_pk_bf16_f32 v230, v92, v93
	v_cvt_pk_bf16_f32 v231, v94, v95
	s_nop 0
	s_nop 0
	s_waitcnt lgkmcnt(2)
	v_mfma_f32_32x32x16_bf16 v[0:15], v[150:153], v[228:231], v[0:15]
	v_add_f32_e32 v142, v88, v142
	v_add_f32_e32 v142, v89, v142
	v_add_f32_e32 v142, v90, v142
	v_add_f32_e32 v142, v91, v142
	s_waitcnt lgkmcnt(1)
	v_mfma_f32_32x32x16_bf16 v[16:31], v[248:251], v[228:231], v[16:31]
	v_add_f32_e32 v142, v92, v142
	v_add_f32_e32 v142, v93, v142
	v_add_f32_e32 v142, v94, v142
	v_add_f32_e32 v142, v95, v142
	v_mfma_f32_32x32x16_bf16 v[32:47], v[108:111], v[228:231], v[32:47]
	v_add_f32_e32 v176, v128, v142
	v_cmp_neq_f32_e32 vcc, v129, v177
	v_add_u32_e32 v140, 0x9800, v140
	v_add_u32_e32 v141, 0x9800, v141
	v_lshl_add_u64 v[130:131], v[130:131], 0, s[90:91]
	v_lshl_add_u64 v[132:133], v[132:133], 0, s[90:91]
	s_waitcnt lgkmcnt(0)
	v_mfma_f32_32x32x16_bf16 v[48:63], v[146:149], v[228:231], v[48:63]
	s_mov_b32 s22, 0x80000000
	s_cmp_eq_u64 vcc, 0
	s_cbranch_scc1 .Lda_negm_same
	v_xor_b32_e32 v79, s22, v129
	v_xor_b32_e32 v78, s22, v129
	v_xor_b32_e32 v77, s22, v129
	v_xor_b32_e32 v76, s22, v129
	v_xor_b32_e32 v75, s22, v129
	v_xor_b32_e32 v74, s22, v129
	v_xor_b32_e32 v73, s22, v129
	v_xor_b32_e32 v72, s22, v129
	v_xor_b32_e32 v71, s22, v129
	v_xor_b32_e32 v70, s22, v129
	v_xor_b32_e32 v69, s22, v129
	v_xor_b32_e32 v68, s22, v129
	v_xor_b32_e32 v67, s22, v129
	v_xor_b32_e32 v66, s22, v129
	v_xor_b32_e32 v65, s22, v129
	v_xor_b32_e32 v64, s22, v129
.Lda_negm_same:
	s_nop 0
	s_add_i32 s20, s10, s20
	s_cmp_lg_u32 s21, s12
	s_cselect_b32 s12, s20, 0x13000
	s_add_i32 s12, s12, 0
	s_add_i32 s11, s11, 1
	s_add_i32 s10, s10, 0x9800
	v_add3_u32 v80, s12, v137, v186
	v_add3_u32 v81, s12, v138, v186
	v_readfirstlane_b32 s20, v200
	s_nop 1
	s_bitcmp1_b32 s20, 8
	s_cbranch_scc1 .Lda_nobar_a
	s_barrier

; #define LAS __attribute__((address_space(3)))
; DI int crow(int i, int h) { return (i & 3) + 8 * (i >> 2) + 4 * h; }
; #define MFMA32(a, b, c) __builtin_amdgcn_mfma_f32_32x32x16_bf16((a), (b), (c), 0, 0, 0)
; #define SBAR() __builtin_amdgcn_sched_barrier(0)
; template <int KSTR> DI void qk64c(f32x16& s0, f32x16& s1, const lds8* kp, const bf16x8 (&q)[4], const f32x16& negm) {
;   bf16x8 a[8];
; #pragma unroll
;   for (int ks = 0; ks < 4; ++ks) { a[2 * ks] = *(const LAS bf16x8*)(kp + ks * 32); a[2 * ks + 1] = *(const LAS bf16x8*)(kp + 32 * KSTR + ks * 32); }
;   SBAR();
;   __builtin_amdgcn_s_setprio(1);
;   s0 = MFMA32(a[0], q[0], negm); s1 = MFMA32(a[1], q[0], negm);
; #pragma unroll
;   for (int ks = 1; ks < 4; ++ks) { s0 = MFMA32(a[2 * ks], q[ks], s0); s1 = MFMA32(a[2 * ks + 1], q[ks], s1); }
;   __builtin_amdgcn_s_setprio(0);
;   SBAR();
; }
; template <bool LOAD2, bool MASK>
; DI void da_step(lds8* lds, const DaCtx& cx, int t, const bf16x8 (&q)[4], f32x16 (&O)[4], float& muse, float& l, f32x16& negm) {
;     ...
;   SBAR();
;   const int st = t % 3, stn2 = (st == 0) ? 2 : st - 1;
;   const bool cur_live = !MASK || 64 * t <= cx.q0 + 32 * cx.qs + 31;
;   if (cur_live) {
;     f32x16 sa0, sa1, du0, du1;
;     qk64c<DA_KSTR>(sa0, sa1, lds + st * DA_STAGE + cx.koff, q, negm);
;     if (MASK) {
;       if (64 * t + 63 > cx.q0 + 32 * cx.qs) {
; #pragma unroll
;         for (int i = 0; i < 16; ++i) { const int key = 64 * t + crow(i, cx.h); if (key > cx.qpos) sa0[i] = NEG; if (key + 32 > cx.qpos) sa1[i] = NEG; }
;       }
;     }
.LBB0_854:
	v_and_b32_e32 v194, 63, v134
	v_lshlrev_b32_e32 v193, 3, v135
	v_bfe_u32 v177, v134, 4, 2
	v_lshlrev_b32_e32 v192, 3, v136
	s_lshl_b32 s10, s19, 6
	s_or_b32 s20, s18, 31
	s_cmp_gt_u32 s10, s20
	s_cbranch_scc1 .LBB0_866
	s_mul_hi_u32 s6, s19, 0x55555556
	s_mul_i32 s6, s6, 3
	s_sub_i32 s6, s19, s6
	s_mul_i32 s6, s6, 0x9800
	s_add_i32 s6, s6, 0
	v_add_u32_e32 v84, s6, v144
	ds_read_b128 v[80:83], v84
	ds_read_b128 v[112:115], v84 offset:32
	ds_read_b128 v[116:119], v84 offset:9728
	ds_read_b128 v[120:123], v84 offset:9760
	ds_read_b128 v[124:127], v84 offset:64
	ds_read_b128 v[130:133], v84 offset:96
	ds_read_b128 v[134:137], v84 offset:9792
	ds_read_b128 v[138:141], v84 offset:9824
	s_nop 0
	s_waitcnt lgkmcnt(7)
	v_mfma_f32_32x32x16_bf16 v[96:111], v[80:83], v[172:175], v[64:79]
	s_waitcnt lgkmcnt(5)
	v_mfma_f32_32x32x16_bf16 v[80:95], v[116:119], v[172:175], v[64:79]
	v_mfma_f32_32x32x16_bf16 v[96:111], v[112:115], v[168:171], v[96:111]
	s_waitcnt lgkmcnt(4)
	v_mfma_f32_32x32x16_bf16 v[80:95], v[120:123], v[168:171], v[80:95]
	s_waitcnt lgkmcnt(3)
	v_mfma_f32_32x32x16_bf16 v[96:111], v[124:127], v[164:167], v[96:111]
	s_waitcnt lgkmcnt(1)
	v_mfma_f32_32x32x16_bf16 v[80:95], v[134:137], v[164:167], v[80:95]
	v_mfma_f32_32x32x16_bf16 v[96:111], v[130:133], v[160:163], v[96:111]
	s_waitcnt lgkmcnt(0)
	v_mfma_f32_32x32x16_bf16 v[80:95], v[138:141], v[160:163], v[80:95]
	s_nop 0
	s_or_b32 s11, s10, 63
	s_cmp_le_u32 s11, s18
	s_cbranch_scc1 .LBB0_857
	v_or_b32_e32 v112, s10, v180
	v_or_b32_e32 v113, 32, v112
	v_cmp_le_u32_e32 vcc, v113, v183
	v_or_b32_e32 v113, 33, v112
	s_nop 3
	v_cndmask_b32_e32 v80, v207, v80, vcc
	v_cmp_lt_u32_e32 vcc, v112, v183
	s_nop 1
	v_cndmask_b32_e32 v97, v207, v97, vcc
	v_cmp_le_u32_e32 vcc, v112, v183
	s_nop 1
	v_cndmask_b32_e32 v96, v207, v96, vcc
	v_cmp_le_u32_e32 vcc, v113, v183
	v_or_b32_e32 v113, 2, v112
	s_nop 0
	v_cndmask_b32_e32 v81, v207, v81, vcc
	v_cmp_le_u32_e32 vcc, v113, v183
	v_or_b32_e32 v113, 34, v112
	s_nop 0
	v_cndmask_b32_e32 v98, v207, v98, vcc
	v_cmp_le_u32_e32 vcc, v113, v183
	v_or_b32_e32 v113, 3, v112
	s_nop 0
	v_cndmask_b32_e32 v82, v207, v82, vcc
	v_cmp_le_u32_e32 vcc, v113, v183
	v_or_b32_e32 v113, 35, v112
	s_nop 0
	v_cndmask_b32_e32 v99, v207, v99, vcc
	v_cmp_le_u32_e32 vcc, v113, v183
	v_or_b32_e32 v113, 8, v112
	s_nop 0
	v_cndmask_b32_e32 v83, v207, v83, vcc
	v_cmp_le_u32_e32 vcc, v113, v183
	v_or_b32_e32 v113, 40, v112
	s_nop 0
	v_cndmask_b32_e32 v100, v207, v100, vcc
	v_cmp_le_u32_e32 vcc, v113, v183
	v_or_b32_e32 v113, 9, v112
	s_nop 0
	v_cndmask_b32_e32 v84, v207, v84, vcc
	v_cmp_le_u32_e32 vcc, v113, v183
	v_or_b32_e32 v113, 41, v112
	s_nop 0
	v_cndmask_b32_e32 v101, v207, v101, vcc
	v_cmp_le_u32_e32 vcc, v113, v183
	v_or_b32_e32 v113, 10, v112
	s_nop 0
	v_cndmask_b32_e32 v85, v207, v85, vcc
	v_cmp_le_u32_e32 vcc, v113, v183
	v_or_b32_e32 v113, 42, v112
	s_nop 0
	v_cndmask_b32_e32 v102, v207, v102, vcc
	v_cmp_le_u32_e32 vcc, v113, v183
	v_or_b32_e32 v113, 11, v112
	s_nop 0
	v_cndmask_b32_e32 v86, v207, v86, vcc
	v_cmp_le_u32_e32 vcc, v113, v183
	v_or_b32_e32 v113, 43, v112
	s_nop 0
	v_cndmask_b32_e32 v103, v207, v103, vcc
	v_cmp_le_u32_e32 vcc, v113, v183
	v_or_b32_e32 v113, 16, v112
	s_nop 0
	v_cndmask_b32_e32 v87, v207, v87, vcc
	v_cmp_le_u32_e32 vcc, v113, v183
	v_or_b32_e32 v113, 48, v112
	s_nop 0
	v_cndmask_b32_e32 v104, v207, v104, vcc
	v_cmp_le_u32_e32 vcc, v113, v183
	v_or_b32_e32 v113, 17, v112
	s_nop 0
	v_cndmask_b32_e32 v88, v207, v88, vcc
	v_cmp_le_u32_e32 vcc, v113, v183
	v_or_b32_e32 v113, 49, v112
	s_nop 0
	v_cndmask_b32_e32 v105, v207, v105, vcc
	v_cmp_le_u32_e32 vcc, v113, v183
	v_or_b32_e32 v113, 18, v112
	s_nop 0
	v_cndmask_b32_e32 v89, v207, v89, vcc
	v_cmp_le_u32_e32 vcc, v113, v183
	v_or_b32_e32 v113, 50, v112
	s_nop 0
	v_cndmask_b32_e32 v106, v207, v106, vcc
	v_cmp_le_u32_e32 vcc, v113, v183
	v_or_b32_e32 v113, 19, v112
	s_nop 0
	v_cndmask_b32_e32 v90, v207, v90, vcc
	v_cmp_le_u32_e32 vcc, v113, v183
	v_or_b32_e32 v113, 51, v112
	s_nop 0
	v_cndmask_b32_e32 v107, v207, v107, vcc
	v_cmp_le_u32_e32 vcc, v113, v183
	v_or_b32_e32 v113, 24, v112
	s_nop 0
	v_cndmask_b32_e32 v91, v207, v91, vcc
	v_cmp_le_u32_e32 vcc, v113, v183
	v_or_b32_e32 v113, 56, v112
	s_nop 0
	v_cndmask_b32_e32 v108, v207, v108, vcc
	v_cmp_le_u32_e32 vcc, v113, v183
	v_or_b32_e32 v113, 25, v112
	s_nop 0
	v_cndmask_b32_e32 v92, v207, v92, vcc
	v_cmp_le_u32_e32 vcc, v113, v183
	v_or_b32_e32 v113, 57, v112
	s_nop 0
	v_cndmask_b32_e32 v109, v207, v109, vcc
	v_cmp_le_u32_e32 vcc, v113, v183
	v_or_b32_e32 v113, 26, v112
	s_nop 0
	v_cndmask_b32_e32 v93, v207, v93, vcc
	v_cmp_le_u32_e32 vcc, v113, v183
	v_or_b32_e32 v113, 58, v112
	s_nop 0
	v_cndmask_b32_e32 v110, v207, v110, vcc
	v_cmp_le_u32_e32 vcc, v113, v183
	v_or_b32_e32 v113, 27, v112
	v_or_b32_e32 v112, 59, v112
	v_cndmask_b32_e32 v94, v207, v94, vcc
	v_cmp_le_u32_e32 vcc, v113, v183
	s_nop 1
	v_cndmask_b32_e32 v111, v207, v111, vcc
	v_cmp_le_u32_e32 vcc, v112, v183
	s_nop 1
	v_cndmask_b32_e32 v95, v207, v95, vcc

; template <int NDVB, bool HAS_NEXT> DI void softmax_def(f32x16& sa0, f32x16& sa1, f32x16& sb0, f32x16& sb1, f32x16 (&O)[NDVB], float& muse, float& l, bool first, bf16x8 (&P)[4], bool check = true) {
;     ...
;   float sum = 0.f;
; #pragma unroll
;   for (int i = 0; i < 16; ++i) { sa0[i] = __builtin_amdgcn_exp2f(sa0[i]); sum += sa0[i]; }
; #pragma unroll
;   for (int i = 0; i < 16; ++i) { sa1[i] = __builtin_amdgcn_exp2f(sa1[i]); sum += sa1[i]; }
;   l += sum;
;   u32x4 w;
;   w.x = cvtpk(sa0[0], sa0[1]); w.y = cvtpk(sa0[2], sa0[3]); w.z = cvtpk(sa0[4], sa0[5]); w.w = cvtpk(sa0[6], sa0[7]); P[0] = __builtin_bit_cast(bf16x8, w);
;   w.x = cvtpk(sa0[8], sa0[9]); w.y = cvtpk(sa0[10], sa0[11]); w.z = cvtpk(sa0[12], sa0[13]); w.w = cvtpk(sa0[14], sa0[15]); P[1] = __builtin_bit_cast(bf16x8, w);
;   w.x = cvtpk(sa1[0], sa1[1]); w.y = cvtpk(sa1[2], sa1[3]); w.z = cvtpk(sa1[4], sa1[5]); w.w = cvtpk(sa1[6], sa1[7]); P[2] = __builtin_bit_cast(bf16x8, w);
;   w.x = cvtpk(sa1[8], sa1[9]); w.y = cvtpk(sa1[10], sa1[11]); w.z = cvtpk(sa1[12], sa1[13]); w.w = cvtpk(sa1[14], sa1[15]); P[3] = __builtin_bit_cast(bf16x8, w);
; }
; template <bool LOAD2, bool MASK>
; DI void da_step(lds8* lds, const DaCtx& cx, int t, const bf16x8 (&q)[4], f32x16 (&O)[4], float& muse, float& l, f32x16& negm) {
;   u32x4 kr0, kr1, vr0, vr1;
;   if (LOAD2) { const size_t ro = (size_t)(t + 2) * 64;
;     kr0 = *(const u32x4*)(cx.kg + (ro + cx.sr0) * DM + cx.sc0 * 8); kr1 = *(const u32x4*)(cx.kg + (ro + cx.sr1) * DM + cx.sc1 * 8);
;     vr0 = *(const u32x4*)(cx.vg + (ro + cx.sr0) * DM + cx.sc0 * 8); vr1 = *(const u32x4*)(cx.vg + (ro + cx.sr1) * DM + cx.sc1 * 8); }
;   SBAR();
;   const int st = t % 3, stn2 = (st == 0) ? 2 : st - 1;
;   const bool cur_live = !MASK || 64 * t <= cx.q0 + 32 * cx.qs + 31;
;   if (cur_live) {
;     f32x16 sa0, sa1, du0, du1;
;     qk64c<DA_KSTR>(sa0, sa1, lds + st * DA_STAGE + cx.koff, q, negm);
;     if (MASK) {
;       if (64 * t + 63 > cx.q0 + 32 * cx.qs) {
; #pragma unroll
;         for (int i = 0; i < 16; ++i) { const int key = 64 * t + crow(i, cx.h); if (key > cx.qpos) sa0[i] = NEG; if (key + 32 > cx.qpos) sa1[i] = NEG; }
;       }
;     }
;     bf16x8 P[4];
;     const float mprev = muse;
;     softmax_def<4, false>(sa0, sa1, du0, du1, O, muse, l, t == 0, P, MASK || (t & 1) == 0);
;     if (__any(muse != mprev)) {
; #pragma unroll
.LBB0_865:
	v_exp_f32_e32 v96, v96
	v_exp_f32_e32 v97, v97
	v_exp_f32_e32 v98, v98
	v_exp_f32_e32 v99, v99
	v_add_f32_e32 v113, 0, v96
	v_exp_f32_e32 v100, v100
	v_add_f32_e32 v113, v97, v113
	v_exp_f32_e32 v101, v101
	v_add_f32_e32 v113, v98, v113
	v_exp_f32_e32 v102, v102
	v_add_f32_e32 v113, v99, v113
	v_exp_f32_e32 v103, v103
	v_add_f32_e32 v113, v100, v113
	v_exp_f32_e32 v104, v104
	v_add_f32_e32 v113, v101, v113
	v_exp_f32_e32 v105, v105
	v_add_f32_e32 v113, v102, v113
	v_exp_f32_e32 v106, v106
	v_add_f32_e32 v113, v103, v113
	v_exp_f32_e32 v107, v107
	v_add_f32_e32 v113, v104, v113
	v_exp_f32_e32 v108, v108
	v_add_f32_e32 v113, v105, v113
	v_exp_f32_e32 v109, v109
	v_add_f32_e32 v113, v106, v113
	v_exp_f32_e32 v110, v110
	v_add_f32_e32 v113, v107, v113
	v_exp_f32_e32 v111, v111
	v_add_f32_e32 v113, v108, v113
	v_exp_f32_e32 v80, v80
	v_add_f32_e32 v113, v109, v113
	v_exp_f32_e32 v81, v81
	v_add_f32_e32 v113, v110, v113
	v_exp_f32_e32 v82, v82
	v_add_f32_e32 v113, v111, v113
	v_exp_f32_e32 v83, v83
	v_add_f32_e32 v113, v80, v113
	v_exp_f32_e32 v114, v84
	v_add_f32_e32 v113, v81, v113
	v_add_f32_e32 v113, v82, v113
	v_add_f32_e32 v113, v83, v113
	v_add_f32_e32 v84, v114, v113
	v_exp_f32_e32 v113, v85
	v_exp_f32_e32 v115, v86
	v_exp_f32_e32 v116, v87
	v_exp_f32_e32 v117, v88
	v_add_f32_e32 v84, v113, v84
	v_exp_f32_e32 v118, v89
	v_add_f32_e32 v84, v115, v84
	v_exp_f32_e32 v119, v90
	v_add_f32_e32 v84, v116, v84
	v_exp_f32_e32 v120, v91
	v_add_f32_e32 v84, v117, v84
	v_exp_f32_e32 v121, v92
	v_add_f32_e32 v84, v118, v84
	v_exp_f32_e32 v122, v93
	v_add_f32_e32 v84, v119, v84
	v_exp_f32_e32 v123, v94
	v_add_f32_e32 v84, v120, v84
	v_exp_f32_e32 v124, v95
	v_add_f32_e32 v84, v121, v84
	v_add_f32_e32 v84, v122, v84
	v_cmp_neq_f32_e32 vcc, v112, v129
	v_add_f32_e32 v84, v123, v84
	s_cmp_eq_u64 vcc, 0
	v_add_f32_e32 v84, v124, v84
	s_cselect_b64 s[10:11], -1, 0
	v_add3_u32 v128, v181, v182, s6
	v_add_f32_e32 v176, v176, v84
	v_cvt_pk_bf16_f32 v84, v96, v97
	v_cvt_pk_bf16_f32 v85, v98, v99
	v_cvt_pk_bf16_f32 v86, v100, v101
	v_cvt_pk_bf16_f32 v87, v102, v103
	v_cvt_pk_bf16_f32 v88, v104, v105
	v_cvt_pk_bf16_f32 v89, v106, v107
	v_cvt_pk_bf16_f32 v90, v108, v109
	v_cvt_pk_bf16_f32 v91, v110, v111
	v_cvt_pk_bf16_f32 v92, v80, v81
	v_cvt_pk_bf16_f32 v93, v82, v83
	v_cvt_pk_bf16_f32 v94, v114, v113
	v_cvt_pk_bf16_f32 v95, v115, v116
	v_cvt_pk_bf16_f32 v80, v117, v118
	v_cvt_pk_bf16_f32 v81, v119, v120
	v_cvt_pk_bf16_f32 v82, v121, v122
	v_cvt_pk_bf16_f32 v83, v123, v124
	v_cndmask_b32_e64 v79, -v112, v79, s[10:11]
	v_cndmask_b32_e64 v78, -v112, v78, s[10:11]
	v_cndmask_b32_e64 v77, -v112, v77, s[10:11]
	v_cndmask_b32_e64 v76, -v112, v76, s[10:11]
	v_cndmask_b32_e64 v75, -v112, v75, s[10:11]
	v_cndmask_b32_e64 v74, -v112, v74, s[10:11]
	v_cndmask_b32_e64 v73, -v112, v73, s[10:11]
	v_cndmask_b32_e64 v72, -v112, v72, s[10:11]
	v_cndmask_b32_e64 v71, -v112, v71, s[10:11]
	v_cndmask_b32_e64 v70, -v112, v70, s[10:11]
	v_cndmask_b32_e64 v69, -v112, v69, s[10:11]
	v_cndmask_b32_e64 v68, -v112, v68, s[10:11]
	v_cndmask_b32_e64 v67, -v112, v67, s[10:11]
	v_cndmask_b32_e64 v66, -v112, v66, s[10:11]
	v_cndmask_b32_e64 v65, -v112, v65, s[10:11]
	v_cndmask_b32_e64 v64, -v112, v64, s[10:11]
	ds_read_b64_tr_b16 v[96:97], v128 offset:19456
	ds_read_b64_tr_b16 v[98:99], v128 offset:21888
	ds_read_b64_tr_b16 v[100:101], v128 offset:19520
	ds_read_b64_tr_b16 v[102:103], v128 offset:21952
	ds_read_b64_tr_b16 v[104:105], v128 offset:19584
	ds_read_b64_tr_b16 v[106:107], v128 offset:22016
	ds_read_b64_tr_b16 v[108:109], v128 offset:19648
	ds_read_b64_tr_b16 v[110:111], v128 offset:22080
	ds_read_b64_tr_b16 v[112:113], v128 offset:24320
	ds_read_b64_tr_b16 v[114:115], v128 offset:26752
	ds_read_b64_tr_b16 v[116:117], v128 offset:24384
	ds_read_b64_tr_b16 v[118:119], v128 offset:26816
	ds_read_b64_tr_b16 v[120:121], v128 offset:24448
	ds_read_b64_tr_b16 v[122:123], v128 offset:26880
	ds_read_b64_tr_b16 v[124:125], v128 offset:24512
	ds_read_b64_tr_b16 v[126:127], v128 offset:26944
	s_nop 0
	s_waitcnt lgkmcnt(14)
	v_mfma_f32_32x32x16_bf16 v[0:15], v[96:99], v[84:87], v[0:15]
	s_waitcnt lgkmcnt(12)
	v_mfma_f32_32x32x16_bf16 v[16:31], v[100:103], v[84:87], v[16:31]
	s_waitcnt lgkmcnt(10)
	v_mfma_f32_32x32x16_bf16 v[32:47], v[104:107], v[84:87], v[32:47]
	s_waitcnt lgkmcnt(8)
	v_mfma_f32_32x32x16_bf16 v[48:63], v[108:111], v[84:87], v[48:63]
	s_nop 0
	ds_read_b64_tr_b16 v[84:85], v128 offset:29184
	ds_read_b64_tr_b16 v[96:97], v128 offset:29248
	ds_read_b64_tr_b16 v[100:101], v128 offset:29312
	ds_read_b64_tr_b16 v[104:105], v128 offset:29376
	ds_read_b64_tr_b16 v[86:87], v128 offset:31616
	ds_read_b64_tr_b16 v[98:99], v128 offset:31680
	ds_read_b64_tr_b16 v[102:103], v128 offset:31744
	ds_read_b64_tr_b16 v[106:107], v128 offset:31808
	s_nop 0
	s_waitcnt lgkmcnt(14)
	v_mfma_f32_32x32x16_bf16 v[0:15], v[112:115], v[88:91], v[0:15]
	s_waitcnt lgkmcnt(12)
	v_mfma_f32_32x32x16_bf16 v[16:31], v[116:119], v[88:91], v[16:31]
	s_waitcnt lgkmcnt(10)
	v_mfma_f32_32x32x16_bf16 v[32:47], v[120:123], v[88:91], v[32:47]
	s_waitcnt lgkmcnt(8)
	v_mfma_f32_32x32x16_bf16 v[48:63], v[124:127], v[88:91], v[48:63]
	s_nop 0
	ds_read_b64_tr_b16 v[88:89], v128 offset:34048
	ds_read_b64_tr_b16 v[108:109], v128 offset:34112
	ds_read_b64_tr_b16 v[112:113], v128 offset:34176
	ds_read_b64_tr_b16 v[116:117], v128 offset:34240
	ds_read_b64_tr_b16 v[90:91], v128 offset:36480
	ds_read_b64_tr_b16 v[110:111], v128 offset:36544
	ds_read_b64_tr_b16 v[114:115], v128 offset:36608
	ds_read_b64_tr_b16 v[118:119], v128 offset:36672
	s_nop 0
	s_waitcnt lgkmcnt(11)
	v_mfma_f32_32x32x16_bf16 v[0:15], v[84:87], v[92:95], v[0:15]
	s_waitcnt lgkmcnt(10)
	v_mfma_f32_32x32x16_bf16 v[16:31], v[96:99], v[92:95], v[16:31]
	s_waitcnt lgkmcnt(9)
	v_mfma_f32_32x32x16_bf16 v[32:47], v[100:103], v[92:95], v[32:47]
	s_waitcnt lgkmcnt(8)
	v_mfma_f32_32x32x16_bf16 v[48:63], v[104:107], v[92:95], v[48:63]
	s_nop 0
	s_nop 0
	s_waitcnt lgkmcnt(3)
	v_mfma_f32_32x32x16_bf16 v[0:15], v[88:91], v[80:83], v[0:15]
	s_waitcnt lgkmcnt(2)
	v_mfma_f32_32x32x16_bf16 v[16:31], v[108:111], v[80:83], v[16:31]
	s_waitcnt lgkmcnt(1)
	v_mfma_f32_32x32x16_bf16 v[32:47], v[112:115], v[80:83], v[32:47]
	s_waitcnt lgkmcnt(0)
	v_mfma_f32_32x32x16_bf16 v[48:63], v[116:119], v[80:83], v[48:63]
	s_nop 0
; #define LAS __attribute__((address_space(3)))
; DI int crow(int i, int h) { return (i & 3) + 8 * (i >> 2) + 4 * h; }
; #define MFMA32(a, b, c) __builtin_amdgcn_mfma_f32_32x32x16_bf16((a), (b), (c), 0, 0, 0)
; #define SBAR() __builtin_amdgcn_sched_barrier(0)
; template <int KSTR> DI void qk64c(f32x16& s0, f32x16& s1, const lds8* kp, const bf16x8 (&q)[4], const f32x16& negm) {
;   bf16x8 a[8];
; #pragma unroll
;   for (int ks = 0; ks < 4; ++ks) { a[2 * ks] = *(const LAS bf16x8*)(kp + ks * 32); a[2 * ks + 1] = *(const LAS bf16x8*)(kp + 32 * KSTR + ks * 32); }
;   SBAR();
;   __builtin_amdgcn_s_setprio(1);
;   s0 = MFMA32(a[0], q[0], negm); s1 = MFMA32(a[1], q[0], negm);
; #pragma unroll
;   for (int ks = 1; ks < 4; ++ks) { s0 = MFMA32(a[2 * ks], q[ks], s0); s1 = MFMA32(a[2 * ks + 1], q[ks], s1); }
;   __builtin_amdgcn_s_setprio(0);
;   SBAR();
; }
; template <bool LOAD2, bool MASK>
; DI void da_step(lds8* lds, const DaCtx& cx, int t, const bf16x8 (&q)[4], f32x16 (&O)[4], float& muse, float& l, f32x16& negm) {
;     ...
;   SBAR();
;   const int st = t % 3, stn2 = (st == 0) ? 2 : st - 1;
;   const bool cur_live = !MASK || 64 * t <= cx.q0 + 32 * cx.qs + 31;
;   if (cur_live) {
;     f32x16 sa0, sa1, du0, du1;
;     qk64c<DA_KSTR>(sa0, sa1, lds + st * DA_STAGE + cx.koff, q, negm);
;     if (MASK) {
;       if (64 * t + 63 > cx.q0 + 32 * cx.qs) {
; #pragma unroll
;         for (int i = 0; i < 16; ++i) { const int key = 64 * t + crow(i, cx.h); if (key > cx.qpos) sa0[i] = NEG; if (key + 32 > cx.qpos) sa1[i] = NEG; }
;       }
;     }
.LBB0_866:
	s_or_b32 s6, s19, 1
	s_lshl_b32 s12, s6, 6
	s_cmp_le_u32 s12, s20
	s_mov_b64 s[10:11], -1
	s_cbranch_scc0 .LBB0_872
	s_mul_hi_u32 s10, s6, 0x55555556
	s_mul_i32 s10, s10, 3
	s_sub_i32 s6, s6, s10
	s_mul_i32 s6, s6, 0x9800
	s_add_i32 s6, s6, 0
	v_add_u32_e32 v108, s6, v144
	ds_read_b128 v[80:83], v108
	ds_read_b128 v[84:87], v108 offset:32
	ds_read_b128 v[88:91], v108 offset:9728
	ds_read_b128 v[92:95], v108 offset:9760
	ds_read_b128 v[96:99], v108 offset:64
	ds_read_b128 v[100:103], v108 offset:96
	ds_read_b128 v[104:107], v108 offset:9792
	ds_read_b128 v[108:111], v108 offset:9824
	s_nop 0
	s_waitcnt lgkmcnt(7)
	v_mfma_f32_32x32x16_bf16 v[144:159], v[80:83], v[172:175], v[64:79]
	s_waitcnt lgkmcnt(5)
	v_mfma_f32_32x32x16_bf16 v[64:79], v[88:91], v[172:175], v[64:79]
	v_mfma_f32_32x32x16_bf16 v[144:159], v[84:87], v[168:171], v[144:159]
	s_waitcnt lgkmcnt(4)
	v_mfma_f32_32x32x16_bf16 v[64:79], v[92:95], v[168:171], v[64:79]
	s_waitcnt lgkmcnt(3)
	v_mfma_f32_32x32x16_bf16 v[144:159], v[96:99], v[164:167], v[144:159]
	s_waitcnt lgkmcnt(1)
	v_mfma_f32_32x32x16_bf16 v[64:79], v[104:107], v[164:167], v[64:79]
	v_mfma_f32_32x32x16_bf16 v[144:159], v[100:103], v[160:163], v[144:159]
	s_waitcnt lgkmcnt(0)
	v_mfma_f32_32x32x16_bf16 v[64:79], v[108:111], v[160:163], v[64:79]
	s_nop 0
	s_or_b32 s10, s12, 63
	s_cmp_le_u32 s10, s18
	s_cbranch_scc1 .LBB0_869
	v_or_b32_e32 v80, s12, v180
	v_or_b32_e32 v81, 32, v80
	v_cmp_le_u32_e32 vcc, v81, v183
	v_or_b32_e32 v81, 33, v80
	s_nop 3
	v_cndmask_b32_e32 v64, v207, v64, vcc
	v_cmp_lt_u32_e32 vcc, v80, v183
	s_nop 1
	v_cndmask_b32_e32 v145, v207, v145, vcc
	v_cmp_le_u32_e32 vcc, v80, v183
	s_nop 1
	v_cndmask_b32_e32 v144, v207, v144, vcc
	v_cmp_le_u32_e32 vcc, v81, v183
	v_or_b32_e32 v81, 2, v80
	s_nop 0
	v_cndmask_b32_e32 v65, v207, v65, vcc
	v_cmp_le_u32_e32 vcc, v81, v183
	v_or_b32_e32 v81, 34, v80
	s_nop 0
	v_cndmask_b32_e32 v146, v207, v146, vcc
	v_cmp_le_u32_e32 vcc, v81, v183
	v_or_b32_e32 v81, 3, v80
	s_nop 0
	v_cndmask_b32_e32 v66, v207, v66, vcc
	v_cmp_le_u32_e32 vcc, v81, v183
	v_or_b32_e32 v81, 35, v80
	s_nop 0
	v_cndmask_b32_e32 v147, v207, v147, vcc
	v_cmp_le_u32_e32 vcc, v81, v183
	v_or_b32_e32 v81, 8, v80
	s_nop 0
	v_cndmask_b32_e32 v67, v207, v67, vcc
	v_cmp_le_u32_e32 vcc, v81, v183
	v_or_b32_e32 v81, 40, v80
	s_nop 0
	v_cndmask_b32_e32 v148, v207, v148, vcc
	v_cmp_le_u32_e32 vcc, v81, v183
	v_or_b32_e32 v81, 9, v80
	s_nop 0
	v_cndmask_b32_e32 v68, v207, v68, vcc
	v_cmp_le_u32_e32 vcc, v81, v183
	v_or_b32_e32 v81, 41, v80
	s_nop 0
	v_cndmask_b32_e32 v149, v207, v149, vcc
	v_cmp_le_u32_e32 vcc, v81, v183
	v_or_b32_e32 v81, 10, v80
	s_nop 0
	v_cndmask_b32_e32 v69, v207, v69, vcc
	v_cmp_le_u32_e32 vcc, v81, v183
	v_or_b32_e32 v81, 42, v80
	s_nop 0
	v_cndmask_b32_e32 v150, v207, v150, vcc
	v_cmp_le_u32_e32 vcc, v81, v183
	v_or_b32_e32 v81, 11, v80
	s_nop 0
	v_cndmask_b32_e32 v70, v207, v70, vcc
	v_cmp_le_u32_e32 vcc, v81, v183
	v_or_b32_e32 v81, 43, v80
	s_nop 0
	v_cndmask_b32_e32 v151, v207, v151, vcc
	v_cmp_le_u32_e32 vcc, v81, v183
	v_or_b32_e32 v81, 16, v80
	s_nop 0
	v_cndmask_b32_e32 v71, v207, v71, vcc
	v_cmp_le_u32_e32 vcc, v81, v183
	v_or_b32_e32 v81, 48, v80
	s_nop 0
	v_cndmask_b32_e32 v152, v207, v152, vcc
	v_cmp_le_u32_e32 vcc, v81, v183
	v_or_b32_e32 v81, 17, v80
	s_nop 0
	v_cndmask_b32_e32 v72, v207, v72, vcc
	v_cmp_le_u32_e32 vcc, v81, v183
	v_or_b32_e32 v81, 49, v80
	s_nop 0
	v_cndmask_b32_e32 v153, v207, v153, vcc
	v_cmp_le_u32_e32 vcc, v81, v183
	v_or_b32_e32 v81, 18, v80
	s_nop 0
	v_cndmask_b32_e32 v73, v207, v73, vcc
	v_cmp_le_u32_e32 vcc, v81, v183
	v_or_b32_e32 v81, 50, v80
	s_nop 0
	v_cndmask_b32_e32 v154, v207, v154, vcc
	v_cmp_le_u32_e32 vcc, v81, v183
	v_or_b32_e32 v81, 19, v80
	s_nop 0
	v_cndmask_b32_e32 v74, v207, v74, vcc
	v_cmp_le_u32_e32 vcc, v81, v183
	v_or_b32_e32 v81, 51, v80
	s_nop 0
	v_cndmask_b32_e32 v155, v207, v155, vcc
	v_cmp_le_u32_e32 vcc, v81, v183
	v_or_b32_e32 v81, 24, v80
	s_nop 0
	v_cndmask_b32_e32 v75, v207, v75, vcc
	v_cmp_le_u32_e32 vcc, v81, v183
	v_or_b32_e32 v81, 56, v80
	s_nop 0
	v_cndmask_b32_e32 v156, v207, v156, vcc
	v_cmp_le_u32_e32 vcc, v81, v183
	v_or_b32_e32 v81, 25, v80
	s_nop 0
	v_cndmask_b32_e32 v76, v207, v76, vcc
	v_cmp_le_u32_e32 vcc, v81, v183
	v_or_b32_e32 v81, 57, v80
	s_nop 0
	v_cndmask_b32_e32 v157, v207, v157, vcc
	v_cmp_le_u32_e32 vcc, v81, v183
	v_or_b32_e32 v81, 26, v80
	s_nop 0
	v_cndmask_b32_e32 v77, v207, v77, vcc
	v_cmp_le_u32_e32 vcc, v81, v183
	v_or_b32_e32 v81, 58, v80
	s_nop 0
	v_cndmask_b32_e32 v158, v207, v158, vcc
	v_cmp_le_u32_e32 vcc, v81, v183
	v_or_b32_e32 v81, 27, v80
	v_or_b32_e32 v80, 59, v80
	v_cndmask_b32_e32 v78, v207, v78, vcc
	v_cmp_le_u32_e32 vcc, v81, v183
	s_nop 1
	v_cndmask_b32_e32 v159, v207, v159, vcc
	v_cmp_le_u32_e32 vcc, v80, v183
	s_nop 1
	v_cndmask_b32_e32 v79, v207, v79, vcc

; template <int NDVB, bool HAS_NEXT> DI void softmax_def(f32x16& sa0, f32x16& sa1, f32x16& sb0, f32x16& sb1, f32x16 (&O)[NDVB], float& muse, float& l, bool first, bf16x8 (&P)[4], bool check = true) {
;     ...
;   float sum = 0.f;
; #pragma unroll
;   for (int i = 0; i < 16; ++i) { sa0[i] = __builtin_amdgcn_exp2f(sa0[i]); sum += sa0[i]; }
; #pragma unroll
;   for (int i = 0; i < 16; ++i) { sa1[i] = __builtin_amdgcn_exp2f(sa1[i]); sum += sa1[i]; }
;   l += sum;
;   u32x4 w;
;   w.x = cvtpk(sa0[0], sa0[1]); w.y = cvtpk(sa0[2], sa0[3]); w.z = cvtpk(sa0[4], sa0[5]); w.w = cvtpk(sa0[6], sa0[7]); P[0] = __builtin_bit_cast(bf16x8, w);
;   w.x = cvtpk(sa0[8], sa0[9]); w.y = cvtpk(sa0[10], sa0[11]); w.z = cvtpk(sa0[12], sa0[13]); w.w = cvtpk(sa0[14], sa0[15]); P[1] = __builtin_bit_cast(bf16x8, w);
;   w.x = cvtpk(sa1[0], sa1[1]); w.y = cvtpk(sa1[2], sa1[3]); w.z = cvtpk(sa1[4], sa1[5]); w.w = cvtpk(sa1[6], sa1[7]); P[2] = __builtin_bit_cast(bf16x8, w);
;   w.x = cvtpk(sa1[8], sa1[9]); w.y = cvtpk(sa1[10], sa1[11]); w.z = cvtpk(sa1[12], sa1[13]); w.w = cvtpk(sa1[14], sa1[15]); P[3] = __builtin_bit_cast(bf16x8, w);
; }
; template <bool LOAD2, bool MASK>
; DI void da_step(lds8* lds, const DaCtx& cx, int t, const bf16x8 (&q)[4], f32x16 (&O)[4], float& muse, float& l, f32x16& negm) {
;   u32x4 kr0, kr1, vr0, vr1;
;   if (LOAD2) { const size_t ro = (size_t)(t + 2) * 64;
;     kr0 = *(const u32x4*)(cx.kg + (ro + cx.sr0) * DM + cx.sc0 * 8); kr1 = *(const u32x4*)(cx.kg + (ro + cx.sr1) * DM + cx.sc1 * 8);
;     vr0 = *(const u32x4*)(cx.vg + (ro + cx.sr0) * DM + cx.sc0 * 8); vr1 = *(const u32x4*)(cx.vg + (ro + cx.sr1) * DM + cx.sc1 * 8); }
;   SBAR();
;   const int st = t % 3, stn2 = (st == 0) ? 2 : st - 1;
;   const bool cur_live = !MASK || 64 * t <= cx.q0 + 32 * cx.qs + 31;
;   if (cur_live) {
;     f32x16 sa0, sa1, du0, du1;
;     qk64c<DA_KSTR>(sa0, sa1, lds + st * DA_STAGE + cx.koff, q, negm);
;     if (MASK) {
;       if (64 * t + 63 > cx.q0 + 32 * cx.qs) {
; #pragma unroll
;         for (int i = 0; i < 16; ++i) { const int key = 64 * t + crow(i, cx.h); if (key > cx.qpos) sa0[i] = NEG; if (key + 32 > cx.qpos) sa1[i] = NEG; }
;       }
;     }
;     bf16x8 P[4];
;     const float mprev = muse;
;     softmax_def<4, false>(sa0, sa1, du0, du1, O, muse, l, t == 0, P, MASK || (t & 1) == 0);
;     if (__any(muse != mprev)) {
; #pragma unroll
.LBB0_871:
	v_exp_f32_e32 v144, v144
	v_exp_f32_e32 v162, v145
	v_exp_f32_e32 v146, v146
	v_exp_f32_e32 v147, v147
	v_add_f32_e32 v161, 0, v144
	v_exp_f32_e32 v148, v148
	v_add_f32_e32 v145, v162, v161
	v_exp_f32_e32 v149, v149
	v_add_f32_e32 v145, v146, v145
	v_exp_f32_e32 v150, v150
	v_add_f32_e32 v145, v147, v145
	v_exp_f32_e32 v151, v151
	v_add_f32_e32 v145, v148, v145
	v_exp_f32_e32 v152, v152
	v_add_f32_e32 v145, v149, v145
	v_exp_f32_e32 v153, v153
	v_add_f32_e32 v145, v150, v145
	v_exp_f32_e32 v154, v154
	v_add_f32_e32 v145, v151, v145
	v_exp_f32_e32 v155, v155
	v_add_f32_e32 v145, v152, v145
	v_exp_f32_e32 v156, v156
	v_add_f32_e32 v145, v153, v145
	v_exp_f32_e32 v157, v157
	v_add_f32_e32 v145, v154, v145
	v_exp_f32_e32 v158, v158
	v_add_f32_e32 v145, v155, v145
	v_exp_f32_e32 v159, v159
	v_add_f32_e32 v145, v156, v145
	v_exp_f32_e32 v161, v64
	v_add_f32_e32 v145, v157, v145
	v_exp_f32_e32 v163, v65
	v_add_f32_e32 v145, v158, v145
	v_exp_f32_e32 v164, v66
	v_add_f32_e32 v145, v159, v145
	v_exp_f32_e32 v165, v67
	v_add_f32_e32 v64, v161, v145
	v_exp_f32_e32 v166, v68
	v_add_f32_e32 v64, v163, v64
	v_exp_f32_e32 v167, v69
	v_add_f32_e32 v64, v164, v64
	v_exp_f32_e32 v168, v70
	v_add_f32_e32 v64, v165, v64
	v_exp_f32_e32 v169, v71
	v_add_f32_e32 v64, v166, v64
	v_exp_f32_e32 v170, v72
	v_add_f32_e32 v64, v167, v64
	v_exp_f32_e32 v171, v73
	v_add_f32_e32 v64, v168, v64
	v_exp_f32_e32 v172, v74
	v_add_f32_e32 v64, v169, v64
	v_exp_f32_e32 v173, v75
	v_add_f32_e32 v64, v170, v64
	v_exp_f32_e32 v174, v76
	v_add_f32_e32 v64, v171, v64
	v_exp_f32_e32 v175, v77
	v_add_f32_e32 v64, v172, v64
	v_exp_f32_e32 v183, v78
	v_add_f32_e32 v64, v173, v64
	v_exp_f32_e32 v79, v79
	v_add_f32_e32 v64, v174, v64
	v_add_f32_e32 v64, v175, v64
	v_add_f32_e32 v64, v183, v64
	v_add_f32_e32 v64, v79, v64
	v_add_f32_e32 v145, v160, v64
	v_cvt_pk_bf16_f32 v64, v144, v162
	v_add3_u32 v144, v181, v182, s6
	v_cvt_pk_bf16_f32 v65, v146, v147
	v_cvt_pk_bf16_f32 v66, v148, v149
	v_cvt_pk_bf16_f32 v67, v150, v151
	v_cvt_pk_bf16_f32 v68, v152, v153
	v_cvt_pk_bf16_f32 v69, v154, v155
	v_cvt_pk_bf16_f32 v70, v156, v157
	v_cvt_pk_bf16_f32 v71, v158, v159
	v_cvt_pk_bf16_f32 v72, v161, v163
	v_cvt_pk_bf16_f32 v73, v164, v165
	v_cvt_pk_bf16_f32 v74, v166, v167
	v_cvt_pk_bf16_f32 v75, v168, v169
	v_cvt_pk_bf16_f32 v76, v170, v171
	v_cvt_pk_bf16_f32 v77, v172, v173
	ds_read_b64_tr_b16 v[146:147], v144 offset:19456
	ds_read_b64_tr_b16 v[148:149], v144 offset:21888
	ds_read_b64_tr_b16 v[150:151], v144 offset:19520
	ds_read_b64_tr_b16 v[152:153], v144 offset:21952
	ds_read_b64_tr_b16 v[154:155], v144 offset:19584
	ds_read_b64_tr_b16 v[156:157], v144 offset:22016
	ds_read_b64_tr_b16 v[158:159], v144 offset:19648
	ds_read_b64_tr_b16 v[160:161], v144 offset:22080
	ds_read_b64_tr_b16 v[162:163], v144 offset:24320
	ds_read_b64_tr_b16 v[164:165], v144 offset:26752
	ds_read_b64_tr_b16 v[166:167], v144 offset:24384
	ds_read_b64_tr_b16 v[168:169], v144 offset:26816
	ds_read_b64_tr_b16 v[170:171], v144 offset:24448
	ds_read_b64_tr_b16 v[172:173], v144 offset:26880
	ds_read_b64_tr_b16 v[208:209], v144 offset:24512
	ds_read_b64_tr_b16 v[210:211], v144 offset:26944
	v_cvt_pk_bf16_f32 v78, v174, v175
	v_cvt_pk_bf16_f32 v79, v183, v79
	s_nop 0
	s_waitcnt lgkmcnt(14)
	v_mfma_f32_32x32x16_bf16 v[128:143], v[146:149], v[64:67], v[128:143]
	s_waitcnt lgkmcnt(12)
	v_mfma_f32_32x32x16_bf16 v[112:127], v[150:153], v[64:67], v[112:127]
	s_waitcnt lgkmcnt(10)
	v_mfma_f32_32x32x16_bf16 v[96:111], v[154:157], v[64:67], v[96:111]
	s_waitcnt lgkmcnt(8)
	v_mfma_f32_32x32x16_bf16 v[80:95], v[158:161], v[64:67], v[80:95]
	s_nop 0
	ds_read_b64_tr_b16 v[64:65], v144 offset:29184
	ds_read_b64_tr_b16 v[146:147], v144 offset:29248
	ds_read_b64_tr_b16 v[150:151], v144 offset:29312
	ds_read_b64_tr_b16 v[154:155], v144 offset:29376
	ds_read_b64_tr_b16 v[66:67], v144 offset:31616
	ds_read_b64_tr_b16 v[148:149], v144 offset:31680
	ds_read_b64_tr_b16 v[152:153], v144 offset:31744
	ds_read_b64_tr_b16 v[156:157], v144 offset:31808
	s_nop 0
	s_waitcnt lgkmcnt(14)
	v_mfma_f32_32x32x16_bf16 v[128:143], v[162:165], v[68:71], v[128:143]
	s_waitcnt lgkmcnt(12)
	v_mfma_f32_32x32x16_bf16 v[112:127], v[166:169], v[68:71], v[112:127]
	s_waitcnt lgkmcnt(10)
	v_mfma_f32_32x32x16_bf16 v[96:111], v[170:173], v[68:71], v[96:111]
	s_waitcnt lgkmcnt(8)
	v_mfma_f32_32x32x16_bf16 v[80:95], v[208:211], v[68:71], v[80:95]
	s_nop 0
	ds_read_b64_tr_b16 v[68:69], v144 offset:34048
	ds_read_b64_tr_b16 v[158:159], v144 offset:34112
	ds_read_b64_tr_b16 v[162:163], v144 offset:34176
	ds_read_b64_tr_b16 v[166:167], v144 offset:34240
	ds_read_b64_tr_b16 v[70:71], v144 offset:36480
	ds_read_b64_tr_b16 v[160:161], v144 offset:36544
	ds_read_b64_tr_b16 v[164:165], v144 offset:36608
	ds_read_b64_tr_b16 v[168:169], v144 offset:36672
	s_nop 0
	s_waitcnt lgkmcnt(11)
	v_mfma_f32_32x32x16_bf16 v[128:143], v[64:67], v[72:75], v[128:143]
	s_waitcnt lgkmcnt(10)
	v_mfma_f32_32x32x16_bf16 v[112:127], v[146:149], v[72:75], v[112:127]
	s_waitcnt lgkmcnt(9)
	v_mfma_f32_32x32x16_bf16 v[96:111], v[150:153], v[72:75], v[96:111]
	s_waitcnt lgkmcnt(8)
	v_mfma_f32_32x32x16_bf16 v[80:95], v[154:157], v[72:75], v[80:95]
	s_nop 0
	s_nop 0
	s_waitcnt lgkmcnt(3)
	v_mfma_f32_32x32x16_bf16 v[128:143], v[68:71], v[76:79], v[128:143]
	s_waitcnt lgkmcnt(2)
	v_mfma_f32_32x32x16_bf16 v[112:127], v[158:161], v[76:79], v[112:127]
	s_waitcnt lgkmcnt(1)
	v_mfma_f32_32x32x16_bf16 v[96:111], v[162:165], v[76:79], v[96:111]
	s_waitcnt lgkmcnt(0)
	v_mfma_f32_32x32x16_bf16 v[80:95], v[166:169], v[76:79], v[80:95]
	s_nop 0
	s_mov_b64 s[10:11], 0

; __device__ __forceinline__ unsigned xb_add(unsigned* p, unsigned v) { return __hip_atomic_fetch_add(p, v, __ATOMIC_RELAXED, __HIP_MEMORY_SCOPE_AGENT); }
; __device__ __forceinline__ void xcd_barrier(const XcdBarrier& b) {
;     asm volatile("s_waitcnt vmcnt(0)" ::: "memory");
;     __syncthreads();
;     if (threadIdx.x == 0) {
;         unsigned* bar = b.bar;
;         __builtin_amdgcn_s_waitcnt(0);
;         unsigned nloc = b.st[0], nx = b.st[1];
;         if (nloc == 0u) { xcd_barrier_complete(bar, b.x, nloc, nx); b.st[0] = nloc; b.st[1] = nx; }
;         const unsigned old = xb_add(&bar[XB_XSUB(b.x)], 1u);
;         const unsigned gen = old / nloc;
.LBB0_890:
	s_setprio 0
	s_getreg_b32 s0, hwreg(HW_REG_XCC_ID, 0, 4)
	s_waitcnt vmcnt(0)
	s_barrier
	s_and_saveexec_b64 s[8:9], s[62:63]
	s_cbranch_execz .LBB0_1065
	v_readlane_b32 s1, v255, 3
	s_waitcnt vmcnt(0) expcnt(0) lgkmcnt(0)
	s_and_b32 s0, s0, 15
	v_mov_b32_e32 v0, s1
	ds_read_b32 v2, v0
	v_readlane_b32 s1, v255, 4
	s_waitcnt lgkmcnt(0)
	v_cmp_ne_u32_e32 vcc, 0, v2
	v_mov_b32_e32 v0, s1
	ds_read_b32 v0, v0
	s_cbranch_vccnz .LBB0_1029
	s_mov_b32 s1, 1
	s_branch .LBB0_1017

; template <int MODE>
; DI void nsa_branch(lds8* lds, const bf16_t* kg, const bf16_t* vg, int pitch, unsigned tiles, const bf16x8 (&q)[4], int qpos, unsigned mybits, int blk,
;                    f32x16 (&O)[2], float& muse, float& l, int tid, int lane, int grp, CmpCap& cap) {
;   const int r = lane & 31, h = lane >> 5;
;   const int sr = tid >> 3, sc = tid & 7;
;   const int koff = r * NS_STR + h * 16;
;   const int voff = 64 * NS_STR + (4 * h + ((lane & 15) >> 2)) * NS_STR + ((lane >> 4) & 1) * 32 + (lane & 3) * 8;
;   volatile LAS int* jl = (volatile LAS int*)(lds + NS_LIST);
;   tiles = __builtin_amdgcn_readfirstlane(tiles);
;   const int ntl = __builtin_popcount(tiles);
;   if (tid < 32) { unsigned below = tiles & ((1u << tid) - 1u); if ((tiles >> tid) & 1u) jl[__builtin_popcount(below)] = tid; }
;   __syncthreads();
; #pragma unroll
;   for (int d = 0; d < 2; ++d)
; #pragma unroll
;     for (int i = 0; i < 16; ++i) O[d][i] = 0.f;
;   muse = 0.f; l = 0.f;
;   u32x4 kra, vra;
; DI void nsa_unit(const Params& p, lds8* lds, int bl, int g, int qb32) {
;   int tid = threadIdx.x; asm volatile("" : "+v"(tid));
;   const int lane = tid & 63, wid = __builtin_amdgcn_readfirstlane(tid >> 6);
;   unsigned char* ws = p.ws;
;   bf16_t* QNS = (bf16_t*)(ws + OFF_QNS); const bf16_t* KSW = (const bf16_t*)(ws + OFF_KSW); const bf16_t* VSW = (const bf16_t*)(ws + OFF_VSW);
;   const bf16_t* KC = (const bf16_t*)(ws + OFF_KC); const bf16_t* VC = (const bf16_t*)(ws + OFF_VC); const bf16_t* GNS = (const bf16_t*)(ws + OFF_GNS);
;   const float* rope = (const float*)(ws + OFF_ROPE);
;   const int r = lane & 31, h = lane >> 5; const int hh = g * 8 + wid;
;   const size_t rowbase = (size_t)bl * SEQ; const int q0 = qb32 * 32, qpos = q0 + r, blk = q0 >> 6;
;   bf16x8 qraw[4], qrot[4];
;   { const bf16_t* qp = QNS + (rowbase + qpos) * DM + hh * 64 + 8 * h;
; #pragma unroll
;     for (int ks = 0; ks < 4; ++ks) qraw[ks] = *(const bf16x8*)(qp + 16 * ks); }
;   const bf16_t* gp = GNS + (rowbase + qpos) * 64 + hh * 3;
;   const float g0 = bf2f(gp[0]), g1 = bf2f(gp[1]), g2 = bf2f(gp[2]);
;   f32x16 OT[2], O[2]; float m, l; const int grp = ((wid >> 2) ^ wid) & 1;
;   const bf16_t* kc = KC + (size_t)(bl * 2 + g) * 128 * 64; const bf16_t* vc = VC + (size_t)(bl * 2 + g) * 128 * 64;
;   CmpCap cap;
;   nsa_branch<0>(lds, kc, vc, 64, 3u, qraw, qpos, 0u, blk, O, m, l, tid, lane, grp, cap);
.LBB0_898:
	v_writelane_b32 v255, s88, 37
	s_movk_i32 s94, 0x84
	s_nop 0
	v_writelane_b32 v255, s89, 38
	s_or_b64 exec, exec, s[8:9]
	s_ashr_i32 s1, s0, 5
	v_mov_b32_e32 v136, v200
	s_sub_i32 s3, 63, s1
	s_bfe_u32 s71, s0, 0x40001
	s_and_b32 s70, s0, 1
	s_lshl_b32 s2, s3, 5
	v_readfirstlane_b32 s0, v136
	s_ashr_i32 s1, s0, 6
	s_setprio 0
	s_cmp_ge_u32 s1, 4
	s_cbranch_scc0 .Lnsa_prio_lo
	s_setprio 1
.Lnsa_prio_lo:
	v_and_b32_e32 v52, 31, v136
	s_lshl_b32 s0, s70, 3
	v_writelane_b32 v255, s1, 39
	s_add_i32 s0, s1, s0
	s_lshl_b32 s1, s71, 11
	v_or_b32_e32 v211, s2, v52
	v_add_u32_e32 v186, s1, v211
	v_readlane_b32 s8, v254, 51
	v_lshlrev_b64 v[0:1], 11, v[186:187]
	v_readlane_b32 s9, v254, 52
	s_lshl_b32 s96, s0, 6
	v_bfe_u32 v55, v136, 5, 1
	v_lshl_add_u64 v[0:1], s[8:9], 0, v[0:1]
	s_ashr_i32 s97, s96, 31
	v_lshl_add_u64 v[0:1], s[96:97], 1, v[0:1]
	v_lshlrev_b32_e32 v2, 4, v55
	v_mov_b32_e32 v3, v187
	v_lshl_add_u64 v[0:1], v[0:1], 0, v[2:3]
	v_readlane_b32 s8, v254, 57
	global_load_dwordx4 v[44:47], v[0:1], off
	global_load_dwordx4 v[36:39], v[0:1], off offset:32
	global_load_dwordx4 v[40:43], v[0:1], off offset:64
	global_load_dwordx4 v[32:35], v[0:1], off offset:96
	v_lshlrev_b64 v[0:1], 7, v[186:187]
	v_readlane_b32 s9, v254, 58
	v_writelane_b32 v255, s2, 40
	v_writelane_b32 v255, s1, 41
	v_lshl_add_u64 v[0:1], s[8:9], 0, v[0:1]
	s_mul_i32 s8, s0, 3
	s_ashr_i32 s9, s8, 31
	v_lshl_add_u64 v[0:1], s[8:9], 1, v[0:1]
	global_load_dword v209, v[0:1], off
	global_load_ushort v210, v[0:1], off offset:4
	v_cmp_gt_u32_e32 vcc, 2, v136
	s_and_saveexec_b64 s[8:9], vcc
	v_lshl_add_u32 v0, v136, 2, 0
	v_add_u32_e32 v0, 0x16d10, v0
	ds_write_b32 v0, v136
	s_or_b64 exec, exec, s[8:9]
	s_lshl_b32 s0, s70, 14
	s_lshl_b32 s6, s71, 15
	s_or_b32 s0, s6, s0
	v_readlane_b32 s1, v254, 55
	s_add_u32 s10, s1, s0
	v_readlane_b32 s1, v254, 56
	s_addc_u32 s11, s1, 0
	v_readlane_b32 s1, v254, 61
	v_and_b32_e32 v199, 63, v136
	s_add_u32 s8, s1, s0
	v_readlane_b32 s0, v254, 62
	s_addc_u32 s9, s0, 0
	v_lshlrev_b32_e32 v214, 2, v55
	v_lshrrev_b32_e32 v0, 2, v136
	v_lshlrev_b32_e32 v1, 3, v199
	s_add_i32 s0, 0, 0x16d10
	v_and_or_b32 v51, v0, 3, v214
	v_lshlrev_b32_e32 v0, 1, v199
	v_and_b32_e32 v1, 24, v1
	v_mov_b32_e32 v48, s0
	v_and_or_b32 v66, v0, 32, v1
	s_waitcnt lgkmcnt(0)
	s_barrier
	v_readlane_b32 s2, v255, 9
	ds_read_b32 v0, v48
	v_ashrrev_i32_e32 v212, 3, v136
	v_and_b32_e32 v54, 7, v136
	v_mov_b32_e32 v50, s2
	ds_read_b32 v9, v50
	v_lshlrev_b32_e32 v192, 4, v54
	v_mov_b32_e32 v193, v187
	s_movk_i32 s1, 0x90
	v_mul_lo_u32 v8, v212, s1
	v_mul_u32_u24_e32 v208, 0x90, v52
	v_lshl_add_u32 v213, v55, 4, v208
	s_waitcnt lgkmcnt(0)
	v_readfirstlane_b32 s6, v0
	v_readfirstlane_b32 s77, v9
	v_add3_u32 v215, 0, v8, v192
	s_nop 0
	v_lshl_add_u32 v0, s6, 6, v212
	s_nop 0
	v_lshl_add_u32 v10, s77, 6, v212
	v_ashrrev_i32_e32 v1, 31, v0
	v_ashrrev_i32_e32 v11, 31, v10
	v_lshlrev_b64 v[4:5], 7, v[0:1]
	v_lshlrev_b64 v[12:13], 7, v[10:11]
	v_lshl_add_u64 v[0:1], s[10:11], 0, v[4:5]
	v_lshl_add_u64 v[0:1], v[0:1], 0, v[192:193]
	v_lshl_add_u64 v[4:5], s[8:9], 0, v[4:5]
	global_load_dwordx4 v[0:3], v[0:1], off
	v_lshl_add_u64 v[4:5], v[4:5], 0, v[192:193]
	global_load_dwordx4 v[4:7], v[4:5], off
	v_lshl_add_u64 v[8:9], s[10:11], 0, v[12:13]
	v_lshl_add_u64 v[8:9], v[8:9], 0, v[192:193]
	v_lshl_add_u64 v[12:13], s[8:9], 0, v[12:13]
	global_load_dwordx4 v[8:11], v[8:9], off
	v_lshl_add_u64 v[12:13], v[12:13], 0, v[192:193]
	global_load_dwordx4 v[12:15], v[12:13], off
	s_waitcnt vmcnt(3)
	ds_write_b128 v215, v[0:3]
	s_waitcnt vmcnt(2)
	ds_write_b128 v215, v[4:7] offset:9216
	s_waitcnt vmcnt(1)
	ds_write_b128 v215, v[8:11] offset:18432
	s_waitcnt vmcnt(0)
	ds_write_b128 v215, v[12:15] offset:27648
	v_subrev_u32_e32 v0, 31, v211
	v_and_b32_e32 v1, 64, v202
	v_ashrrev_i32_e32 v121, 4, v0
	v_xor_b32_e32 v0, 32, v202
	v_add_u32_e32 v53, 64, v1
	v_cmp_lt_i32_e32 vcc, v0, v53
	s_waitcnt lgkmcnt(0)
	s_barrier
	v_cndmask_b32_e32 v0, v202, v0, vcc
	v_lshlrev_b32_e32 v193, 2, v0
	v_add_u32_e32 v134, 0, v213
	ds_read_b128 v[56:59], v134
	ds_read_b128 v[60:63], v134 offset:32
	ds_read_b128 v[68:71], v134 offset:4608
	ds_read_b128 v[72:75], v134 offset:4640
	ds_read_b128 v[76:79], v134 offset:64
	ds_read_b128 v[80:83], v134 offset:96
	ds_read_b128 v[84:87], v134 offset:4672
	ds_read_b128 v[88:91], v134 offset:4704
	s_nop 0
	s_mov_b32 s77, s76
	s_mov_b32 s78, s76
	s_mov_b32 s79, s76
	s_mov_b32 s80, s76
	s_mov_b32 s81, s76
	s_mov_b32 s82, s76
	s_mov_b32 s83, s76
	s_mov_b32 s84, s76
	s_mov_b32 s85, s76
	s_mov_b32 s86, s76
	s_mov_b32 s87, s76
	s_mov_b32 s88, s76
	s_mov_b32 s89, s76
	s_mov_b32 s90, s76
	s_mov_b32 s91, s76
	v_mov_b64_e32 v[0:1], s[76:77]
	v_mov_b64_e32 v[2:3], s[78:79]
	v_mov_b64_e32 v[4:5], s[80:81]
	v_mov_b64_e32 v[6:7], s[82:83]
	v_mov_b64_e32 v[8:9], s[84:85]
	v_mov_b64_e32 v[10:11], s[86:87]
	v_mov_b64_e32 v[12:13], s[88:89]
	v_mov_b64_e32 v[14:15], s[90:91]
	s_waitcnt lgkmcnt(7)
	s_nop 0
	v_mfma_f32_32x32x16_bf16 v[16:31], v[56:59], v[44:47], v[0:15]
	s_waitcnt lgkmcnt(5)
	v_mfma_f32_32x32x16_bf16 v[0:15], v[68:71], v[44:47], v[0:15]
	v_mfma_f32_32x32x16_bf16 v[16:31], v[60:63], v[36:39], v[16:31]
	s_waitcnt lgkmcnt(4)
	v_mfma_f32_32x32x16_bf16 v[0:15], v[72:75], v[36:39], v[0:15]
	s_waitcnt lgkmcnt(3)
	v_mfma_f32_32x32x16_bf16 v[16:31], v[76:79], v[40:43], v[16:31]
	s_waitcnt lgkmcnt(1)
	v_mfma_f32_32x32x16_bf16 v[0:15], v[84:87], v[40:43], v[0:15]
	v_mfma_f32_32x32x16_bf16 v[16:31], v[80:83], v[32:35], v[16:31]
	s_waitcnt lgkmcnt(0)
	v_mfma_f32_32x32x16_bf16 v[0:15], v[88:91], v[32:35], v[0:15]
	s_nop 0
	ds_read_b32 v48, v48
	s_mov_b32 s85, 0xefa18f08
	v_mad_u32_u24 v216, v51, s1, v66
	v_add_u32_e32 v96, 0, v216
	s_waitcnt lgkmcnt(0)
; #define LAS __attribute__((address_space(3)))
; DI float rowmax32(const f32x16& s0, const f32x16& s1) {
;   float a = fmaxf(fmaxf(s0[0], s0[1]), s1[0]), b = fmaxf(fmaxf(s0[2], s0[3]), s1[1]); a = fmaxf(fmaxf(a, s1[2]), s1[3]);
; #pragma unroll
;   for (int r = 4; r < 16; r += 4) { a = fmaxf(fmaxf(a, s0[r]), s0[r + 1]); b = fmaxf(fmaxf(b, s0[r + 2]), s0[r + 3]); a = fmaxf(fmaxf(a, s1[r]), s1[r + 1]); b = fmaxf(fmaxf(b, s1[r + 2]), s1[r + 3]); }
;   const float m = fmaxf(a, b);
;   return fmaxf(m, __shfl_xor(m, 32));
; }
; template <int MODE, int SLOT> DI void ns_valu(volatile LAS int* jl, int t, int ntl, int qpos, int h, int blk, f32x16& s0, f32x16& s1, f32x16& du0, f32x16& du1, f32x16 (&O)[2], float& muse, float& l, bf16x8 (&P)[4], CmpCap& cap) {
;     if (t < ntl) {
;       const int j = __builtin_amdgcn_readfirstlane(jl[t]);
;       if (MODE == 0) {
;         const int lim = ((qpos - 31) >> 4) - 64 * j - 4 * h;
; #pragma unroll
;         for (int i = 0; i < 16; ++i) { const int ci = (i & 3) + 8 * (i >> 2); if (ci > lim) s0[i] = NEG; if (ci + 32 > lim) s1[i] = NEG; }
	v_readfirstlane_b32 s6, v48
	s_nop 1
	v_lshl_or_b32 v48, s6, 6, v214
	v_sub_u32_e32 v48, v121, v48
	v_cmp_gt_i32_e64 s[64:65], 26, v48
	v_cmp_gt_i32_e64 s[68:69], 27, v48
	v_cmp_gt_i32_e64 s[60:61], 25, v48
	s_and_b64 s[64:65], s[68:69], s[64:65]
	v_cmp_gt_i32_e64 s[56:57], 24, v48
	s_and_b64 s[60:61], s[64:65], s[60:61]
	v_cmp_gt_i32_e64 s[52:53], 19, v48
	s_and_b64 s[56:57], s[60:61], s[56:57]
	v_cmp_gt_i32_e64 s[48:49], 18, v48
	s_and_b64 s[52:53], s[56:57], s[52:53]
	v_cmp_gt_i32_e64 s[44:45], 17, v48
	s_and_b64 s[48:49], s[52:53], s[48:49]
	v_cmp_gt_i32_e64 s[40:41], 16, v48
	s_and_b64 s[44:45], s[48:49], s[44:45]
	v_cmp_gt_i32_e64 s[36:37], 11, v48
	s_and_b64 s[40:41], s[44:45], s[40:41]
	v_cmp_gt_i32_e64 s[30:31], 10, v48
	s_and_b64 s[36:37], s[40:41], s[36:37]
	v_cmp_gt_i32_e64 s[26:27], 9, v48
	s_and_b64 s[30:31], s[36:37], s[30:31]
	v_cmp_gt_i32_e64 s[22:23], 8, v48
	s_and_b64 s[26:27], s[30:31], s[26:27]
	v_cmp_gt_i32_e64 s[20:21], 3, v48
	s_and_b64 s[22:23], s[26:27], s[22:23]
	v_cmp_gt_i32_e64 s[18:19], 2, v48
	s_and_b64 s[20:21], s[22:23], s[20:21]
	v_cmp_gt_i32_e64 s[16:17], 1, v48
	s_and_b64 s[18:19], s[20:21], s[18:19]
	v_cmp_gt_i32_e64 s[14:15], 0, v48
	s_and_b64 s[16:17], s[18:19], s[16:17]
	s_and_b64 s[14:15], s[16:17], s[14:15]
	v_cmp_gt_i32_e64 s[66:67], 58, v48
	v_cndmask_b32_e64 v16, v16, v207, s[14:15]
	v_cmp_gt_i32_e64 s[14:15], 59, v48
	v_cmp_gt_i32_e64 s[62:63], 57, v48
	v_cmp_gt_i32_e64 s[58:59], 56, v48
	v_cndmask_b32_e64 v15, v15, v207, s[14:15]
	s_and_b64 s[14:15], s[14:15], s[66:67]
	v_cndmask_b32_e64 v14, v14, v207, s[14:15]
	s_and_b64 s[14:15], s[14:15], s[62:63]
	v_cmp_gt_i32_e64 s[54:55], 51, v48
	v_cndmask_b32_e64 v13, v13, v207, s[14:15]
	s_and_b64 s[14:15], s[14:15], s[58:59]
	v_cmp_gt_i32_e64 s[50:51], 50, v48
	v_cndmask_b32_e64 v12, v12, v207, s[14:15]
	s_and_b64 s[14:15], s[14:15], s[54:55]
	v_cmp_gt_i32_e64 s[46:47], 49, v48
	v_cndmask_b32_e64 v11, v11, v207, s[14:15]
	s_and_b64 s[14:15], s[14:15], s[50:51]
	v_cmp_gt_i32_e64 s[42:43], 48, v48
	v_cndmask_b32_e64 v10, v10, v207, s[14:15]
	s_and_b64 s[14:15], s[14:15], s[46:47]
	v_cmp_gt_i32_e64 s[38:39], 43, v48
	v_cndmask_b32_e64 v9, v9, v207, s[14:15]
	s_and_b64 s[14:15], s[14:15], s[42:43]
	v_cmp_gt_i32_e64 s[34:35], 42, v48
	v_cndmask_b32_e64 v8, v8, v207, s[14:15]
	s_and_b64 s[14:15], s[14:15], s[38:39]
	v_cmp_gt_i32_e64 s[28:29], 41, v48
	v_cndmask_b32_e64 v7, v7, v207, s[14:15]
	s_and_b64 s[14:15], s[14:15], s[34:35]
	v_cmp_gt_i32_e64 s[24:25], 40, v48
	v_cndmask_b32_e64 v6, v6, v207, s[14:15]
	s_and_b64 s[14:15], s[14:15], s[28:29]
	v_cmp_gt_i32_e64 s[12:13], 35, v48
	v_cndmask_b32_e64 v5, v5, v207, s[14:15]
	s_and_b64 s[14:15], s[14:15], s[24:25]
	v_cmp_gt_i32_e64 s[10:11], 34, v48
	s_and_b64 s[12:13], s[14:15], s[12:13]
	v_cmp_gt_i32_e64 s[8:9], 33, v48
	s_and_b64 s[10:11], s[12:13], s[10:11]
	v_cmp_gt_i32_e32 vcc, 32, v48
	v_cndmask_b32_e64 v17, v17, v207, s[16:17]
	s_and_b64 s[8:9], s[10:11], s[8:9]
	s_and_b64 vcc, s[8:9], vcc
	v_max_f32_e32 v48, v17, v17
	v_max_f32_e32 v49, v16, v16
	v_cndmask_b32_e64 v19, v19, v207, s[20:21]
	v_cndmask_b32_e64 v18, v18, v207, s[18:19]
	v_cndmask_b32_e64 v2, v2, v207, s[10:11]
	v_cndmask_b32_e64 v1, v1, v207, s[8:9]
	v_cndmask_b32_e32 v0, v0, v207, vcc
	v_max_f32_e32 v48, v49, v48
	v_cndmask_b32_e64 v23, v23, v207, s[36:37]
	v_cndmask_b32_e64 v22, v22, v207, s[30:31]
	v_cndmask_b32_e64 v20, v20, v207, s[22:23]
	v_cndmask_b32_e64 v3, v3, v207, s[12:13]
	v_max3_f32 v49, v18, v19, v1
	v_max3_f32 v48, v48, v0, v2
	v_cndmask_b32_e64 v21, v21, v207, s[26:27]
	v_cndmask_b32_e64 v4, v4, v207, s[14:15]
	v_max3_f32 v48, v48, v3, v20
	v_max3_f32 v49, v49, v22, v23
	v_cndmask_b32_e64 v27, v27, v207, s[52:53]
	v_cndmask_b32_e64 v26, v26, v207, s[48:49]
	v_cndmask_b32_e64 v24, v24, v207, s[40:41]
	v_max3_f32 v48, v48, v21, v4
	v_max3_f32 v49, v49, v6, v7
	v_cndmask_b32_e64 v25, v25, v207, s[44:45]
	v_max3_f32 v48, v48, v5, v24
	v_max3_f32 v49, v49, v26, v27
	v_cndmask_b32_e64 v31, v31, v207, s[68:69]
	v_cndmask_b32_e64 v30, v30, v207, s[64:65]
	v_cndmask_b32_e64 v28, v28, v207, s[56:57]
	v_max3_f32 v48, v48, v25, v8
	v_max3_f32 v49, v49, v10, v11
	v_cndmask_b32_e64 v29, v29, v207, s[60:61]
	v_max3_f32 v48, v48, v9, v28
	v_max3_f32 v49, v49, v30, v31
	v_max3_f32 v48, v48, v29, v12
	v_max3_f32 v49, v49, v14, v15
	v_max3_f32 v48, v48, v13, v49
	ds_bpermute_b32 v49, v193, v48
	s_waitcnt lgkmcnt(0)
; template <int VSTR, int NDVB> DI void pv64(f32x16 (&O)[NDVB], const lds8* vp, const bf16x8 (&P)[4]) {
;   bf16x8 f[2][NDVB];
; #pragma unroll
;   for (int d = 0; d < NDVB; ++d) { const s16x4 lo = trrd(vp + d * 64), hi = trrd(vp + 8 * VSTR + d * 64); f[0][d] = __builtin_shufflevector(lo, hi, 0, 1, 2, 3, 4, 5, 6, 7); }
; #pragma unroll
;   for (int kk = 0; kk < 4; ++kk) {
;     if (kk < 3) {
; #pragma unroll
;       for (int d = 0; d < NDVB; ++d) { const s16x4 lo = trrd(vp + (16 * (kk + 1)) * VSTR + d * 64), hi = trrd(vp + (16 * (kk + 1) + 8) * VSTR + d * 64);
;         f[(kk + 1) & 1][d] = __builtin_shufflevector(lo, hi, 0, 1, 2, 3, 4, 5, 6, 7); }
;     }
;     SBAR();
; template <int NDVB, bool HAS_NEXT> DI void softmax_def(f32x16& sa0, f32x16& sa1, f32x16& sb0, f32x16& sb1, f32x16 (&O)[NDVB], float& muse, float& l, bool first, bf16x8 (&P)[4], bool check = true) {
;   float mx = 0.f;
;   if (check) mx = rowmax32(sa0, sa1);
;   if (check && (first || __any(mx > 8.f))) {
;     float dl = first ? mx : fmaxf(mx, 0.f);
;     if (mx < -1e29f) dl = 0.f;
;     const float alpha = __builtin_amdgcn_exp2f(-dl);
;     muse += dl; l *= alpha;
; #pragma unroll
;     for (int i = 0; i < 16; ++i) { sa0[i] -= dl; sa1[i] -= dl; }
;     if (HAS_NEXT) {
; #pragma unroll
;       for (int i = 0; i < 16; ++i) { sb0[i] -= dl; sb1[i] -= dl; }
;     }
; #pragma unroll
;     for (int d = 0; d < NDVB; ++d)
; #pragma unroll
;       for (int i = 0; i < 16; ++i) O[d][i] *= alpha;
;   }
;   float sum = 0.f;
; #pragma unroll
;   for (int i = 0; i < 16; ++i) { sa0[i] = __builtin_amdgcn_exp2f(sa0[i]); sum += sa0[i]; }
; #pragma unroll
;   for (int i = 0; i < 16; ++i) { sa1[i] = __builtin_amdgcn_exp2f(sa1[i]); sum += sa1[i]; }
;   l += sum;
;   u32x4 w;
;   w.x = cvtpk(sa0[0], sa0[1]); w.y = cvtpk(sa0[2], sa0[3]); w.z = cvtpk(sa0[4], sa0[5]); w.w = cvtpk(sa0[6], sa0[7]); P[0] = __builtin_bit_cast(bf16x8, w);
;   w.x = cvtpk(sa0[8], sa0[9]); w.y = cvtpk(sa0[10], sa0[11]); w.z = cvtpk(sa0[12], sa0[13]); w.w = cvtpk(sa0[14], sa0[15]); P[1] = __builtin_bit_cast(bf16x8, w);
;   w.x = cvtpk(sa1[0], sa1[1]); w.y = cvtpk(sa1[2], sa1[3]); w.z = cvtpk(sa1[4], sa1[5]); w.w = cvtpk(sa1[6], sa1[7]); P[2] = __builtin_bit_cast(bf16x8, w);
;   w.x = cvtpk(sa1[8], sa1[9]); w.y = cvtpk(sa1[10], sa1[11]); w.z = cvtpk(sa1[12], sa1[13]); w.w = cvtpk(sa1[14], sa1[15]); P[3] = __builtin_bit_cast(bf16x8, w);
; }
	v_max_f32_e32 v49, v49, v49
	v_max_f32_e32 v48, v48, v49
	v_cmp_ngt_f32_e32 vcc, s85, v48
	s_nop 1
	v_cndmask_b32_e32 v65, 0, v48, vcc
	v_sub_f32_e32 v16, v16, v65
	v_sub_f32_e32 v17, v17, v65
	v_exp_f32_e32 v97, v16
	v_sub_f32_e32 v18, v18, v65
	v_exp_f32_e32 v98, v17
	v_sub_f32_e32 v19, v19, v65
	v_exp_f32_e32 v99, v18
	v_sub_f32_e32 v20, v20, v65
	v_exp_f32_e32 v56, v19
	v_sub_f32_e32 v21, v21, v65
	v_add_f32_e32 v16, 0, v97
	v_exp_f32_e32 v100, v20
	v_sub_f32_e32 v22, v22, v65
	v_add_f32_e32 v16, v98, v16
	v_exp_f32_e32 v101, v21
	v_sub_f32_e32 v23, v23, v65
	v_add_f32_e32 v16, v99, v16
	v_exp_f32_e32 v102, v22
	v_sub_f32_e32 v24, v24, v65
	v_add_f32_e32 v16, v56, v16
	v_exp_f32_e32 v57, v23
	v_sub_f32_e32 v25, v25, v65
	v_add_f32_e32 v16, v100, v16
	v_exp_f32_e32 v103, v24
	v_sub_f32_e32 v26, v26, v65
	v_add_f32_e32 v16, v101, v16
	v_exp_f32_e32 v104, v25
	v_sub_f32_e32 v27, v27, v65
	v_add_f32_e32 v16, v102, v16
	v_exp_f32_e32 v105, v26
	v_sub_f32_e32 v28, v28, v65
	v_add_f32_e32 v16, v57, v16
	v_exp_f32_e32 v58, v27
	v_sub_f32_e32 v29, v29, v65
	v_add_f32_e32 v16, v103, v16
	v_exp_f32_e32 v106, v28
	v_sub_f32_e32 v30, v30, v65
	v_add_f32_e32 v16, v104, v16
	v_exp_f32_e32 v107, v29
	v_sub_f32_e32 v31, v31, v65
	v_add_f32_e32 v16, v105, v16
	v_exp_f32_e32 v108, v30
	v_sub_f32_e32 v0, v0, v65
	v_add_f32_e32 v16, v58, v16
	v_exp_f32_e32 v59, v31
	v_sub_f32_e32 v1, v1, v65
	v_add_f32_e32 v16, v106, v16
	v_exp_f32_e32 v109, v0
	v_sub_f32_e32 v2, v2, v65
	v_add_f32_e32 v16, v107, v16
	v_exp_f32_e32 v110, v1
	v_sub_f32_e32 v3, v3, v65
	v_add_f32_e32 v16, v108, v16
	v_exp_f32_e32 v111, v2
	v_sub_f32_e32 v4, v4, v65
	v_add_f32_e32 v16, v59, v16
	v_exp_f32_e32 v60, v3
	v_sub_f32_e32 v5, v5, v65
	v_add_f32_e32 v0, v109, v16
	v_exp_f32_e32 v112, v4
	v_sub_f32_e32 v6, v6, v65
	v_add_f32_e32 v0, v110, v0
	v_exp_f32_e32 v113, v5
	v_sub_f32_e32 v7, v7, v65
	v_add_f32_e32 v0, v111, v0
	v_exp_f32_e32 v114, v6
	v_sub_f32_e32 v8, v8, v65
	v_add_f32_e32 v0, v60, v0
	v_exp_f32_e32 v61, v7
	v_sub_f32_e32 v9, v9, v65
	v_add_f32_e32 v0, v112, v0
	v_exp_f32_e32 v115, v8
	v_sub_f32_e32 v10, v10, v65
	v_sub_f32_e32 v12, v12, v65
	v_sub_f32_e32 v13, v13, v65
	v_sub_f32_e32 v14, v14, v65
	v_sub_f32_e32 v15, v15, v65
	v_add_f32_e32 v0, v113, v0
	v_exp_f32_e32 v116, v9
	v_sub_f32_e32 v11, v11, v65
	v_add_f32_e32 v0, v114, v0
	v_exp_f32_e32 v117, v10
	v_exp_f32_e32 v118, v12
	v_exp_f32_e32 v119, v13
	v_exp_f32_e32 v120, v14
	v_exp_f32_e32 v63, v15
	ds_read_b64_tr_b16 v[12:13], v96 offset:9216
	ds_read_b64_tr_b16 v[14:15], v96 offset:10368
	ds_read_b64_tr_b16 v[18:19], v96 offset:10432
	ds_read_b64_tr_b16 v[16:17], v96 offset:9280
	ds_read_b64_tr_b16 v[20:21], v96 offset:11520
	ds_read_b64_tr_b16 v[22:23], v96 offset:12672
	ds_read_b64_tr_b16 v[26:27], v96 offset:12736
	ds_read_b64_tr_b16 v[24:25], v96 offset:11584
	v_add_f32_e32 v0, v61, v0
	v_exp_f32_e32 v62, v11
	v_add_f32_e32 v0, v115, v0
	v_add_f32_e32 v0, v116, v0
	v_add_f32_e32 v0, v117, v0
	v_exp_f32_e64 v48, -v65
	v_add_f32_e32 v0, v62, v0
	v_add_f32_e32 v0, v118, v0
	v_add_f32_e32 v0, v119, v0
	v_add_f32_e32 v0, v120, v0
	v_mul_f32_e32 v64, 0, v48
	v_add_f32_e32 v186, v63, v0
	v_pk_add_f32 v[48:49], v[64:65], v[186:187]
	v_cvt_pk_bf16_f32 v0, v97, v98
	v_cvt_pk_bf16_f32 v2, v100, v101
	v_cvt_pk_bf16_f32 v3, v102, v57
	v_cvt_pk_bf16_f32 v4, v103, v104
	v_cvt_pk_bf16_f32 v5, v105, v58
	v_cvt_pk_bf16_f32 v6, v106, v107
	v_cvt_pk_bf16_f32 v7, v108, v59
	v_cvt_pk_bf16_f32 v8, v109, v110
	v_cvt_pk_bf16_f32 v9, v111, v60
	v_cvt_pk_bf16_f32 v10, v112, v113
	v_cvt_pk_bf16_f32 v11, v114, v61
	v_cvt_pk_bf16_f32 v28, v115, v116
	v_cvt_pk_bf16_f32 v29, v117, v62
	v_cvt_pk_bf16_f32 v30, v118, v119
	v_cvt_pk_bf16_f32 v31, v120, v63
	v_cvt_pk_bf16_f32 v1, v99, v56
	s_nop 0
	v_mov_b32_e32 v65, v64
	v_mov_b32_e32 v66, v64
	v_mov_b32_e32 v67, v64
	v_mov_b32_e32 v68, v64
	v_mov_b32_e32 v69, v64
	v_mov_b32_e32 v70, v64
	v_mov_b32_e32 v71, v64
	v_mov_b32_e32 v72, v64
	v_mov_b32_e32 v73, v64
	v_mov_b32_e32 v74, v64
	v_mov_b32_e32 v75, v64
	v_mov_b32_e32 v76, v64
	v_mov_b32_e32 v77, v64
	v_mov_b32_e32 v78, v64
	v_mov_b32_e32 v79, v64
	s_waitcnt lgkmcnt(6)
	s_nop 0
	v_mfma_f32_32x32x16_bf16 v[80:95], v[12:15], v[0:3], v[64:79]
	s_waitcnt lgkmcnt(4)
	v_mfma_f32_32x32x16_bf16 v[64:79], v[16:19], v[0:3], v[64:79]
	s_nop 0
	ds_read_b64_tr_b16 v[0:1], v96 offset:13824
	ds_read_b64_tr_b16 v[2:3], v96 offset:14976
	ds_read_b64_tr_b16 v[14:15], v96 offset:15040
	ds_read_b64_tr_b16 v[12:13], v96 offset:13888
	s_nop 0
	s_waitcnt lgkmcnt(6)
	v_mfma_f32_32x32x16_bf16 v[80:95], v[20:23], v[4:7], v[80:95]
	s_waitcnt lgkmcnt(4)
	v_mfma_f32_32x32x16_bf16 v[64:79], v[24:27], v[4:7], v[64:79]
	s_nop 0
	ds_read_b64_tr_b16 v[4:5], v96 offset:16128
	ds_read_b64_tr_b16 v[6:7], v96 offset:17280
	ds_read_b64_tr_b16 v[18:19], v96 offset:17344
	ds_read_b64_tr_b16 v[16:17], v96 offset:16192
	s_nop 0
	s_waitcnt lgkmcnt(6)
	v_mfma_f32_32x32x16_bf16 v[80:95], v[0:3], v[8:11], v[80:95]
	s_waitcnt lgkmcnt(4)
	v_mfma_f32_32x32x16_bf16 v[64:79], v[12:15], v[8:11], v[64:79]
	s_nop 0
	s_nop 0
	s_waitcnt lgkmcnt(2)
	v_mfma_f32_32x32x16_bf16 v[80:95], v[4:7], v[28:31], v[80:95]
	s_waitcnt lgkmcnt(0)
	v_mfma_f32_32x32x16_bf16 v[64:79], v[16:19], v[28:31], v[64:79]
	s_nop 0
	s_barrier
; #define LAS __attribute__((address_space(3)))
; #define MFMA32(a, b, c) __builtin_amdgcn_mfma_f32_32x32x16_bf16((a), (b), (c), 0, 0, 0)
; #define SBAR() __builtin_amdgcn_sched_barrier(0)
; template <int KSTR> DI void qk64b(f32x16& s0, f32x16& s1, const lds8* kp, const bf16x8 (&q)[4], float bias) {
;   bf16x8 a[8];
; #pragma unroll
;   for (int ks = 0; ks < 4; ++ks) { a[2 * ks] = *(const LAS bf16x8*)(kp + ks * 32); a[2 * ks + 1] = *(const LAS bf16x8*)(kp + 32 * KSTR + ks * 32); }
; #pragma unroll
;   for (int i = 0; i < 16; ++i) { s0[i] = bias; s1[i] = bias; }
;   SBAR();
;   __builtin_amdgcn_s_setprio(1);
; #pragma unroll
;   for (int ks = 0; ks < 4; ++ks) { s0 = MFMA32(a[2 * ks], q[ks], s0); s1 = MFMA32(a[2 * ks + 1], q[ks], s1); }
;   __builtin_amdgcn_s_setprio(0);
;   SBAR();
; }
; template <int MODE, int SLOT> DI void ns_valu(volatile LAS int* jl, int t, int ntl, int qpos, int h, int blk, f32x16& s0, f32x16& s1, f32x16& du0, f32x16& du1, f32x16 (&O)[2], float& muse, float& l, bf16x8 (&P)[4], CmpCap& cap) {
;     if (t < ntl) {
;       const int j = __builtin_amdgcn_readfirstlane(jl[t]);
;       if (MODE == 0) {
;         const int lim = ((qpos - 31) >> 4) - 64 * j - 4 * h;
; #pragma unroll
;         for (int i = 0; i < 16; ++i) { const int ci = (i & 3) + 8 * (i >> 2); if (ci > lim) s0[i] = NEG; if (ci + 32 > lim) s1[i] = NEG; }
;       } else if (MODE == 1) {
;         if (j == blk) {
;           const int lim = qpos - 64 * j - 4 * h;
; #pragma unroll
;           for (int i = 0; i < 16; ++i) { const int ci = (i & 3) + 8 * (i >> 2); if (ci > lim) s0[i] = NEG; if (ci + 32 > lim) s1[i] = NEG; }
;         }
;       } else {
;         if (j == blk || j + 8 == blk) {
;           const int lim = qpos - 64 * j - 4 * h, lo = lim - 512;
; #pragma unroll
;           for (int i = 0; i < 16; ++i) { const int ci = (i & 3) + 8 * (i >> 2); if (ci > lim || ci <= lo) s0[i] = NEG; if (ci + 32 > lim || ci + 32 <= lo) s1[i] = NEG; }
;         }
;       }
;       softmax_def<2, false>(s0, s1, du0, du1, O, muse, l, t == 0, P);
	ds_read_b128 v[122:125], v134 offset:18432
	ds_read_b128 v[126:129], v134 offset:18464
	ds_read_b128 v[130:133], v134 offset:23040
	ds_read_b128 v[138:141], v134 offset:23072
	ds_read_b128 v[142:145], v134 offset:18496
	ds_read_b128 v[146:149], v134 offset:18528
	ds_read_b128 v[150:153], v134 offset:23104
	ds_read_b128 v[154:157], v134 offset:23136
	v_xor_b32_e32 v0, 0x80000000, v49
	v_mov_b32_e32 v2, v0
	v_mov_b32_e32 v3, v0
	v_mov_b32_e32 v4, v0
	v_mov_b32_e32 v5, v0
	v_mov_b32_e32 v6, v0
	v_mov_b32_e32 v7, v0
	v_mov_b32_e32 v8, v0
	v_mov_b32_e32 v9, v0
	v_mov_b32_e32 v10, v0
	v_mov_b32_e32 v11, v0
	v_mov_b32_e32 v12, v0
	v_mov_b32_e32 v13, v0
	v_mov_b32_e32 v14, v0
	v_mov_b32_e32 v15, v0
	v_mov_b32_e32 v1, v0
	s_nop 0
	s_waitcnt lgkmcnt(7)
	v_mfma_f32_32x32x16_bf16 v[16:31], v[122:125], v[44:47], v[0:15]
	s_waitcnt lgkmcnt(5)
	v_mfma_f32_32x32x16_bf16 v[0:15], v[130:133], v[44:47], v[0:15]
	v_mfma_f32_32x32x16_bf16 v[16:31], v[126:129], v[36:39], v[16:31]
	s_waitcnt lgkmcnt(4)
	v_mfma_f32_32x32x16_bf16 v[0:15], v[138:141], v[36:39], v[0:15]
	s_waitcnt lgkmcnt(3)
	v_mfma_f32_32x32x16_bf16 v[16:31], v[142:145], v[40:43], v[16:31]
	s_waitcnt lgkmcnt(1)
	v_mfma_f32_32x32x16_bf16 v[0:15], v[150:153], v[40:43], v[0:15]
	v_mfma_f32_32x32x16_bf16 v[16:31], v[146:149], v[32:35], v[16:31]
	s_waitcnt lgkmcnt(0)
	v_mfma_f32_32x32x16_bf16 v[0:15], v[154:157], v[32:35], v[0:15]
	s_nop 0
	ds_read_b32 v50, v50
	s_waitcnt lgkmcnt(0)
	v_readfirstlane_b32 s6, v50
	s_nop 1
	v_lshl_or_b32 v50, s6, 6, v214
	v_sub_u32_e32 v121, v121, v50
	v_cmp_gt_i32_e64 s[64:65], 26, v121
	v_cmp_gt_i32_e64 s[68:69], 27, v121
	v_cmp_gt_i32_e64 s[60:61], 25, v121
	s_and_b64 s[64:65], s[68:69], s[64:65]
	v_cmp_gt_i32_e64 s[56:57], 24, v121
	s_and_b64 s[60:61], s[64:65], s[60:61]
	v_cmp_gt_i32_e64 s[52:53], 19, v121
	s_and_b64 s[56:57], s[60:61], s[56:57]
	v_cmp_gt_i32_e64 s[48:49], 18, v121
	s_and_b64 s[52:53], s[56:57], s[52:53]
	v_cmp_gt_i32_e64 s[44:45], 17, v121
	s_and_b64 s[48:49], s[52:53], s[48:49]
	v_cmp_gt_i32_e64 s[40:41], 16, v121
	s_and_b64 s[44:45], s[48:49], s[44:45]
	v_cmp_gt_i32_e64 s[36:37], 11, v121
	s_and_b64 s[40:41], s[44:45], s[40:41]
	v_cmp_gt_i32_e64 s[30:31], 10, v121
	s_and_b64 s[36:37], s[40:41], s[36:37]
	v_cmp_gt_i32_e64 s[26:27], 9, v121
	s_and_b64 s[30:31], s[36:37], s[30:31]
	v_cmp_gt_i32_e64 s[22:23], 8, v121
	s_and_b64 s[26:27], s[30:31], s[26:27]
	v_cmp_gt_i32_e64 s[20:21], 3, v121
	s_and_b64 s[22:23], s[26:27], s[22:23]
	v_cmp_gt_i32_e64 s[18:19], 2, v121
	s_and_b64 s[20:21], s[22:23], s[20:21]
	v_cmp_gt_i32_e64 s[16:17], 1, v121
	s_and_b64 s[18:19], s[20:21], s[18:19]
	v_cmp_gt_i32_e64 s[14:15], 0, v121
	s_and_b64 s[16:17], s[18:19], s[16:17]
	s_and_b64 s[14:15], s[16:17], s[14:15]
	v_cmp_gt_i32_e64 s[66:67], 58, v121
	v_cndmask_b32_e64 v50, v16, v207, s[14:15]
	v_cmp_gt_i32_e64 s[14:15], 59, v121
	v_cmp_gt_i32_e64 s[62:63], 57, v121
	v_cmp_gt_i32_e64 s[58:59], 56, v121
	v_cndmask_b32_e64 v15, v15, v207, s[14:15]
	s_and_b64 s[14:15], s[14:15], s[66:67]
	v_cndmask_b32_e64 v14, v14, v207, s[14:15]
	s_and_b64 s[14:15], s[14:15], s[62:63]
	v_cmp_gt_i32_e64 s[54:55], 51, v121
	v_cndmask_b32_e64 v13, v13, v207, s[14:15]
	s_and_b64 s[14:15], s[14:15], s[58:59]
	v_cmp_gt_i32_e64 s[50:51], 50, v121
	v_cndmask_b32_e64 v12, v12, v207, s[14:15]
	s_and_b64 s[14:15], s[14:15], s[54:55]
	v_cmp_gt_i32_e64 s[46:47], 49, v121
	v_cndmask_b32_e64 v11, v11, v207, s[14:15]
	s_and_b64 s[14:15], s[14:15], s[50:51]
	v_cmp_gt_i32_e64 s[42:43], 48, v121
	v_cndmask_b32_e64 v10, v10, v207, s[14:15]
	s_and_b64 s[14:15], s[14:15], s[46:47]
	v_cmp_gt_i32_e64 s[38:39], 43, v121
	v_cndmask_b32_e64 v9, v9, v207, s[14:15]
	s_and_b64 s[14:15], s[14:15], s[42:43]
	v_cmp_gt_i32_e64 s[34:35], 42, v121
	v_cndmask_b32_e64 v8, v8, v207, s[14:15]
	s_and_b64 s[14:15], s[14:15], s[38:39]
	v_cmp_gt_i32_e64 s[28:29], 41, v121
	v_cndmask_b32_e64 v7, v7, v207, s[14:15]
	s_and_b64 s[14:15], s[14:15], s[34:35]
	v_cmp_gt_i32_e64 s[24:25], 40, v121
	v_cndmask_b32_e64 v6, v6, v207, s[14:15]
	s_and_b64 s[14:15], s[14:15], s[28:29]
	v_cmp_gt_i32_e64 s[12:13], 35, v121
	v_cndmask_b32_e64 v5, v5, v207, s[14:15]
	s_and_b64 s[14:15], s[14:15], s[24:25]
	v_cmp_gt_i32_e64 s[10:11], 34, v121
	s_and_b64 s[12:13], s[14:15], s[12:13]
	v_cmp_gt_i32_e64 s[8:9], 33, v121
	s_and_b64 s[10:11], s[12:13], s[10:11]
	v_cmp_gt_i32_e32 vcc, 32, v121
	s_and_b64 s[8:9], s[10:11], s[8:9]
	v_cndmask_b32_e64 v51, v17, v207, s[16:17]
	s_and_b64 vcc, s[8:9], vcc
	v_cndmask_b32_e64 v17, v1, v207, s[8:9]
	v_cndmask_b32_e32 v16, v0, v207, vcc
	v_max_f32_e32 v0, v51, v51
	v_max_f32_e32 v1, v50, v50
	v_cndmask_b32_e64 v19, v19, v207, s[20:21]
	v_cndmask_b32_e64 v18, v18, v207, s[18:19]
	v_cndmask_b32_e64 v2, v2, v207, s[10:11]
	v_max_f32_e32 v0, v1, v0
	v_cndmask_b32_e64 v23, v23, v207, s[36:37]
	v_cndmask_b32_e64 v22, v22, v207, s[30:31]
	v_cndmask_b32_e64 v20, v20, v207, s[22:23]
	v_cndmask_b32_e64 v3, v3, v207, s[12:13]
	v_max3_f32 v1, v18, v19, v17
	v_max3_f32 v0, v0, v16, v2
	v_cndmask_b32_e64 v21, v21, v207, s[26:27]
	v_cndmask_b32_e64 v4, v4, v207, s[14:15]
	v_max3_f32 v0, v0, v3, v20
	v_max3_f32 v1, v1, v22, v23
	v_cndmask_b32_e64 v27, v27, v207, s[52:53]
	v_cndmask_b32_e64 v26, v26, v207, s[48:49]
	v_cndmask_b32_e64 v24, v24, v207, s[40:41]
	v_max3_f32 v0, v0, v21, v4
	v_max3_f32 v1, v1, v6, v7
	v_cndmask_b32_e64 v25, v25, v207, s[44:45]
	v_max3_f32 v0, v0, v5, v24
	v_max3_f32 v1, v1, v26, v27
	v_cndmask_b32_e64 v31, v31, v207, s[68:69]
	v_cndmask_b32_e64 v30, v30, v207, s[64:65]
	v_cndmask_b32_e64 v28, v28, v207, s[56:57]
	v_max3_f32 v0, v0, v25, v8
	v_max3_f32 v1, v1, v10, v11
	v_cndmask_b32_e64 v29, v29, v207, s[60:61]
	v_max3_f32 v0, v0, v9, v28
	v_max3_f32 v1, v1, v30, v31
	v_max3_f32 v0, v0, v29, v12
	v_max3_f32 v1, v1, v14, v15
	v_max3_f32 v0, v0, v13, v1
	ds_bpermute_b32 v1, v193, v0
	s_waitcnt lgkmcnt(0)
	v_max_f32_e32 v1, v1, v1
	v_max_f32_e32 v0, v0, v1
	v_cmp_lt_f32_e32 vcc, s7, v0
	s_cbranch_vccz .LBB0_902
; template <int NDVB, bool HAS_NEXT> DI void softmax_def(f32x16& sa0, f32x16& sa1, f32x16& sb0, f32x16& sb1, f32x16 (&O)[NDVB], float& muse, float& l, bool first, bf16x8 (&P)[4], bool check = true) {
;     ...
;   if (check && (first || __any(mx > 8.f))) {
;     float dl = first ? mx : fmaxf(mx, 0.f);
;     if (mx < -1e29f) dl = 0.f;
;     const float alpha = __builtin_amdgcn_exp2f(-dl);
;     muse += dl; l *= alpha;
; #pragma unroll
;     for (int i = 0; i < 16; ++i) { sa0[i] -= dl; sa1[i] -= dl; }
;     if (HAS_NEXT) {
; #pragma unroll
;       for (int i = 0; i < 16; ++i) { sb0[i] -= dl; sb1[i] -= dl; }
;     }
; #pragma unroll
;     for (int d = 0; d < NDVB; ++d)
; #pragma unroll
;       for (int i = 0; i < 16; ++i) O[d][i] *= alpha;
;   }
	v_max_f32_e32 v1, v0, v0
	v_max_f32_e32 v1, 0, v1
	v_cmp_ngt_f32_e32 vcc, s85, v0
	s_nop 1
	v_cndmask_b32_e32 v121, 0, v1, vcc
	v_exp_f32_e64 v122, -v121
	v_pk_add_f32 v[0:1], v[48:49], v[120:121]
	v_pk_mul_f32 v[78:79], v[78:79], v[122:123] op_sel_hi:[1,0]
	v_mov_b32_e32 v0, v121
	v_pk_add_f32 v[50:51], v[50:51], v[0:1] op_sel_hi:[1,0] neg_lo:[0,1] neg_hi:[0,1]
	v_pk_add_f32 v[16:17], v[16:17], v[0:1] op_sel_hi:[1,0] neg_lo:[0,1] neg_hi:[0,1]
	v_pk_add_f32 v[18:19], v[18:19], v[0:1] op_sel_hi:[1,0] neg_lo:[0,1] neg_hi:[0,1]
	v_pk_add_f32 v[2:3], v[2:3], v[0:1] op_sel_hi:[1,0] neg_lo:[0,1] neg_hi:[0,1]
	v_pk_add_f32 v[20:21], v[20:21], v[0:1] op_sel_hi:[1,0] neg_lo:[0,1] neg_hi:[0,1]
	v_pk_add_f32 v[4:5], v[4:5], v[0:1] op_sel_hi:[1,0] neg_lo:[0,1] neg_hi:[0,1]
	v_pk_add_f32 v[22:23], v[22:23], v[0:1] op_sel_hi:[1,0] neg_lo:[0,1] neg_hi:[0,1]
	v_pk_add_f32 v[6:7], v[6:7], v[0:1] op_sel_hi:[1,0] neg_lo:[0,1] neg_hi:[0,1]
	v_pk_add_f32 v[24:25], v[24:25], v[0:1] op_sel_hi:[1,0] neg_lo:[0,1] neg_hi:[0,1]
	v_pk_add_f32 v[8:9], v[8:9], v[0:1] op_sel_hi:[1,0] neg_lo:[0,1] neg_hi:[0,1]
	v_pk_add_f32 v[26:27], v[26:27], v[0:1] op_sel_hi:[1,0] neg_lo:[0,1] neg_hi:[0,1]
	v_pk_add_f32 v[10:11], v[10:11], v[0:1] op_sel_hi:[1,0] neg_lo:[0,1] neg_hi:[0,1]
	v_pk_add_f32 v[28:29], v[28:29], v[0:1] op_sel_hi:[1,0] neg_lo:[0,1] neg_hi:[0,1]
	v_pk_add_f32 v[12:13], v[12:13], v[0:1] op_sel_hi:[1,0] neg_lo:[0,1] neg_hi:[0,1]
	v_pk_add_f32 v[30:31], v[30:31], v[0:1] op_sel_hi:[1,0] neg_lo:[0,1] neg_hi:[0,1]
	v_pk_add_f32 v[14:15], v[14:15], v[0:1] op_sel_hi:[1,0] neg_lo:[0,1] neg_hi:[0,1]
	v_pk_mul_f32 v[76:77], v[76:77], v[122:123] op_sel_hi:[1,0]
	v_pk_mul_f32 v[74:75], v[74:75], v[122:123] op_sel_hi:[1,0]
	v_pk_mul_f32 v[72:73], v[72:73], v[122:123] op_sel_hi:[1,0]
	v_pk_mul_f32 v[70:71], v[70:71], v[122:123] op_sel_hi:[1,0]
	v_pk_mul_f32 v[68:69], v[68:69], v[122:123] op_sel_hi:[1,0]
	v_pk_mul_f32 v[66:67], v[66:67], v[122:123] op_sel_hi:[1,0]
	v_pk_mul_f32 v[64:65], v[64:65], v[122:123] op_sel_hi:[1,0]
	v_pk_mul_f32 v[94:95], v[94:95], v[122:123] op_sel_hi:[1,0]
	v_pk_mul_f32 v[92:93], v[92:93], v[122:123] op_sel_hi:[1,0]
	v_pk_mul_f32 v[90:91], v[90:91], v[122:123] op_sel_hi:[1,0]
	v_pk_mul_f32 v[88:89], v[88:89], v[122:123] op_sel_hi:[1,0]
	v_pk_mul_f32 v[86:87], v[86:87], v[122:123] op_sel_hi:[1,0]
	v_pk_mul_f32 v[84:85], v[84:85], v[122:123] op_sel_hi:[1,0]
	v_pk_mul_f32 v[82:83], v[82:83], v[122:123] op_sel_hi:[1,0]
	v_pk_mul_f32 v[80:81], v[80:81], v[122:123] op_sel_hi:[1,0]
	v_mul_f32_e32 v48, v48, v122
	s_branch .LBB0_903

; DI unsigned cvtpk(float lo, float hi) { f32x2_t v = {lo, hi}; bf16x2_t b = __builtin_convertvector(v, bf16x2_t); return __builtin_bit_cast(unsigned, b); }
; template <int NDVB, bool HAS_NEXT> DI void softmax_def(f32x16& sa0, f32x16& sa1, f32x16& sb0, f32x16& sb1, f32x16 (&O)[NDVB], float& muse, float& l, bool first, bf16x8 (&P)[4], bool check = true) {
;     ...
;   float sum = 0.f;
; #pragma unroll
;   for (int i = 0; i < 16; ++i) { sa0[i] = __builtin_amdgcn_exp2f(sa0[i]); sum += sa0[i]; }
; #pragma unroll
;   for (int i = 0; i < 16; ++i) { sa1[i] = __builtin_amdgcn_exp2f(sa1[i]); sum += sa1[i]; }
;   l += sum;
;   u32x4 w;
;   w.x = cvtpk(sa0[0], sa0[1]); w.y = cvtpk(sa0[2], sa0[3]); w.z = cvtpk(sa0[4], sa0[5]); w.w = cvtpk(sa0[6], sa0[7]); P[0] = __builtin_bit_cast(bf16x8, w);
;   w.x = cvtpk(sa0[8], sa0[9]); w.y = cvtpk(sa0[10], sa0[11]); w.z = cvtpk(sa0[12], sa0[13]); w.w = cvtpk(sa0[14], sa0[15]); P[1] = __builtin_bit_cast(bf16x8, w);
;   w.x = cvtpk(sa1[0], sa1[1]); w.y = cvtpk(sa1[2], sa1[3]); w.z = cvtpk(sa1[4], sa1[5]); w.w = cvtpk(sa1[6], sa1[7]); P[2] = __builtin_bit_cast(bf16x8, w);
;   w.x = cvtpk(sa1[8], sa1[9]); w.y = cvtpk(sa1[10], sa1[11]); w.z = cvtpk(sa1[12], sa1[13]); w.w = cvtpk(sa1[14], sa1[15]); P[3] = __builtin_bit_cast(bf16x8, w);
; }
; template <int MODE, int SLOT> DI void ns_valu(volatile LAS int* jl, int t, int ntl, int qpos, int h, int blk, f32x16& s0, f32x16& s1, f32x16& du0, f32x16& du1, f32x16 (&O)[2], float& muse, float& l, bf16x8 (&P)[4], CmpCap& cap) {
;     ...
;       if (MODE == 0) {
; #pragma unroll
;         for (int ii = 0; ii < 4; ++ii) { cap.qs[SLOT][ii] = (s0[4 * ii] + s0[4 * ii + 1]) + (s0[4 * ii + 2] + s0[4 * ii + 3]); cap.ls[SLOT][ii] = s0[4 * ii + 3];
;           cap.qs[SLOT][4 + ii] = (s1[4 * ii] + s1[4 * ii + 1]) + (s1[4 * ii + 2] + s1[4 * ii + 3]); cap.ls[SLOT][4 + ii] = s1[4 * ii + 3]; }
;         cap.mrec[SLOT] = muse;
;       }
.LBB0_903:
	v_lshlrev_b32_e32 v217, 3, v55
	v_add_f32_e32 v0, v97, v98
	v_add_f32_e32 v55, v99, v56
	v_add_f32_e32 v121, v0, v55
	v_add_f32_e32 v0, v109, v110
	v_add_f32_e32 v55, v111, v60
	v_add_f32_e32 v97, v0, v55
	v_add_f32_e32 v0, v100, v101
	v_add_f32_e32 v55, v102, v57
	v_add_f32_e32 v101, v0, v55
	v_add_f32_e32 v0, v112, v113
	v_add_f32_e32 v55, v114, v61
	v_add_f32_e32 v98, v0, v55
	v_add_f32_e32 v0, v103, v104
	v_add_f32_e32 v55, v105, v58
	v_exp_f32_e32 v50, v50
	v_add_f32_e32 v100, v0, v55
	v_add_f32_e32 v0, v115, v116
	v_add_f32_e32 v55, v117, v62
	v_exp_f32_e32 v51, v51
	v_add_f32_e32 v55, v0, v55
	v_add_f32_e32 v0, v106, v107
	v_add_f32_e32 v99, v108, v59
	v_exp_f32_e32 v103, v18
	v_add_f32_e32 v99, v0, v99
	v_add_f32_e32 v0, v118, v119
	v_add_f32_e32 v102, v120, v63
	v_exp_f32_e32 v18, v19
	v_add_f32_e32 v0, v0, v102
	v_add_f32_e32 v102, 0, v50
	v_add_f32_e32 v102, v51, v102
	v_add_f32_e32 v102, v103, v102
	v_add_f32_e32 v19, v18, v102
	v_exp_f32_e32 v102, v20
	v_exp_f32_e32 v21, v21
	v_exp_f32_e32 v22, v22
	v_exp_f32_e32 v104, v2
	v_add_f32_e32 v19, v102, v19
	v_add_f32_e32 v19, v21, v19
	v_add_f32_e32 v20, v22, v19
	v_exp_f32_e32 v19, v23
	v_exp_f32_e32 v23, v24
	v_exp_f32_e32 v24, v25
	v_exp_f32_e32 v25, v26
	v_add_f32_e32 v20, v19, v20
	v_add_f32_e32 v20, v23, v20
	v_add_f32_e32 v20, v24, v20
	v_add_f32_e32 v26, v25, v20
	v_exp_f32_e32 v20, v27
	v_exp_f32_e32 v27, v28
	v_exp_f32_e32 v28, v29
	v_exp_f32_e32 v29, v30
	v_add_f32_e32 v26, v20, v26
	v_exp_f32_e32 v30, v31
	v_add_f32_e32 v26, v27, v26
	v_exp_f32_e32 v31, v16
	v_add_f32_e32 v26, v28, v26
	v_add_f32_e32 v26, v29, v26
	v_add_f32_e32 v26, v30, v26
	v_add_f32_e32 v16, v31, v26
	v_exp_f32_e32 v26, v17
	v_exp_f32_e32 v110, v3
	v_exp_f32_e32 v105, v4
	v_exp_f32_e32 v106, v5
	v_add_f32_e32 v16, v26, v16
	v_add_f32_e32 v2, v104, v16
	v_exp_f32_e32 v107, v6
	v_add_f32_e32 v2, v110, v2
	v_exp_f32_e32 v111, v7
	v_add_f32_e32 v2, v105, v2
	v_exp_f32_e32 v108, v8
	v_add_f32_e32 v2, v106, v2
	v_exp_f32_e32 v109, v9
	v_add_f32_e32 v2, v107, v2
	v_exp_f32_e32 v112, v10
	v_add_f32_e32 v2, v111, v2
	v_exp_f32_e32 v113, v11
	v_add_f32_e32 v2, v108, v2
	v_exp_f32_e32 v114, v12
	v_add_f32_e32 v2, v109, v2
	v_exp_f32_e32 v115, v13
	v_add_f32_e32 v2, v112, v2
	v_exp_f32_e32 v116, v14
	v_add_f32_e32 v2, v113, v2
	v_exp_f32_e32 v117, v15
	v_add_f32_e32 v2, v114, v2
	v_add_f32_e32 v2, v115, v2
	v_add_f32_e32 v2, v116, v2
	v_add_f32_e32 v2, v117, v2
	v_cvt_pk_bf16_f32 v4, v102, v21
	v_cvt_pk_bf16_f32 v5, v22, v19
	v_cvt_pk_bf16_f32 v10, v31, v26
	v_add_f32_e32 v26, v26, v31
	v_add_f32_e32 v31, v110, v104
	v_add_f32_e32 v21, v21, v102
	v_add_f32_e32 v22, v19, v22
	v_add_f32_e32 v48, v48, v2
	v_cvt_pk_bf16_f32 v2, v50, v51
	v_add_f32_e32 v50, v51, v50
	v_add_f32_e32 v51, v18, v103
	v_add_f32_e32 v31, v31, v26
	v_add_f32_e32 v21, v22, v21
	v_add_f32_e32 v22, v106, v105
	v_add_f32_e32 v26, v111, v107
	v_cvt_pk_bf16_f32 v6, v23, v24
	v_add_f32_e32 v50, v51, v50
	v_add_f32_e32 v51, v26, v22
	v_add_f32_e32 v22, v24, v23
	v_add_f32_e32 v23, v20, v25
	v_add_f32_e32 v118, v23, v22
	v_add_f32_e32 v22, v109, v108
	v_add_f32_e32 v23, v113, v112
	v_cvt_pk_bf16_f32 v15, v112, v113
	v_add_f32_e32 v112, v23, v22
	v_add_f32_e32 v22, v28, v27
	v_add_f32_e32 v23, v30, v29
	v_add_f32_e32 v119, v23, v22
	v_add_f32_e32 v22, v115, v114
	v_add_f32_e32 v23, v117, v116
	v_cvt_pk_bf16_f32 v3, v103, v18
	v_cvt_pk_bf16_f32 v7, v25, v20
	v_cvt_pk_bf16_f32 v8, v27, v28
	v_cvt_pk_bf16_f32 v9, v29, v30
	v_cvt_pk_bf16_f32 v11, v104, v110
	v_cvt_pk_bf16_f32 v12, v105, v106
	v_cvt_pk_bf16_f32 v13, v107, v111
	v_cvt_pk_bf16_f32 v14, v108, v109
	v_cvt_pk_bf16_f32 v16, v114, v115
	v_add_f32_e32 v114, v23, v22
	ds_read_b64_tr_b16 v[22:23], v96 offset:27648
	ds_read_b64_tr_b16 v[24:25], v96 offset:28800
	ds_read_b64_tr_b16 v[26:27], v96 offset:27712
	ds_read_b64_tr_b16 v[28:29], v96 offset:28864
	ds_read_b64_tr_b16 v[102:103], v96 offset:29952
	ds_read_b64_tr_b16 v[104:105], v96 offset:31104
	ds_read_b64_tr_b16 v[106:107], v96 offset:30016
	ds_read_b64_tr_b16 v[108:109], v96 offset:31168
	v_cvt_pk_bf16_f32 v17, v116, v117
	s_nop 0
	s_waitcnt lgkmcnt(6)
	v_mfma_f32_32x32x16_bf16 v[80:95], v[22:25], v[2:5], v[80:95]
	s_waitcnt lgkmcnt(4)
	v_mfma_f32_32x32x16_bf16 v[64:79], v[26:29], v[2:5], v[64:79]
	s_nop 0
	ds_read_b64_tr_b16 v[2:3], v96 offset:32256
	ds_read_b64_tr_b16 v[4:5], v96 offset:33408
	ds_read_b64_tr_b16 v[22:23], v96 offset:32320
	ds_read_b64_tr_b16 v[24:25], v96 offset:33472
	s_nop 0
	s_waitcnt lgkmcnt(6)
	v_mfma_f32_32x32x16_bf16 v[80:95], v[102:105], v[6:9], v[80:95]
	s_waitcnt lgkmcnt(4)
	v_mfma_f32_32x32x16_bf16 v[64:79], v[106:109], v[6:9], v[64:79]
	s_nop 0
	ds_read_b64_tr_b16 v[6:7], v96 offset:34560
	ds_read_b64_tr_b16 v[8:9], v96 offset:35712
	ds_read_b64_tr_b16 v[28:29], v96 offset:35776
	ds_read_b64_tr_b16 v[26:27], v96 offset:34624
	s_nop 0
	s_waitcnt lgkmcnt(6)
	v_mfma_f32_32x32x16_bf16 v[80:95], v[2:5], v[10:13], v[80:95]
	s_waitcnt lgkmcnt(4)
	v_mfma_f32_32x32x16_bf16 v[64:79], v[22:25], v[10:13], v[64:79]
	s_nop 0
	s_nop 0
	s_waitcnt lgkmcnt(2)
	v_mfma_f32_32x32x16_bf16 v[80:95], v[6:9], v[14:17], v[80:95]
	s_waitcnt lgkmcnt(0)
	v_mfma_f32_32x32x16_bf16 v[64:79], v[26:29], v[14:17], v[64:79]
	s_nop 0
	ds_bpermute_b32 v2, v193, v48
	v_readlane_b32 s1, v255, 39
	s_waitcnt lgkmcnt(0)
	s_barrier
; #define LAS __attribute__((address_space(3)))
; DI void nsa_unit(const Params& p, lds8* lds, int bl, int g, int qb32) {
;     ...
;   const float lt0 = l + __shfl_xor(l, 32); const float inv0 = lt0 > 0.f ? 1.f / lt0 : 0.f;
;   { const float f = g0 * inv0;
; #pragma unroll
;     for (int d = 0; d < 2; ++d)
; #pragma unroll
;       for (int i = 0; i < 16; ++i) OT[d][i] = O[d][i] * f; }
;   { LAS float* impw = (LAS float*)(lds + NS_IMPW) + (wid * 32 + r) * 33;
;     float carry = 0.f;
; #pragma unroll
;     for (int kt = 0; kt < 2; ++kt) {
;       const float scale = __builtin_amdgcn_exp2f(cap.mrec[kt] - m) * inv0;
; #pragma unroll
;       for (int kb = 0; kb < 2; ++kb)
; #pragma unroll
;         for (int ii = 0; ii < 4; ++ii) {
;           const float qsum = cap.qs[kt][kb * 4 + ii] * scale, last = cap.ls[kt][kb * 4 + ii] * scale;
;           const float other = __shfl_xor(last, 32);
;           const int ub = 16 * kt + 8 * kb + 2 * ii;
;           const float val = qsum + (h ? other : carry);
;           carry = other;
;           impw[ub + h] = val;
;         }
;     }
;   }
;   __syncthreads();
; #pragma unroll
;   for (int ks = 0; ks < 2; ++ks) {
;     const float* rc = rope + qpos * 32 + 16 * ks + 8 * h;
;     const f32x4 c0 = *(const f32x4*)rc, c1 = *(const f32x4*)(rc + 4), s0 = *(const f32x4*)(rc + 65536), s1 = *(const f32x4*)(rc + 65536 + 4);
	v_add_f32_e32 v2, v48, v2
	v_div_scale_f32 v3, s[8:9], v2, v2, 1.0
	v_rcp_f32_e32 v4, v3
	v_div_scale_f32 v5, vcc, 1.0, v2, 1.0
	v_readlane_b32 s8, v254, 63
	v_fma_f32 v6, -v3, v4, 1.0
	v_fmac_f32_e32 v4, v6, v4
	v_mul_f32_e32 v6, v5, v4
	v_fma_f32 v7, -v3, v6, v5
	v_fmac_f32_e32 v6, v7, v4
	v_fma_f32 v3, -v3, v6, v5
	v_div_fmas_f32 v3, v3, v4, v6
	v_sub_f32_e32 v4, v49, v1
	v_exp_f32_e32 v4, v4
	v_div_fixup_f32 v3, v3, v2, 1.0
	v_cmp_lt_f32_e32 vcc, 0, v2
	v_lshl_or_b32 v2, s1, 5, v52
	v_mul_lo_u32 v2, v2, s94
	v_cndmask_b32_e32 v218, 0, v3, vcc
	v_mul_f32_e32 v3, v4, v218
	v_mul_f32_e32 v4, v56, v3
	v_mul_f32_e32 v5, v57, v3
	ds_bpermute_b32 v4, v193, v4
	ds_bpermute_b32 v5, v193, v5
	v_mul_f32_e32 v7, v58, v3
	v_mul_f32_e32 v8, v59, v3
	ds_bpermute_b32 v7, v193, v7
	ds_bpermute_b32 v8, v193, v8
	v_cmp_gt_u32_e32 vcc, 32, v199
	v_add3_u32 v2, 0, v2, v214
	v_add_u32_e32 v2, 0xd800, v2
	s_waitcnt lgkmcnt(3)
	v_cndmask_b32_e64 v6, v4, 0, vcc
	s_waitcnt lgkmcnt(2)
	v_cndmask_b32_e32 v4, v5, v4, vcc
	v_fmac_f32_e32 v6, v121, v3
	v_fmac_f32_e32 v4, v101, v3
	ds_write2_b32 v2, v6, v4 offset1:2
	s_waitcnt lgkmcnt(2)
	v_cndmask_b32_e32 v4, v7, v5, vcc
	s_waitcnt lgkmcnt(1)
	v_cndmask_b32_e32 v5, v8, v7, vcc
	v_mul_f32_e32 v6, v60, v3
	v_mul_f32_e32 v7, v61, v3
	ds_bpermute_b32 v6, v193, v6
	ds_bpermute_b32 v7, v193, v7
	v_fmac_f32_e32 v4, v100, v3
	v_fmac_f32_e32 v5, v99, v3
	ds_write2_b32 v2, v4, v5 offset0:4 offset1:6
	s_waitcnt lgkmcnt(2)
	v_cndmask_b32_e32 v4, v6, v8, vcc
	s_waitcnt lgkmcnt(1)
	v_cndmask_b32_e32 v5, v7, v6, vcc
	v_fmac_f32_e32 v4, v97, v3
	v_fmac_f32_e32 v5, v98, v3
	ds_write2_b32 v2, v4, v5 offset0:8 offset1:10
	v_mul_f32_e32 v4, v62, v3
	v_sub_f32_e32 v1, v1, v1
	ds_bpermute_b32 v4, v193, v4
	v_exp_f32_e32 v1, v1
	v_mul_f32_e32 v5, v63, v3
	ds_bpermute_b32 v5, v193, v5
	v_lshlrev_b32_e32 v186, 5, v211
	v_mul_f32_e32 v1, v1, v218
	s_waitcnt lgkmcnt(1)
	v_cndmask_b32_e32 v6, v4, v7, vcc
	v_mul_f32_e32 v7, v18, v1
	ds_bpermute_b32 v7, v193, v7
	s_waitcnt lgkmcnt(1)
	v_cndmask_b32_e32 v4, v5, v4, vcc
	v_mul_f32_e32 v8, v19, v1
	v_fmac_f32_e32 v6, v55, v3
	ds_bpermute_b32 v8, v193, v8
	v_fmac_f32_e32 v4, v0, v3
	ds_write2_b32 v2, v6, v4 offset0:12 offset1:14
	s_waitcnt lgkmcnt(2)
	v_cndmask_b32_e32 v0, v7, v5, vcc
	v_mul_f32_e32 v4, v20, v1
	v_mul_f32_e32 v5, v30, v1
	ds_bpermute_b32 v4, v193, v4
	ds_bpermute_b32 v5, v193, v5
	s_waitcnt lgkmcnt(3)
	v_cndmask_b32_e32 v3, v8, v7, vcc
	v_fmac_f32_e32 v0, v50, v1
	v_fmac_f32_e32 v3, v21, v1
	ds_write2_b32 v2, v0, v3 offset0:16 offset1:18
	s_waitcnt lgkmcnt(2)
	v_cndmask_b32_e32 v0, v4, v8, vcc
	s_waitcnt lgkmcnt(1)
	v_cndmask_b32_e32 v3, v5, v4, vcc
	v_mul_f32_e32 v4, v110, v1
	v_mul_f32_e32 v6, v111, v1
	ds_bpermute_b32 v4, v193, v4
	ds_bpermute_b32 v6, v193, v6
	v_fmac_f32_e32 v0, v118, v1
	v_fmac_f32_e32 v3, v119, v1
	ds_write2_b32 v2, v0, v3 offset0:20 offset1:22
	s_waitcnt lgkmcnt(2)
	v_cndmask_b32_e32 v0, v4, v5, vcc
	s_waitcnt lgkmcnt(1)
	v_cndmask_b32_e32 v3, v6, v4, vcc
	v_mul_f32_e32 v4, v113, v1
	v_mul_f32_e32 v5, v117, v1
	ds_bpermute_b32 v4, v193, v4
	ds_bpermute_b32 v5, v193, v5
	v_fmac_f32_e32 v0, v31, v1
	v_fmac_f32_e32 v3, v51, v1
	ds_write2_b32 v2, v0, v3 offset0:24 offset1:26
	s_waitcnt lgkmcnt(2)
	v_cndmask_b32_e32 v0, v4, v6, vcc
	s_waitcnt lgkmcnt(1)
	v_cndmask_b32_e32 v3, v5, v4, vcc
	v_fmac_f32_e32 v0, v112, v1
	v_fmac_f32_e32 v3, v114, v1
	v_readlane_b32 s9, v253, 0
	ds_write2_b32 v2, v0, v3 offset0:28 offset1:30
	s_waitcnt lgkmcnt(0)
	v_lshl_add_u64 v[0:1], v[186:187], 2, s[8:9]
	v_lshlrev_b32_e32 v186, 2, v217
	v_lshl_add_u64 v[4:5], v[0:1], 0, v[186:187]
	s_mov_b64 s[8:9], 0x40000
	v_add_co_u32_e32 v6, vcc, 0x40000, v4
	v_lshl_add_u64 v[0:1], v[4:5], 0, s[8:9]
	s_nop 0
	v_addc_co_u32_e32 v7, vcc, 0, v5, vcc
	s_barrier
	global_load_dwordx4 v[16:19], v[4:5], off offset:16
	global_load_dwordx4 v[24:27], v[4:5], off
	global_load_dwordx4 v[28:31], v[6:7], off
	global_load_dwordx4 v[20:23], v[0:1], off offset:16
	s_nop 0
	global_load_dwordx4 v[0:3], v[4:5], off offset:80
	global_load_dwordx4 v[8:11], v[4:5], off offset:64
	s_mov_b64 s[8:9], 0x40040
	v_lshl_add_u64 v[4:5], v[4:5], 0, s[8:9]
	global_load_dwordx4 v[12:15], v[6:7], off offset:64
	s_nop 0
	global_load_dwordx4 v[4:7], v[4:5], off offset:16
	v_cmp_eq_u32_e32 vcc, 0, v136
	s_and_saveexec_b64 s[8:9], vcc
	s_cbranch_execz .LBB0_905
	v_readlane_b32 s1, v255, 10
	s_nop 1
	v_mov_b32_e32 v48, s1
	ds_write_b32 v48, v187

; template <int MODE, int SLOT> DI void ns_valu(volatile LAS int* jl, int t, int ntl, int qpos, int h, int blk, f32x16& s0, f32x16& s1, f32x16& du0, f32x16& du1, f32x16 (&O)[2], float& muse, float& l, bf16x8 (&P)[4], CmpCap& cap) {
;     ...
;       } else if (MODE == 1) {
;         if (j == blk) {
;           const int lim = qpos - 64 * j - 4 * h;
; #pragma unroll
;           for (int i = 0; i < 16; ++i) { const int ci = (i & 3) + 8 * (i >> 2); if (ci > lim) s0[i] = NEG; if (ci + 32 > lim) s1[i] = NEG; }
;         }
.LBB0_940:
	s_mul_i32 s94, s6, 0x4800
	s_add_i32 s95, s94, 0
	v_mov_b32_e32 v139, s90
	v_add_u32_e32 v33, s95, v213
	ds_read_b32 v32, v139
	ds_read_b128 v[96:99], v33 offset:4608
	ds_read_b128 v[100:103], v33
	ds_read_b128 v[104:107], v33 offset:32
	ds_read_b128 v[108:111], v33 offset:4640
	ds_read_b128 v[112:115], v33 offset:64
	ds_read_b128 v[116:119], v33 offset:4672
	ds_read_b128 v[120:123], v33 offset:96
	ds_read_b128 v[124:127], v33 offset:4704
	s_waitcnt lgkmcnt(8)
	v_readfirstlane_b32 s84, v32
	s_nop 1
	v_lshrrev_b32_e32 v32, s84, v137
	v_and_b32_e32 v32, 1, v32
	v_cmp_eq_u32_e32 vcc, 1, v32
	s_nop 1
	v_cndmask_b32_e64 v32, v207, -v138, vcc
	v_mov_b32_e32 v33, v32
	v_mov_b32_e32 v34, v32
	v_mov_b32_e32 v35, v32
	v_mov_b32_e32 v36, v32
	v_mov_b32_e32 v37, v32
	v_mov_b32_e32 v38, v32
	v_mov_b32_e32 v39, v32
	v_mov_b32_e32 v40, v32
	v_mov_b32_e32 v41, v32
	v_mov_b32_e32 v42, v32
	v_mov_b32_e32 v43, v32
	v_mov_b32_e32 v44, v32
	v_mov_b32_e32 v45, v32
	v_mov_b32_e32 v46, v32
	v_mov_b32_e32 v47, v32
	s_nop 0
	s_waitcnt lgkmcnt(6)
	v_mfma_f32_32x32x16_bf16 v[48:63], v[100:103], v[160:163], v[32:47]
	v_mfma_f32_32x32x16_bf16 v[32:47], v[96:99], v[160:163], v[32:47]
	s_waitcnt lgkmcnt(5)
	v_mfma_f32_32x32x16_bf16 v[48:63], v[104:107], v[168:171], v[48:63]
	s_waitcnt lgkmcnt(4)
	v_mfma_f32_32x32x16_bf16 v[32:47], v[108:111], v[168:171], v[32:47]
	s_waitcnt lgkmcnt(3)
	v_mfma_f32_32x32x16_bf16 v[48:63], v[112:115], v[164:167], v[48:63]
	s_waitcnt lgkmcnt(2)
	v_mfma_f32_32x32x16_bf16 v[32:47], v[116:119], v[164:167], v[32:47]
	s_waitcnt lgkmcnt(1)
	v_mfma_f32_32x32x16_bf16 v[48:63], v[120:123], v[172:175], v[48:63]
	s_waitcnt lgkmcnt(0)
	v_mfma_f32_32x32x16_bf16 v[32:47], v[124:127], v[172:175], v[32:47]
	s_nop 0
	s_cmp_lg_u32 s84, s77
	s_cbranch_scc1 .LBB0_944
	s_and_b64 vcc, s[70:71], s[66:67]
	s_nop 7
	v_cndmask_b32_e32 v45, v45, v207, vcc
	s_and_b64 vcc, vcc, s[62:63]
	v_cndmask_b32_e32 v44, v44, v207, vcc
	s_and_b64 vcc, vcc, s[58:59]
	v_cndmask_b32_e32 v43, v43, v207, vcc
	s_and_b64 vcc, vcc, s[54:55]
	v_cndmask_b32_e32 v42, v42, v207, vcc
	s_and_b64 vcc, vcc, s[50:51]
	v_cndmask_b32_e32 v41, v41, v207, vcc
	s_and_b64 vcc, vcc, s[46:47]
	v_cndmask_b32_e32 v40, v40, v207, vcc
	s_and_b64 vcc, vcc, s[42:43]
	v_cndmask_b32_e32 v39, v39, v207, vcc
	s_and_b64 vcc, vcc, s[38:39]
	v_cndmask_b32_e32 v38, v38, v207, vcc
	s_and_b64 vcc, vcc, s[34:35]
	v_cndmask_b32_e32 v37, v37, v207, vcc
	s_and_b64 vcc, vcc, s[28:29]
	v_cndmask_b32_e32 v36, v36, v207, vcc
	s_and_b64 vcc, vcc, s[24:25]
	v_cndmask_b32_e32 v35, v35, v207, vcc
	s_and_b64 vcc, vcc, s[20:21]
	v_cndmask_b32_e32 v34, v34, v207, vcc
	s_and_b64 vcc, vcc, s[16:17]
	v_cndmask_b32_e32 v33, v33, v207, vcc
	s_and_b64 vcc, vcc, s[12:13]
	v_cndmask_b32_e64 v46, v46, v207, s[70:71]
	v_cndmask_b32_e32 v32, v32, v207, vcc
	s_and_saveexec_b64 s[84:85], s[74:75]
	s_mov_b32 s86, 0xf149f2ca
	v_mov_b32_e32 v47, s86
	s_or_b64 exec, exec, s[84:85]
	s_and_b64 vcc, s[72:73], s[68:69]
	v_cndmask_b32_e32 v62, v62, v207, vcc
	s_and_b64 vcc, vcc, s[64:65]
	v_cndmask_b32_e32 v61, v61, v207, vcc
	s_and_b64 vcc, vcc, s[60:61]
	v_cndmask_b32_e32 v60, v60, v207, vcc
	s_and_b64 vcc, vcc, s[56:57]
	v_cndmask_b32_e32 v59, v59, v207, vcc
	s_and_b64 vcc, vcc, s[52:53]
	v_cndmask_b32_e32 v58, v58, v207, vcc
	s_and_b64 vcc, vcc, s[48:49]
	v_cndmask_b32_e32 v57, v57, v207, vcc
	s_and_b64 vcc, vcc, s[44:45]
	v_cndmask_b32_e32 v56, v56, v207, vcc
	s_and_b64 vcc, vcc, s[40:41]
	v_cndmask_b32_e32 v55, v55, v207, vcc
	s_and_b64 vcc, vcc, s[36:37]
	v_cndmask_b32_e32 v54, v54, v207, vcc
	s_and_b64 vcc, vcc, s[30:31]
	v_cndmask_b32_e32 v53, v53, v207, vcc
	s_and_b64 vcc, vcc, s[26:27]
	v_cndmask_b32_e32 v52, v52, v207, vcc
	s_and_b64 vcc, vcc, s[22:23]
	v_cndmask_b32_e32 v51, v51, v207, vcc
	s_and_b64 vcc, vcc, s[18:19]
	v_cndmask_b32_e32 v50, v50, v207, vcc
	s_and_b64 vcc, vcc, s[14:15]
	v_cndmask_b32_e32 v49, v49, v207, vcc
	s_and_b64 vcc, vcc, s[10:11]
	v_cndmask_b32_e64 v63, v63, v207, s[72:73]
	v_cndmask_b32_e32 v48, v48, v207, vcc

; DI unsigned cvtpk(float lo, float hi) { f32x2_t v = {lo, hi}; bf16x2_t b = __builtin_convertvector(v, bf16x2_t); return __builtin_bit_cast(unsigned, b); }
; #define MFMA32(a, b, c) __builtin_amdgcn_mfma_f32_32x32x16_bf16((a), (b), (c), 0, 0, 0)
; #define SBAR() __builtin_amdgcn_sched_barrier(0)
; template <int VSTR, int NDVB> DI void pv64(f32x16 (&O)[NDVB], const lds8* vp, const bf16x8 (&P)[4]) {
;   bf16x8 f[2][NDVB];
; #pragma unroll
;   for (int d = 0; d < NDVB; ++d) { const s16x4 lo = trrd(vp + d * 64), hi = trrd(vp + 8 * VSTR + d * 64); f[0][d] = __builtin_shufflevector(lo, hi, 0, 1, 2, 3, 4, 5, 6, 7); }
; #pragma unroll
;   for (int kk = 0; kk < 4; ++kk) {
;     if (kk < 3) {
; #pragma unroll
;       for (int d = 0; d < NDVB; ++d) { const s16x4 lo = trrd(vp + (16 * (kk + 1)) * VSTR + d * 64), hi = trrd(vp + (16 * (kk + 1) + 8) * VSTR + d * 64);
;         f[(kk + 1) & 1][d] = __builtin_shufflevector(lo, hi, 0, 1, 2, 3, 4, 5, 6, 7); }
;     }
;     SBAR();
;     __builtin_amdgcn_s_setprio(1);
; #pragma unroll
;     for (int d = 0; d < NDVB; ++d) O[d] = MFMA32(f[kk & 1][d], P[kk], O[d]);
;     __builtin_amdgcn_s_setprio(0);
;     SBAR();
;   }
; }
; template <int NDVB, bool HAS_NEXT> DI void softmax_def(f32x16& sa0, f32x16& sa1, f32x16& sb0, f32x16& sb1, f32x16 (&O)[NDVB], float& muse, float& l, bool first, bf16x8 (&P)[4], bool check = true) {
;     ...
;   float sum = 0.f;
; #pragma unroll
;   for (int i = 0; i < 16; ++i) { sa0[i] = __builtin_amdgcn_exp2f(sa0[i]); sum += sa0[i]; }
; #pragma unroll
;   for (int i = 0; i < 16; ++i) { sa1[i] = __builtin_amdgcn_exp2f(sa1[i]); sum += sa1[i]; }
;   l += sum;
;   u32x4 w;
;   w.x = cvtpk(sa0[0], sa0[1]); w.y = cvtpk(sa0[2], sa0[3]); w.z = cvtpk(sa0[4], sa0[5]); w.w = cvtpk(sa0[6], sa0[7]); P[0] = __builtin_bit_cast(bf16x8, w);
;   w.x = cvtpk(sa0[8], sa0[9]); w.y = cvtpk(sa0[10], sa0[11]); w.z = cvtpk(sa0[12], sa0[13]); w.w = cvtpk(sa0[14], sa0[15]); P[1] = __builtin_bit_cast(bf16x8, w);
;   w.x = cvtpk(sa1[0], sa1[1]); w.y = cvtpk(sa1[2], sa1[3]); w.z = cvtpk(sa1[4], sa1[5]); w.w = cvtpk(sa1[6], sa1[7]); P[2] = __builtin_bit_cast(bf16x8, w);
;   w.x = cvtpk(sa1[8], sa1[9]); w.y = cvtpk(sa1[10], sa1[11]); w.z = cvtpk(sa1[12], sa1[13]); w.w = cvtpk(sa1[14], sa1[15]); P[3] = __builtin_bit_cast(bf16x8, w);
; }
.LBB0_951:
	v_exp_f32_e32 v108, v60
	v_add_u32_e32 v60, s95, v216
	v_exp_f32_e32 v96, v48
	v_exp_f32_e32 v97, v49
	v_exp_f32_e32 v98, v50
	v_exp_f32_e32 v99, v51
	v_exp_f32_e32 v100, v52
	v_exp_f32_e32 v101, v53
	v_exp_f32_e32 v102, v54
	v_exp_f32_e32 v103, v55
	v_exp_f32_e32 v104, v56
	v_exp_f32_e32 v105, v57
	v_exp_f32_e32 v106, v58
	v_exp_f32_e32 v107, v59
	v_exp_f32_e32 v124, v44
	v_exp_f32_e32 v125, v45
	v_exp_f32_e32 v126, v46
	v_exp_f32_e32 v127, v47
	ds_read_b64_tr_b16 v[44:45], v60 offset:9216
	ds_read_b64_tr_b16 v[46:47], v60 offset:10368
	ds_read_b64_tr_b16 v[50:51], v60 offset:10432
	ds_read_b64_tr_b16 v[48:49], v60 offset:9280
	ds_read_b64_tr_b16 v[52:53], v60 offset:11520
	ds_read_b64_tr_b16 v[54:55], v60 offset:12672
	ds_read_b64_tr_b16 v[58:59], v60 offset:12736
	ds_read_b64_tr_b16 v[56:57], v60 offset:11584
	v_exp_f32_e32 v109, v61
	v_exp_f32_e32 v110, v62
	v_exp_f32_e32 v111, v63
	v_exp_f32_e32 v112, v32
	v_exp_f32_e32 v113, v33
	v_exp_f32_e32 v114, v34
	v_exp_f32_e32 v115, v35
	v_exp_f32_e32 v116, v36
	v_exp_f32_e32 v117, v37
	v_exp_f32_e32 v118, v38
	v_exp_f32_e32 v119, v39
	v_exp_f32_e32 v120, v40
	v_exp_f32_e32 v121, v41
	v_exp_f32_e32 v122, v42
	v_exp_f32_e32 v123, v43
	v_cvt_pk_bf16_f32 v32, v96, v97
	v_cvt_pk_bf16_f32 v33, v98, v99
	v_cvt_pk_bf16_f32 v34, v100, v101
	v_cvt_pk_bf16_f32 v35, v102, v103
	v_cvt_pk_bf16_f32 v36, v104, v105
	v_cvt_pk_bf16_f32 v37, v106, v107
	v_cvt_pk_bf16_f32 v38, v108, v109
	v_cvt_pk_bf16_f32 v39, v110, v111
	v_cvt_pk_bf16_f32 v40, v112, v113
	v_cvt_pk_bf16_f32 v41, v114, v115
	v_cvt_pk_bf16_f32 v42, v116, v117
	v_cvt_pk_bf16_f32 v43, v118, v119
	v_cvt_pk_bf16_f32 v140, v120, v121
	v_cvt_pk_bf16_f32 v141, v122, v123
	v_cvt_pk_bf16_f32 v142, v124, v125
	v_cvt_pk_bf16_f32 v143, v126, v127
	s_nop 0
	s_waitcnt lgkmcnt(6)
	v_mfma_f32_32x32x16_bf16 v[0:15], v[44:47], v[32:35], v[0:15]
	s_waitcnt lgkmcnt(4)
	v_mfma_f32_32x32x16_bf16 v[16:31], v[48:51], v[32:35], v[16:31]
	s_nop 0
	ds_read_b64_tr_b16 v[32:33], v60 offset:13824
	ds_read_b64_tr_b16 v[34:35], v60 offset:14976
	ds_read_b64_tr_b16 v[46:47], v60 offset:15040
	ds_read_b64_tr_b16 v[44:45], v60 offset:13888
	s_nop 0
	s_waitcnt lgkmcnt(6)
	v_mfma_f32_32x32x16_bf16 v[0:15], v[52:55], v[36:39], v[0:15]
	s_waitcnt lgkmcnt(4)
	v_mfma_f32_32x32x16_bf16 v[16:31], v[56:59], v[36:39], v[16:31]
	s_nop 0
	ds_read_b64_tr_b16 v[48:49], v60 offset:16128
	ds_read_b64_tr_b16 v[50:51], v60 offset:17280
	ds_read_b64_tr_b16 v[146:147], v60 offset:17344
	ds_read_b64_tr_b16 v[144:145], v60 offset:16192
	s_nop 0
	s_waitcnt lgkmcnt(6)
	v_mfma_f32_32x32x16_bf16 v[0:15], v[32:35], v[40:43], v[0:15]
	s_waitcnt lgkmcnt(4)
	v_mfma_f32_32x32x16_bf16 v[16:31], v[44:47], v[40:43], v[16:31]
	s_nop 0
	s_nop 0
	s_waitcnt lgkmcnt(2)
	v_mfma_f32_32x32x16_bf16 v[0:15], v[48:51], v[140:143], v[0:15]
	s_waitcnt lgkmcnt(0)
	v_mfma_f32_32x32x16_bf16 v[16:31], v[144:147], v[140:143], v[16:31]
	s_nop 0
	s_andn2_b64 vcc, exec, s[82:83]
	s_cbranch_vccnz .LBB0_953
	s_addk_i32 s94, 0xb800
	s_cmp_lg_u32 s6, 0
	s_cselect_b32 s82, s94, 0x9000
	v_add_u32_e32 v32, s82, v215
	s_waitcnt vmcnt(1)
	ds_write_b128 v32, v[128:131]
	s_waitcnt vmcnt(0)
	ds_write_b128 v32, v[132:135] offset:9216

; template <int MODE, int SLOT> DI void ns_valu(volatile LAS int* jl, int t, int ntl, int qpos, int h, int blk, f32x16& s0, f32x16& s1, f32x16& du0, f32x16& du1, f32x16 (&O)[2], float& muse, float& l, bf16x8 (&P)[4], CmpCap& cap) {
;     ...
;       } else if (MODE == 1) {
;         if (j == blk) {
;           const int lim = qpos - 64 * j - 4 * h;
; #pragma unroll
;           for (int i = 0; i < 16; ++i) { const int ci = (i & 3) + 8 * (i >> 2); if (ci > lim) s0[i] = NEG; if (ci + 32 > lim) s1[i] = NEG; }
;         }
.LBB0_956:
	s_add_i32 s84, s6, 1
	s_cmp_lg_u32 s6, 2
	s_cselect_b32 s6, s84, 0
	v_mov_b32_e32 v140, s90
	ds_read_b32 v32, v140 offset:4
	s_mul_i32 s86, s6, 0x4800
	s_add_i32 s87, s86, 0
	v_add_u32_e32 v60, s87, v213
	s_waitcnt lgkmcnt(0)
	v_readfirstlane_b32 s84, v32
	s_nop 1
	v_lshrrev_b32_e32 v32, s84, v137
	v_and_b32_e32 v32, 1, v32
	v_cmp_eq_u32_e32 vcc, 1, v32
	ds_read_b128 v[32:35], v60 offset:4608
	ds_read_b128 v[36:39], v60
	ds_read_b128 v[40:43], v60 offset:32
	ds_read_b128 v[44:47], v60 offset:4640
	ds_read_b128 v[48:51], v60 offset:64
	ds_read_b128 v[52:55], v60 offset:4672
	ds_read_b128 v[56:59], v60 offset:96
	ds_read_b128 v[60:63], v60 offset:4704
	v_cndmask_b32_e64 v96, v207, -v138, vcc
	v_mov_b32_e32 v97, v96
	v_mov_b32_e32 v98, v96
	v_mov_b32_e32 v99, v96
	v_mov_b32_e32 v100, v96
	v_mov_b32_e32 v101, v96
	v_mov_b32_e32 v102, v96
	v_mov_b32_e32 v103, v96
	v_mov_b32_e32 v104, v96
	v_mov_b32_e32 v105, v96
	v_mov_b32_e32 v106, v96
	v_mov_b32_e32 v107, v96
	v_mov_b32_e32 v108, v96
	v_mov_b32_e32 v109, v96
	v_mov_b32_e32 v110, v96
	v_mov_b32_e32 v111, v96
	s_nop 0
	s_waitcnt lgkmcnt(6)
	v_mfma_f32_32x32x16_bf16 v[112:127], v[36:39], v[160:163], v[96:111]
	v_mfma_f32_32x32x16_bf16 v[96:111], v[32:35], v[160:163], v[96:111]
	s_waitcnt lgkmcnt(5)
	v_mfma_f32_32x32x16_bf16 v[112:127], v[40:43], v[168:171], v[112:127]
	s_waitcnt lgkmcnt(4)
	v_mfma_f32_32x32x16_bf16 v[96:111], v[44:47], v[168:171], v[96:111]
	s_waitcnt lgkmcnt(3)
	v_mfma_f32_32x32x16_bf16 v[112:127], v[48:51], v[164:167], v[112:127]
	s_waitcnt lgkmcnt(2)
	v_mfma_f32_32x32x16_bf16 v[96:111], v[52:55], v[164:167], v[96:111]
	s_waitcnt lgkmcnt(1)
	v_mfma_f32_32x32x16_bf16 v[112:127], v[56:59], v[172:175], v[112:127]
	s_waitcnt lgkmcnt(0)
	v_mfma_f32_32x32x16_bf16 v[96:111], v[60:63], v[172:175], v[96:111]
	s_nop 0
	s_cmp_lg_u32 s84, s77
	s_cbranch_scc1 .LBB0_960
	s_and_b64 vcc, s[70:71], s[66:67]
	s_nop 7
	v_cndmask_b32_e32 v109, v109, v207, vcc
	s_and_b64 vcc, vcc, s[62:63]
	v_cndmask_b32_e32 v108, v108, v207, vcc
	s_and_b64 vcc, vcc, s[58:59]
	v_cndmask_b32_e32 v107, v107, v207, vcc
	s_and_b64 vcc, vcc, s[54:55]
	v_cndmask_b32_e32 v106, v106, v207, vcc
	s_and_b64 vcc, vcc, s[50:51]
	v_cndmask_b32_e32 v105, v105, v207, vcc
	s_and_b64 vcc, vcc, s[46:47]
	v_cndmask_b32_e32 v104, v104, v207, vcc
	s_and_b64 vcc, vcc, s[42:43]
	v_cndmask_b32_e32 v103, v103, v207, vcc
	s_and_b64 vcc, vcc, s[38:39]
	v_cndmask_b32_e32 v102, v102, v207, vcc
	s_and_b64 vcc, vcc, s[34:35]
	v_cndmask_b32_e32 v101, v101, v207, vcc
	s_and_b64 vcc, vcc, s[28:29]
	v_cndmask_b32_e32 v100, v100, v207, vcc
	s_and_b64 vcc, vcc, s[24:25]
	v_cndmask_b32_e32 v99, v99, v207, vcc
	s_and_b64 vcc, vcc, s[20:21]
	v_cndmask_b32_e32 v98, v98, v207, vcc
	s_and_b64 vcc, vcc, s[16:17]
	v_cndmask_b32_e32 v97, v97, v207, vcc
	s_and_b64 vcc, vcc, s[12:13]
	v_cndmask_b32_e64 v110, v110, v207, s[70:71]
	v_cndmask_b32_e32 v96, v96, v207, vcc
	s_and_saveexec_b64 s[84:85], s[74:75]
	s_mov_b32 s94, 0xf149f2ca
	v_mov_b32_e32 v111, s94
	s_or_b64 exec, exec, s[84:85]
	s_and_b64 vcc, s[72:73], s[68:69]
	v_cndmask_b32_e32 v126, v126, v207, vcc
	s_and_b64 vcc, vcc, s[64:65]
	v_cndmask_b32_e32 v125, v125, v207, vcc
	s_and_b64 vcc, vcc, s[60:61]
	v_cndmask_b32_e32 v124, v124, v207, vcc
	s_and_b64 vcc, vcc, s[56:57]
	v_cndmask_b32_e32 v123, v123, v207, vcc
	s_and_b64 vcc, vcc, s[52:53]
	v_cndmask_b32_e32 v122, v122, v207, vcc
	s_and_b64 vcc, vcc, s[48:49]
	v_cndmask_b32_e32 v121, v121, v207, vcc
	s_and_b64 vcc, vcc, s[44:45]
	v_cndmask_b32_e32 v120, v120, v207, vcc
	s_and_b64 vcc, vcc, s[40:41]
	v_cndmask_b32_e32 v119, v119, v207, vcc
	s_and_b64 vcc, vcc, s[36:37]
	v_cndmask_b32_e32 v118, v118, v207, vcc
	s_and_b64 vcc, vcc, s[30:31]
	v_cndmask_b32_e32 v117, v117, v207, vcc
	s_and_b64 vcc, vcc, s[26:27]
	v_cndmask_b32_e32 v116, v116, v207, vcc
	s_and_b64 vcc, vcc, s[22:23]
	v_cndmask_b32_e32 v115, v115, v207, vcc
	s_and_b64 vcc, vcc, s[18:19]
	v_cndmask_b32_e32 v114, v114, v207, vcc
	s_and_b64 vcc, vcc, s[14:15]
	v_cndmask_b32_e32 v113, v113, v207, vcc
	s_and_b64 vcc, vcc, s[10:11]
	v_cndmask_b32_e64 v127, v127, v207, s[72:73]
	v_cndmask_b32_e32 v112, v112, v207, vcc

; DI unsigned cvtpk(float lo, float hi) { f32x2_t v = {lo, hi}; bf16x2_t b = __builtin_convertvector(v, bf16x2_t); return __builtin_bit_cast(unsigned, b); }
; #define MFMA32(a, b, c) __builtin_amdgcn_mfma_f32_32x32x16_bf16((a), (b), (c), 0, 0, 0)
; #define SBAR() __builtin_amdgcn_sched_barrier(0)
; template <int VSTR, int NDVB> DI void pv64(f32x16 (&O)[NDVB], const lds8* vp, const bf16x8 (&P)[4]) {
;   bf16x8 f[2][NDVB];
; #pragma unroll
;   for (int d = 0; d < NDVB; ++d) { const s16x4 lo = trrd(vp + d * 64), hi = trrd(vp + 8 * VSTR + d * 64); f[0][d] = __builtin_shufflevector(lo, hi, 0, 1, 2, 3, 4, 5, 6, 7); }
; #pragma unroll
;   for (int kk = 0; kk < 4; ++kk) {
;     if (kk < 3) {
; #pragma unroll
;       for (int d = 0; d < NDVB; ++d) { const s16x4 lo = trrd(vp + (16 * (kk + 1)) * VSTR + d * 64), hi = trrd(vp + (16 * (kk + 1) + 8) * VSTR + d * 64);
;         f[(kk + 1) & 1][d] = __builtin_shufflevector(lo, hi, 0, 1, 2, 3, 4, 5, 6, 7); }
;     }
;     SBAR();
;     __builtin_amdgcn_s_setprio(1);
; #pragma unroll
;     for (int d = 0; d < NDVB; ++d) O[d] = MFMA32(f[kk & 1][d], P[kk], O[d]);
;     __builtin_amdgcn_s_setprio(0);
;     SBAR();
;   }
; }
; template <int NDVB, bool HAS_NEXT> DI void softmax_def(f32x16& sa0, f32x16& sa1, f32x16& sb0, f32x16& sb1, f32x16 (&O)[NDVB], float& muse, float& l, bool first, bf16x8 (&P)[4], bool check = true) {
;     ...
;   float sum = 0.f;
; #pragma unroll
;   for (int i = 0; i < 16; ++i) { sa0[i] = __builtin_amdgcn_exp2f(sa0[i]); sum += sa0[i]; }
; #pragma unroll
;   for (int i = 0; i < 16; ++i) { sa1[i] = __builtin_amdgcn_exp2f(sa1[i]); sum += sa1[i]; }
;   l += sum;
;   u32x4 w;
;   w.x = cvtpk(sa0[0], sa0[1]); w.y = cvtpk(sa0[2], sa0[3]); w.z = cvtpk(sa0[4], sa0[5]); w.w = cvtpk(sa0[6], sa0[7]); P[0] = __builtin_bit_cast(bf16x8, w);
;   w.x = cvtpk(sa0[8], sa0[9]); w.y = cvtpk(sa0[10], sa0[11]); w.z = cvtpk(sa0[12], sa0[13]); w.w = cvtpk(sa0[14], sa0[15]); P[1] = __builtin_bit_cast(bf16x8, w);
;   w.x = cvtpk(sa1[0], sa1[1]); w.y = cvtpk(sa1[2], sa1[3]); w.z = cvtpk(sa1[4], sa1[5]); w.w = cvtpk(sa1[6], sa1[7]); P[2] = __builtin_bit_cast(bf16x8, w);
;   w.x = cvtpk(sa1[8], sa1[9]); w.y = cvtpk(sa1[10], sa1[11]); w.z = cvtpk(sa1[12], sa1[13]); w.w = cvtpk(sa1[14], sa1[15]); P[3] = __builtin_bit_cast(bf16x8, w);
; }
.LBB0_964:
	v_add_u32_e32 v141, s87, v216
	ds_read_b64_tr_b16 v[154:155], v141 offset:9216
	ds_read_b64_tr_b16 v[156:157], v141 offset:10368
	ds_read_b64_tr_b16 v[178:179], v141 offset:10432
	ds_read_b64_tr_b16 v[176:177], v141 offset:9280
	ds_read_b64_tr_b16 v[180:181], v141 offset:11520
	ds_read_b64_tr_b16 v[182:183], v141 offset:12672
	ds_read_b64_tr_b16 v[222:223], v141 offset:12736
	ds_read_b64_tr_b16 v[220:221], v141 offset:11584
	v_exp_f32_e32 v112, v112
	v_exp_f32_e32 v113, v113
	v_exp_f32_e32 v114, v114
	v_exp_f32_e32 v115, v115
	v_exp_f32_e32 v116, v116
	v_exp_f32_e32 v117, v117
	v_exp_f32_e32 v118, v118
	v_exp_f32_e32 v119, v119
	v_exp_f32_e32 v120, v120
	v_exp_f32_e32 v121, v121
	v_exp_f32_e32 v122, v122
	v_exp_f32_e32 v123, v123
	v_exp_f32_e32 v124, v124
	v_exp_f32_e32 v125, v125
	v_exp_f32_e32 v126, v126
	v_exp_f32_e32 v127, v127
	v_exp_f32_e32 v96, v96
	v_exp_f32_e32 v97, v97
	v_exp_f32_e32 v98, v98
	v_exp_f32_e32 v99, v99
	v_exp_f32_e32 v100, v100
	v_exp_f32_e32 v101, v101
	v_exp_f32_e32 v102, v102
	v_exp_f32_e32 v103, v103
	v_exp_f32_e32 v104, v104
	v_exp_f32_e32 v105, v105
	v_exp_f32_e32 v106, v106
	v_exp_f32_e32 v107, v107
	v_exp_f32_e32 v108, v108
	v_exp_f32_e32 v109, v109
	v_exp_f32_e32 v110, v110
	v_exp_f32_e32 v111, v111
	v_cvt_pk_bf16_f32 v142, v112, v113
	v_cvt_pk_bf16_f32 v143, v114, v115
	v_cvt_pk_bf16_f32 v144, v116, v117
	v_cvt_pk_bf16_f32 v145, v118, v119
	v_cvt_pk_bf16_f32 v146, v120, v121
	v_cvt_pk_bf16_f32 v147, v122, v123
	v_cvt_pk_bf16_f32 v148, v124, v125
	v_cvt_pk_bf16_f32 v149, v126, v127
	v_cvt_pk_bf16_f32 v150, v96, v97
	v_cvt_pk_bf16_f32 v151, v98, v99
	v_cvt_pk_bf16_f32 v152, v100, v101
	v_cvt_pk_bf16_f32 v153, v102, v103
	v_cvt_pk_bf16_f32 v224, v104, v105
	v_cvt_pk_bf16_f32 v225, v106, v107
	v_cvt_pk_bf16_f32 v226, v108, v109
	v_cvt_pk_bf16_f32 v227, v110, v111
	s_nop 0
	s_waitcnt lgkmcnt(6)
	v_mfma_f32_32x32x16_bf16 v[0:15], v[154:157], v[142:145], v[0:15]
	s_waitcnt lgkmcnt(4)
	v_mfma_f32_32x32x16_bf16 v[16:31], v[176:179], v[142:145], v[16:31]
	s_nop 0
	ds_read_b64_tr_b16 v[142:143], v141 offset:13824
	ds_read_b64_tr_b16 v[144:145], v141 offset:14976
	ds_read_b64_tr_b16 v[156:157], v141 offset:15040
	ds_read_b64_tr_b16 v[154:155], v141 offset:13888
	s_nop 0
	s_waitcnt lgkmcnt(6)
	v_mfma_f32_32x32x16_bf16 v[0:15], v[180:183], v[146:149], v[0:15]
	s_waitcnt lgkmcnt(4)
	v_mfma_f32_32x32x16_bf16 v[16:31], v[220:223], v[146:149], v[16:31]
	s_nop 0
	ds_read_b64_tr_b16 v[146:147], v141 offset:16128
	ds_read_b64_tr_b16 v[148:149], v141 offset:17280
	ds_read_b64_tr_b16 v[178:179], v141 offset:17344
	ds_read_b64_tr_b16 v[176:177], v141 offset:16192
	s_nop 0
	s_waitcnt lgkmcnt(6)
	v_mfma_f32_32x32x16_bf16 v[0:15], v[142:145], v[150:153], v[0:15]
	s_waitcnt lgkmcnt(4)
	v_mfma_f32_32x32x16_bf16 v[16:31], v[154:157], v[150:153], v[16:31]
	s_nop 0
	s_nop 0
	s_waitcnt lgkmcnt(2)
	v_mfma_f32_32x32x16_bf16 v[0:15], v[146:149], v[224:227], v[0:15]
	s_waitcnt lgkmcnt(0)
	v_mfma_f32_32x32x16_bf16 v[16:31], v[176:179], v[224:227], v[16:31]
	s_nop 0
	s_andn2_b64 vcc, exec, s[82:83]
	s_cbranch_vccnz .LBB0_936
	s_addk_i32 s86, 0xb800
	s_cmp_lg_u32 s6, 0
	s_cselect_b32 s82, s86, 0x9000
	v_add_u32_e32 v141, s82, v215
	s_waitcnt vmcnt(1)
	ds_write_b128 v141, v[128:131]
	s_waitcnt vmcnt(0)
	ds_write_b128 v141, v[132:135] offset:9216
	s_branch .LBB0_936

; #define LAS __attribute__((address_space(3)))
; #define MFMA32(a, b, c) __builtin_amdgcn_mfma_f32_32x32x16_bf16((a), (b), (c), 0, 0, 0)
; #define SBAR() __builtin_amdgcn_sched_barrier(0)
; template <int KSTR> DI void qk64b(f32x16& s0, f32x16& s1, const lds8* kp, const bf16x8 (&q)[4], float bias) {
;   bf16x8 a[8];
; #pragma unroll
;   for (int ks = 0; ks < 4; ++ks) { a[2 * ks] = *(const LAS bf16x8*)(kp + ks * 32); a[2 * ks + 1] = *(const LAS bf16x8*)(kp + 32 * KSTR + ks * 32); }
; #pragma unroll
;   for (int i = 0; i < 16; ++i) { s0[i] = bias; s1[i] = bias; }
;   SBAR();
;   __builtin_amdgcn_s_setprio(1);
; #pragma unroll
;   for (int ks = 0; ks < 4; ++ks) { s0 = MFMA32(a[2 * ks], q[ks], s0); s1 = MFMA32(a[2 * ks + 1], q[ks], s1); }
;   __builtin_amdgcn_s_setprio(0);
;   SBAR();
; }
; template <int MODE, int SLOT> DI void ns_valu(volatile LAS int* jl, int t, int ntl, int qpos, int h, int blk, f32x16& s0, f32x16& s1, f32x16& du0, f32x16& du1, f32x16 (&O)[2], float& muse, float& l, bf16x8 (&P)[4], CmpCap& cap) {
;     ...
;       } else {
;         if (j == blk || j + 8 == blk) {
;           const int lim = qpos - 64 * j - 4 * h, lo = lim - 512;
; #pragma unroll
;           for (int i = 0; i < 16; ++i) { const int ci = (i & 3) + 8 * (i >> 2); if (ci > lim || ci <= lo) s0[i] = NEG; if (ci + 32 > lim || ci + 32 <= lo) s1[i] = NEG; }
;         }
.LBB0_983:
	s_mul_i32 s48, s6, 0x4800
	s_add_i32 s49, s48, 0
	v_add_u32_e32 v97, s49, v213
	ds_read_b128 v[130:133], v97
	ds_read_b128 v[134:137], v97 offset:32
	ds_read_b128 v[138:141], v97 offset:4608
	ds_read_b128 v[142:145], v97 offset:4640
	ds_read_b128 v[146:149], v97 offset:64
	ds_read_b128 v[150:153], v97 offset:96
	ds_read_b128 v[154:157], v97 offset:4672
	ds_read_b128 v[222:225], v97 offset:4704
	v_xor_b32_e32 v96, 0x80000000, v221
	v_mov_b32_e32 v97, v96
	v_mov_b32_e32 v98, v96
	v_mov_b32_e32 v99, v96
	v_mov_b32_e32 v100, v96
	v_mov_b32_e32 v101, v96
	v_mov_b32_e32 v102, v96
	v_mov_b32_e32 v103, v96
	v_mov_b32_e32 v104, v96
	v_mov_b32_e32 v105, v96
	v_mov_b32_e32 v106, v96
	v_mov_b32_e32 v107, v96
	v_mov_b32_e32 v108, v96
	v_mov_b32_e32 v109, v96
	v_mov_b32_e32 v110, v96
	v_mov_b32_e32 v111, v96
	s_nop 0
	s_waitcnt lgkmcnt(7)
	v_mfma_f32_32x32x16_bf16 v[112:127], v[130:133], v[160:163], v[96:111]
	s_waitcnt lgkmcnt(5)
	v_mfma_f32_32x32x16_bf16 v[96:111], v[138:141], v[160:163], v[96:111]
	v_mfma_f32_32x32x16_bf16 v[112:127], v[134:137], v[168:171], v[112:127]
	s_waitcnt lgkmcnt(4)
	v_mfma_f32_32x32x16_bf16 v[96:111], v[142:145], v[168:171], v[96:111]
	s_waitcnt lgkmcnt(3)
	v_mfma_f32_32x32x16_bf16 v[112:127], v[146:149], v[164:167], v[112:127]
	s_waitcnt lgkmcnt(1)
	v_mfma_f32_32x32x16_bf16 v[96:111], v[154:157], v[164:167], v[96:111]
	v_mfma_f32_32x32x16_bf16 v[112:127], v[150:153], v[172:175], v[112:127]
	s_waitcnt lgkmcnt(0)
	v_mfma_f32_32x32x16_bf16 v[96:111], v[222:225], v[172:175], v[96:111]
	s_nop 0
	v_mov_b32_e32 v129, s0
	ds_read_b32 v129, v129
	s_waitcnt lgkmcnt(0)
	v_readfirstlane_b32 s8, v129
	s_cmp_eq_u32 s8, s77
	s_cselect_b64 s[10:11], -1, 0
	s_add_i32 s9, s8, 8
	s_cmp_eq_u32 s9, s77
	s_cselect_b64 s[12:13], -1, 0
	s_or_b64 s[10:11], s[10:11], s[12:13]
	s_andn2_b64 vcc, exec, s[10:11]
	s_cbranch_vccnz .LBB0_987
	v_lshl_or_b32 v129, s8, 6, v214
	v_sub_u32_e32 v129, v211, v129
	v_subrev_u32_e32 v130, 32, v129
	v_cmp_gt_u32_e64 s[8:9], s33, v130
	v_add_u32_e32 v130, -1, v129
	v_cmp_gt_u32_e32 vcc, s33, v129
	v_cndmask_b32_e64 v96, v207, v96, s[8:9]
	v_cmp_gt_u32_e64 s[8:9], s33, v130
	v_subrev_u32_e32 v130, 33, v129
	v_cmp_gt_u32_e64 s[10:11], s33, v130
	v_add_u32_e32 v130, -2, v129
	s_nop 0
	v_cndmask_b32_e64 v97, v207, v97, s[10:11]
	v_cmp_gt_u32_e64 s[10:11], s33, v130
	v_subrev_u32_e32 v130, 34, v129
	v_cmp_gt_u32_e64 s[12:13], s33, v130
	v_add_u32_e32 v130, -3, v129
	s_nop 0
	v_cndmask_b32_e64 v98, v207, v98, s[12:13]
	v_cmp_gt_u32_e64 s[12:13], s33, v130
	v_subrev_u32_e32 v130, 35, v129
	v_cmp_gt_u32_e64 s[14:15], s33, v130
	v_add_u32_e32 v130, -8, v129
	s_nop 0
	v_cndmask_b32_e64 v99, v207, v99, s[14:15]
	v_cmp_gt_u32_e64 s[14:15], s33, v130
	v_subrev_u32_e32 v130, 40, v129
	v_cmp_gt_u32_e64 s[16:17], s33, v130
	v_add_u32_e32 v130, -9, v129
	s_nop 0
	v_cndmask_b32_e64 v100, v207, v100, s[16:17]
	v_cmp_gt_u32_e64 s[16:17], s33, v130
	v_subrev_u32_e32 v130, 41, v129
	v_cmp_gt_u32_e64 s[18:19], s33, v130
	v_add_u32_e32 v130, -10, v129
	s_nop 0
	v_cndmask_b32_e64 v101, v207, v101, s[18:19]
	v_cmp_gt_u32_e64 s[18:19], s33, v130
	v_subrev_u32_e32 v130, 42, v129
	v_cmp_gt_u32_e64 s[20:21], s33, v130
	v_add_u32_e32 v130, -11, v129
	s_nop 0
	v_cndmask_b32_e64 v102, v207, v102, s[20:21]
	v_cmp_gt_u32_e64 s[20:21], s33, v130
	v_subrev_u32_e32 v130, 43, v129
	v_cmp_gt_u32_e64 s[22:23], s33, v130
	v_add_u32_e32 v130, -16, v129
	s_nop 0
	v_cndmask_b32_e64 v103, v207, v103, s[22:23]
	v_cmp_gt_u32_e64 s[22:23], s33, v130
	v_subrev_u32_e32 v130, 48, v129
	v_cmp_gt_u32_e64 s[24:25], s33, v130
	v_subrev_u32_e32 v130, 17, v129
	s_nop 0
	v_cndmask_b32_e64 v104, v207, v104, s[24:25]
	v_cmp_gt_u32_e64 s[24:25], s33, v130
	v_subrev_u32_e32 v130, 49, v129
	v_cmp_gt_u32_e64 s[26:27], s33, v130
	v_subrev_u32_e32 v130, 18, v129
	s_nop 0
	v_cndmask_b32_e64 v105, v207, v105, s[26:27]
	v_cmp_gt_u32_e64 s[26:27], s33, v130
	v_subrev_u32_e32 v130, 50, v129
	v_cmp_gt_u32_e64 s[28:29], s33, v130
	v_subrev_u32_e32 v130, 19, v129
	s_nop 0
	v_cndmask_b32_e64 v106, v207, v106, s[28:29]
	v_cmp_gt_u32_e64 s[28:29], s33, v130
	v_subrev_u32_e32 v130, 51, v129
	v_cmp_gt_u32_e64 s[30:31], s33, v130
	v_subrev_u32_e32 v130, 24, v129
	s_nop 0
	v_cndmask_b32_e64 v107, v207, v107, s[30:31]
	v_cmp_gt_u32_e64 s[30:31], s33, v130
	v_subrev_u32_e32 v130, 56, v129
	v_cmp_gt_u32_e64 s[34:35], s33, v130
	v_subrev_u32_e32 v130, 25, v129
	s_nop 0
	v_cndmask_b32_e64 v108, v207, v108, s[34:35]
	v_cmp_gt_u32_e64 s[34:35], s33, v130
	v_subrev_u32_e32 v130, 57, v129
	v_cmp_gt_u32_e64 s[36:37], s33, v130
	v_subrev_u32_e32 v130, 26, v129
	s_nop 0
	v_cndmask_b32_e64 v109, v207, v109, s[36:37]
	v_cmp_gt_u32_e64 s[36:37], s33, v130
	v_subrev_u32_e32 v130, 58, v129
	v_cmp_gt_u32_e64 s[38:39], s33, v130
	v_subrev_u32_e32 v130, 27, v129
	v_subrev_u32_e32 v129, 59, v129
	v_cndmask_b32_e64 v110, v207, v110, s[38:39]
	v_cmp_gt_u32_e64 s[38:39], s33, v130
	v_cmp_lt_u32_e64 s[40:41], s95, v129
	s_and_saveexec_b64 s[44:45], s[40:41]
	s_mov_b32 s1, 0xf149f2ca
	v_mov_b32_e32 v111, s1
	s_or_b64 exec, exec, s[44:45]
	v_cndmask_b32_e32 v112, v207, v112, vcc
	v_cndmask_b32_e64 v113, v207, v113, s[8:9]
	v_cndmask_b32_e64 v114, v207, v114, s[10:11]
	v_cndmask_b32_e64 v115, v207, v115, s[12:13]
	v_cndmask_b32_e64 v116, v207, v116, s[14:15]
	v_cndmask_b32_e64 v117, v207, v117, s[16:17]
	v_cndmask_b32_e64 v118, v207, v118, s[18:19]
	v_cndmask_b32_e64 v119, v207, v119, s[20:21]
	v_cndmask_b32_e64 v120, v207, v120, s[22:23]
	v_cndmask_b32_e64 v121, v207, v121, s[24:25]
	v_cndmask_b32_e64 v122, v207, v122, s[26:27]
	v_cndmask_b32_e64 v123, v207, v123, s[28:29]
	v_cndmask_b32_e64 v124, v207, v124, s[30:31]
	v_cndmask_b32_e64 v125, v207, v125, s[34:35]
	v_cndmask_b32_e64 v126, v207, v126, s[36:37]
	v_cndmask_b32_e64 v127, v207, v127, s[38:39]

; DI unsigned cvtpk(float lo, float hi) { f32x2_t v = {lo, hi}; bf16x2_t b = __builtin_convertvector(v, bf16x2_t); return __builtin_bit_cast(unsigned, b); }
; #define MFMA32(a, b, c) __builtin_amdgcn_mfma_f32_32x32x16_bf16((a), (b), (c), 0, 0, 0)
; #define SBAR() __builtin_amdgcn_sched_barrier(0)
; template <int VSTR, int NDVB> DI void pv64(f32x16 (&O)[NDVB], const lds8* vp, const bf16x8 (&P)[4]) {
;   bf16x8 f[2][NDVB];
; #pragma unroll
;   for (int d = 0; d < NDVB; ++d) { const s16x4 lo = trrd(vp + d * 64), hi = trrd(vp + 8 * VSTR + d * 64); f[0][d] = __builtin_shufflevector(lo, hi, 0, 1, 2, 3, 4, 5, 6, 7); }
; #pragma unroll
;   for (int kk = 0; kk < 4; ++kk) {
;     if (kk < 3) {
; #pragma unroll
;       for (int d = 0; d < NDVB; ++d) { const s16x4 lo = trrd(vp + (16 * (kk + 1)) * VSTR + d * 64), hi = trrd(vp + (16 * (kk + 1) + 8) * VSTR + d * 64);
;         f[(kk + 1) & 1][d] = __builtin_shufflevector(lo, hi, 0, 1, 2, 3, 4, 5, 6, 7); }
;     }
;     SBAR();
;     __builtin_amdgcn_s_setprio(1);
; #pragma unroll
;     for (int d = 0; d < NDVB; ++d) O[d] = MFMA32(f[kk & 1][d], P[kk], O[d]);
;     __builtin_amdgcn_s_setprio(0);
;     SBAR();
;   }
; }
; template <int NDVB, bool HAS_NEXT> DI void softmax_def(f32x16& sa0, f32x16& sa1, f32x16& sb0, f32x16& sb1, f32x16 (&O)[NDVB], float& muse, float& l, bool first, bf16x8 (&P)[4], bool check = true) {
;     ...
;   float sum = 0.f;
; #pragma unroll
;   for (int i = 0; i < 16; ++i) { sa0[i] = __builtin_amdgcn_exp2f(sa0[i]); sum += sa0[i]; }
; #pragma unroll
;   for (int i = 0; i < 16; ++i) { sa1[i] = __builtin_amdgcn_exp2f(sa1[i]); sum += sa1[i]; }
;   l += sum;
;   u32x4 w;
;   w.x = cvtpk(sa0[0], sa0[1]); w.y = cvtpk(sa0[2], sa0[3]); w.z = cvtpk(sa0[4], sa0[5]); w.w = cvtpk(sa0[6], sa0[7]); P[0] = __builtin_bit_cast(bf16x8, w);
;   w.x = cvtpk(sa0[8], sa0[9]); w.y = cvtpk(sa0[10], sa0[11]); w.z = cvtpk(sa0[12], sa0[13]); w.w = cvtpk(sa0[14], sa0[15]); P[1] = __builtin_bit_cast(bf16x8, w);
;   w.x = cvtpk(sa1[0], sa1[1]); w.y = cvtpk(sa1[2], sa1[3]); w.z = cvtpk(sa1[4], sa1[5]); w.w = cvtpk(sa1[6], sa1[7]); P[2] = __builtin_bit_cast(bf16x8, w);
;   w.x = cvtpk(sa1[8], sa1[9]); w.y = cvtpk(sa1[10], sa1[11]); w.z = cvtpk(sa1[12], sa1[13]); w.w = cvtpk(sa1[14], sa1[15]); P[3] = __builtin_bit_cast(bf16x8, w);
; }
.LBB0_994:
	v_exp_f32_e32 v141, v124
	v_add_u32_e32 v124, s49, v216
	v_exp_f32_e32 v129, v112
	v_exp_f32_e32 v130, v113
	v_exp_f32_e32 v131, v114
	v_exp_f32_e32 v132, v115
	v_exp_f32_e32 v133, v116
	v_exp_f32_e32 v134, v117
	v_exp_f32_e32 v135, v118
	v_exp_f32_e32 v136, v119
	v_exp_f32_e32 v137, v120
	v_exp_f32_e32 v138, v121
	v_exp_f32_e32 v139, v122
	v_exp_f32_e32 v140, v123
	v_exp_f32_e32 v157, v108
	v_exp_f32_e32 v158, v109
	v_exp_f32_e32 v159, v110
	v_exp_f32_e32 v222, v111
	ds_read_b64_tr_b16 v[108:109], v124 offset:9216
	ds_read_b64_tr_b16 v[110:111], v124 offset:10368
	ds_read_b64_tr_b16 v[114:115], v124 offset:10432
	ds_read_b64_tr_b16 v[112:113], v124 offset:9280
	ds_read_b64_tr_b16 v[116:117], v124 offset:11520
	ds_read_b64_tr_b16 v[118:119], v124 offset:12672
	ds_read_b64_tr_b16 v[122:123], v124 offset:12736
	ds_read_b64_tr_b16 v[120:121], v124 offset:11584
	v_exp_f32_e32 v142, v125
	v_exp_f32_e32 v143, v126
	v_exp_f32_e32 v144, v127
	v_exp_f32_e32 v145, v96
	v_exp_f32_e32 v146, v97
	v_exp_f32_e32 v147, v98
	v_exp_f32_e32 v148, v99
	v_exp_f32_e32 v149, v100
	v_exp_f32_e32 v150, v101
	v_exp_f32_e32 v151, v102
	v_exp_f32_e32 v152, v103
	v_exp_f32_e32 v153, v104
	v_exp_f32_e32 v154, v105
	v_exp_f32_e32 v155, v106
	v_exp_f32_e32 v156, v107
	v_cvt_pk_bf16_f32 v96, v129, v130
	v_cvt_pk_bf16_f32 v97, v131, v132
	v_cvt_pk_bf16_f32 v98, v133, v134
	v_cvt_pk_bf16_f32 v99, v135, v136
	v_cvt_pk_bf16_f32 v100, v137, v138
	v_cvt_pk_bf16_f32 v101, v139, v140
	v_cvt_pk_bf16_f32 v102, v141, v142
	v_cvt_pk_bf16_f32 v103, v143, v144
	v_cvt_pk_bf16_f32 v104, v145, v146
	v_cvt_pk_bf16_f32 v105, v147, v148
	v_cvt_pk_bf16_f32 v106, v149, v150
	v_cvt_pk_bf16_f32 v107, v151, v152
	v_cvt_pk_bf16_f32 v224, v153, v154
	v_cvt_pk_bf16_f32 v225, v155, v156
	v_cvt_pk_bf16_f32 v226, v157, v158
	v_cvt_pk_bf16_f32 v227, v159, v222
	s_nop 0
	s_waitcnt lgkmcnt(6)
	v_mfma_f32_32x32x16_bf16 v[32:47], v[108:111], v[96:99], v[32:47]
	s_waitcnt lgkmcnt(4)
	v_mfma_f32_32x32x16_bf16 v[48:63], v[112:115], v[96:99], v[48:63]
	s_nop 0
	ds_read_b64_tr_b16 v[96:97], v124 offset:13824
	ds_read_b64_tr_b16 v[98:99], v124 offset:14976
	ds_read_b64_tr_b16 v[110:111], v124 offset:15040
	ds_read_b64_tr_b16 v[108:109], v124 offset:13888
	s_nop 0
	s_waitcnt lgkmcnt(6)
	v_mfma_f32_32x32x16_bf16 v[32:47], v[116:119], v[100:103], v[32:47]
	s_waitcnt lgkmcnt(4)
	v_mfma_f32_32x32x16_bf16 v[48:63], v[120:123], v[100:103], v[48:63]
	s_nop 0
	ds_read_b64_tr_b16 v[112:113], v124 offset:16128
	ds_read_b64_tr_b16 v[114:115], v124 offset:17280
	ds_read_b64_tr_b16 v[230:231], v124 offset:17344
	ds_read_b64_tr_b16 v[228:229], v124 offset:16192
	s_nop 0
	s_waitcnt lgkmcnt(6)
	v_mfma_f32_32x32x16_bf16 v[32:47], v[96:99], v[104:107], v[32:47]
	s_waitcnt lgkmcnt(4)
	v_mfma_f32_32x32x16_bf16 v[48:63], v[108:111], v[104:107], v[48:63]
	s_nop 0
	s_nop 0
	s_waitcnt lgkmcnt(2)
	v_mfma_f32_32x32x16_bf16 v[32:47], v[112:115], v[224:227], v[32:47]
	s_waitcnt lgkmcnt(0)
	v_mfma_f32_32x32x16_bf16 v[48:63], v[228:231], v[224:227], v[48:63]
	s_nop 0
	s_andn2_b64 vcc, exec, s[42:43]
	s_cbranch_vccnz .LBB0_996
	s_addk_i32 s48, 0xb800
	s_cmp_lg_u32 s6, 0
	s_cselect_b32 s8, s48, 0x9000
	v_add_u32_e32 v96, s8, v215
	s_waitcnt vmcnt(1)
	ds_write_b128 v96, v[176:179]
	s_waitcnt vmcnt(0)
	ds_write_b128 v96, v[180:183] offset:9216

; #define LAS __attribute__((address_space(3)))
; #define MFMA32(a, b, c) __builtin_amdgcn_mfma_f32_32x32x16_bf16((a), (b), (c), 0, 0, 0)
; #define SBAR() __builtin_amdgcn_sched_barrier(0)
; template <int KSTR> DI void qk64b(f32x16& s0, f32x16& s1, const lds8* kp, const bf16x8 (&q)[4], float bias) {
;   bf16x8 a[8];
; #pragma unroll
;   for (int ks = 0; ks < 4; ++ks) { a[2 * ks] = *(const LAS bf16x8*)(kp + ks * 32); a[2 * ks + 1] = *(const LAS bf16x8*)(kp + 32 * KSTR + ks * 32); }
; #pragma unroll
;   for (int i = 0; i < 16; ++i) { s0[i] = bias; s1[i] = bias; }
;   SBAR();
;   __builtin_amdgcn_s_setprio(1);
; #pragma unroll
;   for (int ks = 0; ks < 4; ++ks) { s0 = MFMA32(a[2 * ks], q[ks], s0); s1 = MFMA32(a[2 * ks + 1], q[ks], s1); }
;   __builtin_amdgcn_s_setprio(0);
;   SBAR();
; }
; template <int MODE, int SLOT> DI void ns_valu(volatile LAS int* jl, int t, int ntl, int qpos, int h, int blk, f32x16& s0, f32x16& s1, f32x16& du0, f32x16& du1, f32x16 (&O)[2], float& muse, float& l, bf16x8 (&P)[4], CmpCap& cap) {
;     ...
;       } else {
;         if (j == blk || j + 8 == blk) {
;           const int lim = qpos - 64 * j - 4 * h, lo = lim - 512;
; #pragma unroll
;           for (int i = 0; i < 16; ++i) { const int ci = (i & 3) + 8 * (i >> 2); if (ci > lim || ci <= lo) s0[i] = NEG; if (ci + 32 > lim || ci + 32 <= lo) s1[i] = NEG; }
;         }
.LBB0_999:
	s_add_i32 s8, s6, 1
	s_cmp_lg_u32 s6, 2
	s_cselect_b32 s6, s8, 0
	s_mul_i32 s48, s6, 0x4800
	s_add_i32 s49, s48, 0
	v_add_u32_e32 v124, s49, v213
	ds_read_b128 v[96:99], v124
	ds_read_b128 v[100:103], v124 offset:32
	ds_read_b128 v[104:107], v124 offset:4608
	ds_read_b128 v[108:111], v124 offset:4640
	ds_read_b128 v[112:115], v124 offset:64
	ds_read_b128 v[116:119], v124 offset:96
	ds_read_b128 v[120:123], v124 offset:4672
	ds_read_b128 v[124:127], v124 offset:4704
	v_xor_b32_e32 v128, 0x80000000, v221
	v_mov_b32_e32 v129, v128
	v_mov_b32_e32 v130, v128
	v_mov_b32_e32 v131, v128
	v_mov_b32_e32 v132, v128
	v_mov_b32_e32 v133, v128
	v_mov_b32_e32 v134, v128
	v_mov_b32_e32 v135, v128
	v_mov_b32_e32 v136, v128
	v_mov_b32_e32 v137, v128
	v_mov_b32_e32 v138, v128
	v_mov_b32_e32 v139, v128
	v_mov_b32_e32 v140, v128
	v_mov_b32_e32 v141, v128
	v_mov_b32_e32 v142, v128
	v_mov_b32_e32 v143, v128
	s_nop 0
	s_waitcnt lgkmcnt(7)
	v_mfma_f32_32x32x16_bf16 v[144:159], v[96:99], v[160:163], v[128:143]
	s_waitcnt lgkmcnt(5)
	v_mfma_f32_32x32x16_bf16 v[128:143], v[104:107], v[160:163], v[128:143]
	v_mfma_f32_32x32x16_bf16 v[144:159], v[100:103], v[168:171], v[144:159]
	s_waitcnt lgkmcnt(4)
	v_mfma_f32_32x32x16_bf16 v[128:143], v[108:111], v[168:171], v[128:143]
	s_waitcnt lgkmcnt(3)
	v_mfma_f32_32x32x16_bf16 v[144:159], v[112:115], v[164:167], v[144:159]
	s_waitcnt lgkmcnt(1)
	v_mfma_f32_32x32x16_bf16 v[128:143], v[120:123], v[164:167], v[128:143]
	v_mfma_f32_32x32x16_bf16 v[144:159], v[116:119], v[172:175], v[144:159]
	s_waitcnt lgkmcnt(0)
	v_mfma_f32_32x32x16_bf16 v[128:143], v[124:127], v[172:175], v[128:143]
	s_nop 0
	v_mov_b32_e32 v96, s0
	ds_read_b32 v96, v96 offset:4
	s_waitcnt lgkmcnt(0)
	v_readfirstlane_b32 s8, v96
	s_cmp_eq_u32 s8, s77
	s_cselect_b64 s[10:11], -1, 0
	s_add_i32 s9, s8, 8
	s_cmp_eq_u32 s9, s77
	s_cselect_b64 s[12:13], -1, 0
	s_or_b64 s[10:11], s[10:11], s[12:13]
	s_andn2_b64 vcc, exec, s[10:11]
	s_cbranch_vccnz .LBB0_1003
	v_lshl_or_b32 v96, s8, 6, v214
	v_sub_u32_e32 v96, v211, v96
	v_subrev_u32_e32 v97, 32, v96
	v_cmp_gt_u32_e64 s[8:9], s33, v97
	v_add_u32_e32 v97, -1, v96
	v_cmp_gt_u32_e32 vcc, s33, v96
	v_cndmask_b32_e64 v128, v207, v128, s[8:9]
	v_cmp_gt_u32_e64 s[8:9], s33, v97
	v_subrev_u32_e32 v97, 33, v96
	v_cmp_gt_u32_e64 s[10:11], s33, v97
	v_add_u32_e32 v97, -2, v96
	s_nop 0
	v_cndmask_b32_e64 v129, v207, v129, s[10:11]
	v_cmp_gt_u32_e64 s[10:11], s33, v97
	v_subrev_u32_e32 v97, 34, v96
	v_cmp_gt_u32_e64 s[12:13], s33, v97
	v_add_u32_e32 v97, -3, v96
	s_nop 0
	v_cndmask_b32_e64 v130, v207, v130, s[12:13]
	v_cmp_gt_u32_e64 s[12:13], s33, v97
	v_subrev_u32_e32 v97, 35, v96
	v_cmp_gt_u32_e64 s[14:15], s33, v97
	v_add_u32_e32 v97, -8, v96
	s_nop 0
	v_cndmask_b32_e64 v131, v207, v131, s[14:15]
	v_cmp_gt_u32_e64 s[14:15], s33, v97
	v_subrev_u32_e32 v97, 40, v96
	v_cmp_gt_u32_e64 s[16:17], s33, v97
	v_add_u32_e32 v97, -9, v96
	s_nop 0
	v_cndmask_b32_e64 v132, v207, v132, s[16:17]
	v_cmp_gt_u32_e64 s[16:17], s33, v97
	v_subrev_u32_e32 v97, 41, v96
	v_cmp_gt_u32_e64 s[18:19], s33, v97
	v_add_u32_e32 v97, -10, v96
	s_nop 0
	v_cndmask_b32_e64 v133, v207, v133, s[18:19]
	v_cmp_gt_u32_e64 s[18:19], s33, v97
	v_subrev_u32_e32 v97, 42, v96
	v_cmp_gt_u32_e64 s[20:21], s33, v97
	v_add_u32_e32 v97, -11, v96
	s_nop 0
	v_cndmask_b32_e64 v134, v207, v134, s[20:21]
	v_cmp_gt_u32_e64 s[20:21], s33, v97
	v_subrev_u32_e32 v97, 43, v96
	v_cmp_gt_u32_e64 s[22:23], s33, v97
	v_add_u32_e32 v97, -16, v96
	s_nop 0
	v_cndmask_b32_e64 v135, v207, v135, s[22:23]
	v_cmp_gt_u32_e64 s[22:23], s33, v97
	v_subrev_u32_e32 v97, 48, v96
	v_cmp_gt_u32_e64 s[24:25], s33, v97
	v_subrev_u32_e32 v97, 17, v96
	s_nop 0
	v_cndmask_b32_e64 v136, v207, v136, s[24:25]
	v_cmp_gt_u32_e64 s[24:25], s33, v97
	v_subrev_u32_e32 v97, 49, v96
	v_cmp_gt_u32_e64 s[26:27], s33, v97
	v_subrev_u32_e32 v97, 18, v96
	s_nop 0
	v_cndmask_b32_e64 v137, v207, v137, s[26:27]
	v_cmp_gt_u32_e64 s[26:27], s33, v97
	v_subrev_u32_e32 v97, 50, v96
	v_cmp_gt_u32_e64 s[28:29], s33, v97
	v_subrev_u32_e32 v97, 19, v96
	s_nop 0
	v_cndmask_b32_e64 v138, v207, v138, s[28:29]
	v_cmp_gt_u32_e64 s[28:29], s33, v97
	v_subrev_u32_e32 v97, 51, v96
	v_cmp_gt_u32_e64 s[30:31], s33, v97
	v_subrev_u32_e32 v97, 24, v96
	s_nop 0
	v_cndmask_b32_e64 v139, v207, v139, s[30:31]
	v_cmp_gt_u32_e64 s[30:31], s33, v97
	v_subrev_u32_e32 v97, 56, v96
	v_cmp_gt_u32_e64 s[34:35], s33, v97
	v_subrev_u32_e32 v97, 25, v96
	s_nop 0
	v_cndmask_b32_e64 v140, v207, v140, s[34:35]
	v_cmp_gt_u32_e64 s[34:35], s33, v97
	v_subrev_u32_e32 v97, 57, v96
	v_cmp_gt_u32_e64 s[36:37], s33, v97
	v_subrev_u32_e32 v97, 26, v96
	s_nop 0
	v_cndmask_b32_e64 v141, v207, v141, s[36:37]
	v_cmp_gt_u32_e64 s[36:37], s33, v97
	v_subrev_u32_e32 v97, 58, v96
	v_cmp_gt_u32_e64 s[38:39], s33, v97
	v_subrev_u32_e32 v97, 27, v96
	v_subrev_u32_e32 v96, 59, v96
	v_cndmask_b32_e64 v142, v207, v142, s[38:39]
	v_cmp_gt_u32_e64 s[38:39], s33, v97
	v_cmp_lt_u32_e64 s[40:41], s95, v96
	s_and_saveexec_b64 s[44:45], s[40:41]
	s_mov_b32 s1, 0xf149f2ca
	v_mov_b32_e32 v143, s1
	s_or_b64 exec, exec, s[44:45]
	v_cndmask_b32_e32 v144, v207, v144, vcc
	v_cndmask_b32_e64 v145, v207, v145, s[8:9]
	v_cndmask_b32_e64 v146, v207, v146, s[10:11]
	v_cndmask_b32_e64 v147, v207, v147, s[12:13]
	v_cndmask_b32_e64 v148, v207, v148, s[14:15]
	v_cndmask_b32_e64 v149, v207, v149, s[16:17]
	v_cndmask_b32_e64 v150, v207, v150, s[18:19]
	v_cndmask_b32_e64 v151, v207, v151, s[20:21]
	v_cndmask_b32_e64 v152, v207, v152, s[22:23]
	v_cndmask_b32_e64 v153, v207, v153, s[24:25]
	v_cndmask_b32_e64 v154, v207, v154, s[26:27]
	v_cndmask_b32_e64 v155, v207, v155, s[28:29]
	v_cndmask_b32_e64 v156, v207, v156, s[30:31]
	v_cndmask_b32_e64 v157, v207, v157, s[34:35]
	v_cndmask_b32_e64 v158, v207, v158, s[36:37]
	v_cndmask_b32_e64 v159, v207, v159, s[38:39]

; DI unsigned cvtpk(float lo, float hi) { f32x2_t v = {lo, hi}; bf16x2_t b = __builtin_convertvector(v, bf16x2_t); return __builtin_bit_cast(unsigned, b); }
; #define MFMA32(a, b, c) __builtin_amdgcn_mfma_f32_32x32x16_bf16((a), (b), (c), 0, 0, 0)
; #define SBAR() __builtin_amdgcn_sched_barrier(0)
; template <int VSTR, int NDVB> DI void pv64(f32x16 (&O)[NDVB], const lds8* vp, const bf16x8 (&P)[4]) {
;   bf16x8 f[2][NDVB];
; #pragma unroll
;   for (int d = 0; d < NDVB; ++d) { const s16x4 lo = trrd(vp + d * 64), hi = trrd(vp + 8 * VSTR + d * 64); f[0][d] = __builtin_shufflevector(lo, hi, 0, 1, 2, 3, 4, 5, 6, 7); }
; #pragma unroll
;   for (int kk = 0; kk < 4; ++kk) {
;     if (kk < 3) {
; #pragma unroll
;       for (int d = 0; d < NDVB; ++d) { const s16x4 lo = trrd(vp + (16 * (kk + 1)) * VSTR + d * 64), hi = trrd(vp + (16 * (kk + 1) + 8) * VSTR + d * 64);
;         f[(kk + 1) & 1][d] = __builtin_shufflevector(lo, hi, 0, 1, 2, 3, 4, 5, 6, 7); }
;     }
;     SBAR();
;     __builtin_amdgcn_s_setprio(1);
; #pragma unroll
;     for (int d = 0; d < NDVB; ++d) O[d] = MFMA32(f[kk & 1][d], P[kk], O[d]);
;     __builtin_amdgcn_s_setprio(0);
;     SBAR();
;   }
; }
; template <int NDVB, bool HAS_NEXT> DI void softmax_def(f32x16& sa0, f32x16& sa1, f32x16& sb0, f32x16& sb1, f32x16 (&O)[NDVB], float& muse, float& l, bool first, bf16x8 (&P)[4], bool check = true) {
;     ...
;   float sum = 0.f;
; #pragma unroll
;   for (int i = 0; i < 16; ++i) { sa0[i] = __builtin_amdgcn_exp2f(sa0[i]); sum += sa0[i]; }
; #pragma unroll
;   for (int i = 0; i < 16; ++i) { sa1[i] = __builtin_amdgcn_exp2f(sa1[i]); sum += sa1[i]; }
;   l += sum;
;   u32x4 w;
;   w.x = cvtpk(sa0[0], sa0[1]); w.y = cvtpk(sa0[2], sa0[3]); w.z = cvtpk(sa0[4], sa0[5]); w.w = cvtpk(sa0[6], sa0[7]); P[0] = __builtin_bit_cast(bf16x8, w);
;   w.x = cvtpk(sa0[8], sa0[9]); w.y = cvtpk(sa0[10], sa0[11]); w.z = cvtpk(sa0[12], sa0[13]); w.w = cvtpk(sa0[14], sa0[15]); P[1] = __builtin_bit_cast(bf16x8, w);
;   w.x = cvtpk(sa1[0], sa1[1]); w.y = cvtpk(sa1[2], sa1[3]); w.z = cvtpk(sa1[4], sa1[5]); w.w = cvtpk(sa1[6], sa1[7]); P[2] = __builtin_bit_cast(bf16x8, w);
;   w.x = cvtpk(sa1[8], sa1[9]); w.y = cvtpk(sa1[10], sa1[11]); w.z = cvtpk(sa1[12], sa1[13]); w.w = cvtpk(sa1[14], sa1[15]); P[3] = __builtin_bit_cast(bf16x8, w);
.LBB0_1007:
	v_add_u32_e32 v206, s49, v216
	ds_read_b64_tr_b16 v[236:237], v206 offset:9216
	ds_read_b64_tr_b16 v[238:239], v206 offset:10368
	ds_read_b64_tr_b16 v[242:243], v206 offset:10432
	ds_read_b64_tr_b16 v[240:241], v206 offset:9280
	ds_read_b64_tr_b16 v[244:245], v206 offset:11520
	ds_read_b64_tr_b16 v[246:247], v206 offset:12672
	ds_read_b64_tr_b16 v[250:251], v206 offset:12736
	ds_read_b64_tr_b16 v[248:249], v206 offset:11584
	v_exp_f32_e32 v144, v144
	v_exp_f32_e32 v145, v145
	v_exp_f32_e32 v146, v146
	v_exp_f32_e32 v147, v147
	v_exp_f32_e32 v148, v148
	v_exp_f32_e32 v149, v149
	v_exp_f32_e32 v150, v150
	v_exp_f32_e32 v151, v151
	v_exp_f32_e32 v152, v152
	v_exp_f32_e32 v153, v153
	v_exp_f32_e32 v154, v154
	v_exp_f32_e32 v155, v155
	v_exp_f32_e32 v156, v156
	v_exp_f32_e32 v157, v157
	v_exp_f32_e32 v158, v158
	v_exp_f32_e32 v159, v159
	v_exp_f32_e32 v128, v128
	v_exp_f32_e32 v129, v129
	v_exp_f32_e32 v130, v130
	v_exp_f32_e32 v131, v131
	v_exp_f32_e32 v132, v132
	v_exp_f32_e32 v133, v133
	v_exp_f32_e32 v134, v134
	v_exp_f32_e32 v135, v135
	v_exp_f32_e32 v136, v136
	v_exp_f32_e32 v137, v137
	v_exp_f32_e32 v138, v138
	v_exp_f32_e32 v139, v139
	v_exp_f32_e32 v140, v140
	v_exp_f32_e32 v141, v141
	v_exp_f32_e32 v142, v142
	v_exp_f32_e32 v143, v143
	v_cvt_pk_bf16_f32 v224, v144, v145
	v_cvt_pk_bf16_f32 v225, v146, v147
	v_cvt_pk_bf16_f32 v226, v148, v149
	v_cvt_pk_bf16_f32 v227, v150, v151
	v_cvt_pk_bf16_f32 v228, v152, v153
	v_cvt_pk_bf16_f32 v229, v154, v155
	v_cvt_pk_bf16_f32 v230, v156, v157
	v_cvt_pk_bf16_f32 v231, v158, v159
	v_cvt_pk_bf16_f32 v232, v128, v129
	v_cvt_pk_bf16_f32 v233, v130, v131
	v_cvt_pk_bf16_f32 v234, v132, v133
	v_cvt_pk_bf16_f32 v235, v134, v135
	v_cvt_pk_bf16_f32 v188, v136, v137
	v_cvt_pk_bf16_f32 v189, v138, v139
	v_cvt_pk_bf16_f32 v190, v140, v141
	v_cvt_pk_bf16_f32 v191, v142, v143
	s_nop 0
	s_waitcnt lgkmcnt(6)
	v_mfma_f32_32x32x16_bf16 v[32:47], v[236:239], v[224:227], v[32:47]
	s_waitcnt lgkmcnt(4)
	v_mfma_f32_32x32x16_bf16 v[48:63], v[240:243], v[224:227], v[48:63]
	s_nop 0
	ds_read_b64_tr_b16 v[224:225], v206 offset:13824
	ds_read_b64_tr_b16 v[226:227], v206 offset:14976
	ds_read_b64_tr_b16 v[238:239], v206 offset:15040
	ds_read_b64_tr_b16 v[236:237], v206 offset:13888
	s_nop 0
	s_waitcnt lgkmcnt(6)
	v_mfma_f32_32x32x16_bf16 v[32:47], v[244:247], v[228:231], v[32:47]
	s_waitcnt lgkmcnt(4)
	v_mfma_f32_32x32x16_bf16 v[48:63], v[248:251], v[228:231], v[48:63]
	s_nop 0
	ds_read_b64_tr_b16 v[228:229], v206 offset:16128
	ds_read_b64_tr_b16 v[230:231], v206 offset:17280
	ds_read_b64_tr_b16 v[242:243], v206 offset:17344
	ds_read_b64_tr_b16 v[240:241], v206 offset:16192
	s_nop 0
	s_waitcnt lgkmcnt(6)
	v_mfma_f32_32x32x16_bf16 v[32:47], v[224:227], v[232:235], v[32:47]
	s_waitcnt lgkmcnt(4)
	v_mfma_f32_32x32x16_bf16 v[48:63], v[236:239], v[232:235], v[48:63]
	s_nop 0
	s_nop 0
	s_waitcnt lgkmcnt(2)
	v_mfma_f32_32x32x16_bf16 v[32:47], v[228:231], v[188:191], v[32:47]
	s_waitcnt lgkmcnt(0)
	v_mfma_f32_32x32x16_bf16 v[48:63], v[240:243], v[188:191], v[48:63]
	s_nop 0
	s_andn2_b64 vcc, exec, s[42:43]
	s_cbranch_vccnz .LBB0_979
	s_addk_i32 s48, 0xb800
	s_cmp_lg_u32 s6, 0
	s_cselect_b32 s8, s48, 0x9000
	v_add_u32_e32 v188, s8, v215
	s_waitcnt vmcnt(1)
	ds_write_b128 v188, v[176:179]
	s_waitcnt vmcnt(0)
	ds_write_b128 v188, v[180:183] offset:9216
	s_branch .LBB0_979
